# GEMM K-loops: hand-over barrier of each 32-MFMA block signalled one MFMA before the end of the block (trailing MFMA is register-only)
# baseline (speedup 1.0000x reference)
; #define PG8_STAGE(bufoff, gbase, voff) do { _Pragma("unroll") for (int _i = 0; _i < 2; ++_i) \
;         __builtin_amdgcn_global_load_lds((const unsigned*)((const char*)(gbase) + (voff)[_i]), (PG8_LAS unsigned*)(lds + (bufoff) + ldsw + _i * 8192), 16, 0, 0); } while (0)
; #define PG8_LDA(dst, b, h) do { _Pragma("unroll") for (int m = 0; m < 4; ++m) _Pragma("unroll") for (int k = 0; k < 2; ++k) dst[m][k] = *(const PG8_LAS bf16x8*)(lds + PG8_SA(b, h) + aoff + m * 2048 + k * 1024); } while (0)
; #define PG8_LDB(dst, b, h) do { _Pragma("unroll") for (int n = 0; n < 2; ++n) _Pragma("unroll") for (int k = 0; k < 2; ++k) dst[n][k] = *(const PG8_LAS bf16x8*)(lds + PG8_SB(b, h) + boff + n * 2048 + k * 1024); } while (0)
; #define PG8_MMA(ai, bj, At, Bt) do { __builtin_amdgcn_s_setprio(1); _Pragma("unroll") for (int m = 0; m < 4; ++m) _Pragma("unroll") for (int n = 0; n < 2; ++n) _Pragma("unroll") for (int k = 0; k < 2; ++k) \
;         acc[ai][bj][m][n] = __builtin_amdgcn_mfma_f32_16x16x32_bf16(Bt[n][k], At[m][k], acc[ai][bj][m][n], 0, 0, 0); __builtin_amdgcn_s_setprio(0); } while (0)
; #define PG8_WAIT_V(n) asm volatile("s_waitcnt vmcnt(" #n ")" ::: "memory")
; template <class Epi, class Sched, bool ALIGN_EPI = false, bool SP2 = false>
; __device__ __forceinline__ void gemm_phase(PG8_LAS unsigned char* lds, const Gemm g, const Sched S, const Epi E) {
;     ...
;             PG8_LDB(B0, 0, 0); PG8_LDB(B1, 0, 1); PG8_SCHED; PG8_LDA(At, 0, 0); PG8_STAGE(PG8_SA(1, 1), a1 + hstep, voffA);
;             PG8_WAIT_V(8); PG8_WAIT_L(0); PG8_BAR; PG8_MMA(0, 0, At, B0); PG8_MMA(0, 1, At, B1); PG8_BAR; PG8_SCHED;
;             PG8_LDA(At, 0, 1); PG8_STAGE(PG8_SB(0, 0), b2, voffB); PG8_STAGE(PG8_SB(0, 1), b2 + hstep, voffB); PG8_STAGE(PG8_SA(0, 0), a2, voffA);
;             PG8_WAIT_V(8); PG8_WAIT_L(0); PG8_BAR; PG8_MMA(1, 0, At, B0); PG8_MMA(1, 1, At, B1); PG8_BAR; PG8_SCHED;
;             PG8_LDB(B0, 1, 0); PG8_LDB(B1, 1, 1); PG8_SCHED; PG8_LDA(At, 1, 0); PG8_STAGE(PG8_SA(0, 1), a2 + hstep, voffA);
;             PG8_WAIT_V(8); PG8_WAIT_L(0); PG8_BAR; PG8_MMA(0, 0, At, B0); PG8_MMA(0, 1, At, B1); PG8_BAR; PG8_SCHED;
;             PG8_LDA(At, 1, 1); PG8_STAGE(PG8_SB(1, 0), b3, voffB); PG8_STAGE(PG8_SB(1, 1), b3 + hstep, voffB); PG8_STAGE(PG8_SA(1, 0), a3, voffA);
;             PG8_WAIT_V(8); PG8_WAIT_L(0); PG8_BAR; PG8_MMA(1, 0, At, B0); PG8_MMA(1, 1, At, B1); PG8_BAR; PG8_SCHED;
.LBB0_276:
	ds_read_b128 v[152:155], v149
	ds_read_b128 v[156:159], v149 offset:1024
	ds_read_b128 v[160:163], v149 offset:2048
	ds_read_b128 v[164:167], v149 offset:3072
	ds_read_b128 v[168:171], v150
	ds_read_b128 v[172:175], v150 offset:1024
	ds_read_b128 v[176:179], v150 offset:2048
	ds_read_b128 v[180:183], v150 offset:3072
	s_add_u32 s44, s42, 0xfffc0080
	s_addc_u32 s45, s43, -1
	s_cmp_eq_u32 s69, 12
	s_cselect_b32 s51, s19, s45
	s_cselect_b32 s50, s63, s44
	s_cselect_b32 s45, s17, s68
	s_cselect_b32 s44, s64, s65
	v_lshl_add_u64 v[144:145], s[42:43], 0, v[136:137]
	s_add_i32 m0, s33, 0xc000
	ds_read_b128 v[190:193], v151
	ds_read_b128 v[194:197], v151 offset:1024
	ds_read_b128 v[198:201], v151 offset:2048
	ds_read_b128 v[202:205], v151 offset:3072
	ds_read_b128 v[206:209], v151 offset:4096
	ds_read_b128 v[210:213], v151 offset:5120
	ds_read_b128 v[214:217], v151 offset:6144
	ds_read_b128 v[218:221], v151 offset:7168
	global_load_lds_dwordx4 v[144:145], off
	v_lshl_add_u64 v[144:145], s[42:43], 0, v[138:139]
	s_add_i32 m0, s33, 0xe000
	s_nop 0
	global_load_lds_dwordx4 v[144:145], off
	s_waitcnt vmcnt(8)
	s_waitcnt lgkmcnt(0)
	s_barrier
	s_setprio 1
	s_waitcnt lgkmcnt(0)
	v_mfma_f32_16x16x32_bf16 v[124:127], v[152:155], v[190:193], v[124:127]
	v_mfma_f32_16x16x32_bf16 v[116:119], v[160:163], v[190:193], v[116:119]
	v_mfma_f32_16x16x32_bf16 v[108:111], v[152:155], v[198:201], v[108:111]
	v_mfma_f32_16x16x32_bf16 v[100:103], v[160:163], v[198:201], v[100:103]
	v_mfma_f32_16x16x32_bf16 v[92:95], v[152:155], v[206:209], v[92:95]
	v_mfma_f32_16x16x32_bf16 v[84:87], v[160:163], v[206:209], v[84:87]
	v_mfma_f32_16x16x32_bf16 v[76:79], v[152:155], v[214:217], v[76:79]
	v_mfma_f32_16x16x32_bf16 v[68:71], v[160:163], v[214:217], v[68:71]
	v_mfma_f32_16x16x32_bf16 v[124:127], v[156:159], v[194:197], v[124:127]
	v_mfma_f32_16x16x32_bf16 v[116:119], v[164:167], v[194:197], v[116:119]
	v_mfma_f32_16x16x32_bf16 v[108:111], v[156:159], v[202:205], v[108:111]
	v_mfma_f32_16x16x32_bf16 v[100:103], v[164:167], v[202:205], v[100:103]
	v_mfma_f32_16x16x32_bf16 v[92:95], v[156:159], v[210:213], v[92:95]
	v_mfma_f32_16x16x32_bf16 v[84:87], v[164:167], v[210:213], v[84:87]
	v_mfma_f32_16x16x32_bf16 v[76:79], v[156:159], v[218:221], v[76:79]
	v_mfma_f32_16x16x32_bf16 v[68:71], v[164:167], v[218:221], v[68:71]
	s_setprio 0
	s_setprio 1
	v_mfma_f32_16x16x32_bf16 v[120:123], v[168:171], v[190:193], v[120:123]
	v_mfma_f32_16x16x32_bf16 v[112:115], v[176:179], v[190:193], v[112:115]
	v_mfma_f32_16x16x32_bf16 v[104:107], v[168:171], v[198:201], v[104:107]
	v_mfma_f32_16x16x32_bf16 v[96:99], v[176:179], v[198:201], v[96:99]
	v_mfma_f32_16x16x32_bf16 v[88:91], v[168:171], v[206:209], v[88:91]
	v_mfma_f32_16x16x32_bf16 v[80:83], v[176:179], v[206:209], v[80:83]
	v_mfma_f32_16x16x32_bf16 v[72:75], v[168:171], v[214:217], v[72:75]
	v_mfma_f32_16x16x32_bf16 v[64:67], v[176:179], v[214:217], v[64:67]
	v_mfma_f32_16x16x32_bf16 v[120:123], v[172:175], v[194:197], v[120:123]
	v_mfma_f32_16x16x32_bf16 v[112:115], v[180:183], v[194:197], v[112:115]
	v_mfma_f32_16x16x32_bf16 v[104:107], v[172:175], v[202:205], v[104:107]
	v_mfma_f32_16x16x32_bf16 v[96:99], v[180:183], v[202:205], v[96:99]
	v_mfma_f32_16x16x32_bf16 v[88:91], v[172:175], v[210:213], v[88:91]
	v_mfma_f32_16x16x32_bf16 v[80:83], v[180:183], v[210:213], v[80:83]
	v_mfma_f32_16x16x32_bf16 v[72:75], v[172:175], v[218:221], v[72:75]
	s_barrier
	v_mfma_f32_16x16x32_bf16 v[64:67], v[180:183], v[218:221], v[64:67]
	s_setprio 0
	s_add_i32 s82, s59, s8
	v_lshl_add_u64 v[144:145], s[44:45], 0, v[132:133]
	s_mov_b32 m0, s82
	ds_read_b128 v[190:193], v151 offset:16384
	ds_read_b128 v[194:197], v151 offset:17408
	ds_read_b128 v[198:201], v151 offset:18432
	ds_read_b128 v[202:205], v151 offset:19456
	ds_read_b128 v[206:209], v151 offset:20480
	ds_read_b128 v[210:213], v151 offset:21504
	ds_read_b128 v[214:217], v151 offset:22528
	ds_read_b128 v[218:221], v151 offset:23552
	global_load_lds_dwordx4 v[144:145], off
	s_add_i32 m0, s82, 0x2000
	s_add_u32 s82, s44, 0x40000
	v_lshl_add_u64 v[184:185], s[44:45], 0, v[128:129]
	s_addc_u32 s83, s45, 0
	s_add_i32 s84, s60, s8
	global_load_lds_dwordx4 v[184:185], off
	v_lshl_add_u64 v[222:223], s[82:83], 0, v[132:133]
	s_mov_b32 m0, s84
	v_lshl_add_u64 v[224:225], s[50:51], 0, v[130:131]
	global_load_lds_dwordx4 v[222:223], off
	v_lshl_add_u64 v[222:223], s[82:83], 0, v[128:129]
	s_add_i32 m0, s84, 0x2000
	s_nop 0
	global_load_lds_dwordx4 v[222:223], off
	v_lshl_add_u64 v[222:223], s[50:51], 0, v[134:135]
	s_mov_b32 m0, s33
	s_nop 0
	global_load_lds_dwordx4 v[222:223], off
	s_mov_b32 m0, s36
	s_nop 0
	global_load_lds_dwordx4 v[224:225], off
	s_waitcnt vmcnt(8)
	s_waitcnt lgkmcnt(0)
	s_barrier
; #define PG8_STAGE(bufoff, gbase, voff) do { _Pragma("unroll") for (int _i = 0; _i < 2; ++_i) \
;         __builtin_amdgcn_global_load_lds((const unsigned*)((const char*)(gbase) + (voff)[_i]), (PG8_LAS unsigned*)(lds + (bufoff) + ldsw + _i * 8192), 16, 0, 0); } while (0)
; #define PG8_LDA(dst, b, h) do { _Pragma("unroll") for (int m = 0; m < 4; ++m) _Pragma("unroll") for (int k = 0; k < 2; ++k) dst[m][k] = *(const PG8_LAS bf16x8*)(lds + PG8_SA(b, h) + aoff + m * 2048 + k * 1024); } while (0)
; #define PG8_LDB(dst, b, h) do { _Pragma("unroll") for (int n = 0; n < 2; ++n) _Pragma("unroll") for (int k = 0; k < 2; ++k) dst[n][k] = *(const PG8_LAS bf16x8*)(lds + PG8_SB(b, h) + boff + n * 2048 + k * 1024); } while (0)
; #define PG8_MMA(ai, bj, At, Bt) do { __builtin_amdgcn_s_setprio(1); _Pragma("unroll") for (int m = 0; m < 4; ++m) _Pragma("unroll") for (int n = 0; n < 2; ++n) _Pragma("unroll") for (int k = 0; k < 2; ++k) \
;         acc[ai][bj][m][n] = __builtin_amdgcn_mfma_f32_16x16x32_bf16(Bt[n][k], At[m][k], acc[ai][bj][m][n], 0, 0, 0); __builtin_amdgcn_s_setprio(0); } while (0)
; #define PG8_WAIT_V(n) asm volatile("s_waitcnt vmcnt(" #n ")" ::: "memory")
; template <class Epi, class Sched, bool ALIGN_EPI = false, bool SP2 = false>
; __device__ __forceinline__ void gemm_phase(PG8_LAS unsigned char* lds, const Gemm g, const Sched S, const Epi E) {
;     ...
;             PG8_LDB(B0, 0, 0); PG8_LDB(B1, 0, 1); PG8_SCHED; PG8_LDA(At, 0, 0); PG8_STAGE(PG8_SA(1, 1), a1 + hstep, voffA);
;             PG8_WAIT_V(8); PG8_WAIT_L(0); PG8_BAR; PG8_MMA(0, 0, At, B0); PG8_MMA(0, 1, At, B1); PG8_BAR; PG8_SCHED;
;             PG8_LDA(At, 0, 1); PG8_STAGE(PG8_SB(0, 0), b2, voffB); PG8_STAGE(PG8_SB(0, 1), b2 + hstep, voffB); PG8_STAGE(PG8_SA(0, 0), a2, voffA);
;             PG8_WAIT_V(8); PG8_WAIT_L(0); PG8_BAR; PG8_MMA(1, 0, At, B0); PG8_MMA(1, 1, At, B1); PG8_BAR; PG8_SCHED;
;             PG8_LDB(B0, 1, 0); PG8_LDB(B1, 1, 1); PG8_SCHED; PG8_LDA(At, 1, 0); PG8_STAGE(PG8_SA(0, 1), a2 + hstep, voffA);
;             PG8_WAIT_V(8); PG8_WAIT_L(0); PG8_BAR; PG8_MMA(0, 0, At, B0); PG8_MMA(0, 1, At, B1); PG8_BAR; PG8_SCHED;
;             PG8_LDA(At, 1, 1); PG8_STAGE(PG8_SB(1, 0), b3, voffB); PG8_STAGE(PG8_SB(1, 1), b3 + hstep, voffB); PG8_STAGE(PG8_SA(1, 0), a3, voffA);
;             PG8_WAIT_V(8); PG8_WAIT_L(0); PG8_BAR; PG8_MMA(1, 0, At, B0); PG8_MMA(1, 1, At, B1); PG8_BAR; PG8_SCHED;
	s_setprio 1
	s_waitcnt lgkmcnt(0)
	v_mfma_f32_16x16x32_bf16 v[60:63], v[152:155], v[190:193], v[60:63]
	v_mfma_f32_16x16x32_bf16 v[52:55], v[160:163], v[190:193], v[52:55]
	v_mfma_f32_16x16x32_bf16 v[44:47], v[152:155], v[198:201], v[44:47]
	v_mfma_f32_16x16x32_bf16 v[36:39], v[160:163], v[198:201], v[36:39]
	v_mfma_f32_16x16x32_bf16 v[28:31], v[152:155], v[206:209], v[28:31]
	v_mfma_f32_16x16x32_bf16 v[20:23], v[160:163], v[206:209], v[20:23]
	v_mfma_f32_16x16x32_bf16 v[12:15], v[152:155], v[214:217], v[12:15]
	v_mfma_f32_16x16x32_bf16 v[4:7], v[160:163], v[214:217], v[4:7]
	v_mfma_f32_16x16x32_bf16 v[60:63], v[156:159], v[194:197], v[60:63]
	v_mfma_f32_16x16x32_bf16 v[52:55], v[164:167], v[194:197], v[52:55]
	v_mfma_f32_16x16x32_bf16 v[44:47], v[156:159], v[202:205], v[44:47]
	v_mfma_f32_16x16x32_bf16 v[36:39], v[164:167], v[202:205], v[36:39]
	v_mfma_f32_16x16x32_bf16 v[28:31], v[156:159], v[210:213], v[28:31]
	v_mfma_f32_16x16x32_bf16 v[20:23], v[164:167], v[210:213], v[20:23]
	v_mfma_f32_16x16x32_bf16 v[12:15], v[156:159], v[218:221], v[12:15]
	v_mfma_f32_16x16x32_bf16 v[4:7], v[164:167], v[218:221], v[4:7]
	s_setprio 0
	s_setprio 1
	v_mfma_f32_16x16x32_bf16 v[56:59], v[168:171], v[190:193], v[56:59]
	v_mfma_f32_16x16x32_bf16 v[48:51], v[176:179], v[190:193], v[48:51]
	v_mfma_f32_16x16x32_bf16 v[40:43], v[168:171], v[198:201], v[40:43]
	v_mfma_f32_16x16x32_bf16 v[32:35], v[176:179], v[198:201], v[32:35]
	v_mfma_f32_16x16x32_bf16 v[24:27], v[168:171], v[206:209], v[24:27]
	v_mfma_f32_16x16x32_bf16 v[16:19], v[176:179], v[206:209], v[16:19]
	v_mfma_f32_16x16x32_bf16 v[8:11], v[168:171], v[214:217], v[8:11]
	v_mfma_f32_16x16x32_bf16 v[0:3], v[176:179], v[214:217], v[0:3]
	v_mfma_f32_16x16x32_bf16 v[56:59], v[172:175], v[194:197], v[56:59]
	v_mfma_f32_16x16x32_bf16 v[48:51], v[180:183], v[194:197], v[48:51]
	v_mfma_f32_16x16x32_bf16 v[40:43], v[172:175], v[202:205], v[40:43]
	v_mfma_f32_16x16x32_bf16 v[32:35], v[180:183], v[202:205], v[32:35]
	v_mfma_f32_16x16x32_bf16 v[24:27], v[172:175], v[210:213], v[24:27]
	v_mfma_f32_16x16x32_bf16 v[16:19], v[180:183], v[210:213], v[16:19]
	v_mfma_f32_16x16x32_bf16 v[8:11], v[172:175], v[218:221], v[8:11]
	s_barrier
	v_mfma_f32_16x16x32_bf16 v[0:3], v[180:183], v[218:221], v[0:3]
	s_setprio 0
	s_add_i32 s82, 0, 0x18000
	s_add_i32 s83, 0, 0x1c000
	v_add_u32_e32 v164, s82, v148
	v_add_u32_e32 v180, s83, v148
	ds_read_b128 v[152:155], v164
	ds_read_b128 v[156:159], v164 offset:1024
	ds_read_b128 v[160:163], v164 offset:2048
	ds_read_b128 v[164:167], v164 offset:3072
	ds_read_b128 v[168:171], v180
	ds_read_b128 v[172:175], v180 offset:1024
	ds_read_b128 v[176:179], v180 offset:2048
	ds_read_b128 v[180:183], v180 offset:3072
	s_add_u32 s50, s50, 0x40000
	s_addc_u32 s51, s51, 0
	s_mov_b32 m0, s37
	v_lshl_add_u64 v[226:227], s[50:51], 0, v[134:135]
	ds_read_b128 v[190:193], v151 offset:32768
	ds_read_b128 v[194:197], v151 offset:33792
	ds_read_b128 v[198:201], v151 offset:34816
	ds_read_b128 v[202:205], v151 offset:35840
	ds_read_b128 v[206:209], v151 offset:36864
	ds_read_b128 v[210:213], v151 offset:37888
	ds_read_b128 v[214:217], v151 offset:38912
	ds_read_b128 v[218:221], v151 offset:39936
	global_load_lds_dwordx4 v[226:227], off
	v_lshl_add_u64 v[226:227], s[50:51], 0, v[130:131]
	s_mov_b32 m0, s41
	s_nop 0
	global_load_lds_dwordx4 v[226:227], off
	s_waitcnt vmcnt(8)
	s_waitcnt lgkmcnt(0)
	s_barrier
	s_setprio 1
	s_waitcnt lgkmcnt(0)
	v_mfma_f32_16x16x32_bf16 v[124:127], v[152:155], v[190:193], v[124:127]
	v_mfma_f32_16x16x32_bf16 v[116:119], v[160:163], v[190:193], v[116:119]
	v_mfma_f32_16x16x32_bf16 v[108:111], v[152:155], v[198:201], v[108:111]
	v_mfma_f32_16x16x32_bf16 v[100:103], v[160:163], v[198:201], v[100:103]
	v_mfma_f32_16x16x32_bf16 v[92:95], v[152:155], v[206:209], v[92:95]
	v_mfma_f32_16x16x32_bf16 v[84:87], v[160:163], v[206:209], v[84:87]
	v_mfma_f32_16x16x32_bf16 v[76:79], v[152:155], v[214:217], v[76:79]
	v_mfma_f32_16x16x32_bf16 v[68:71], v[160:163], v[214:217], v[68:71]
	v_mfma_f32_16x16x32_bf16 v[124:127], v[156:159], v[194:197], v[124:127]
	v_mfma_f32_16x16x32_bf16 v[116:119], v[164:167], v[194:197], v[116:119]
	v_mfma_f32_16x16x32_bf16 v[108:111], v[156:159], v[202:205], v[108:111]
	v_mfma_f32_16x16x32_bf16 v[100:103], v[164:167], v[202:205], v[100:103]
	v_mfma_f32_16x16x32_bf16 v[92:95], v[156:159], v[210:213], v[92:95]
	v_mfma_f32_16x16x32_bf16 v[84:87], v[164:167], v[210:213], v[84:87]
	v_mfma_f32_16x16x32_bf16 v[76:79], v[156:159], v[218:221], v[76:79]
	v_mfma_f32_16x16x32_bf16 v[68:71], v[164:167], v[218:221], v[68:71]
	s_setprio 0
	s_setprio 1
	v_mfma_f32_16x16x32_bf16 v[120:123], v[168:171], v[190:193], v[120:123]
	v_mfma_f32_16x16x32_bf16 v[112:115], v[176:179], v[190:193], v[112:115]
	v_mfma_f32_16x16x32_bf16 v[104:107], v[168:171], v[198:201], v[104:107]
	v_mfma_f32_16x16x32_bf16 v[96:99], v[176:179], v[198:201], v[96:99]
	v_mfma_f32_16x16x32_bf16 v[88:91], v[168:171], v[206:209], v[88:91]
	v_mfma_f32_16x16x32_bf16 v[80:83], v[176:179], v[206:209], v[80:83]
	v_mfma_f32_16x16x32_bf16 v[72:75], v[168:171], v[214:217], v[72:75]
	v_mfma_f32_16x16x32_bf16 v[64:67], v[176:179], v[214:217], v[64:67]
	v_mfma_f32_16x16x32_bf16 v[120:123], v[172:175], v[194:197], v[120:123]
	v_mfma_f32_16x16x32_bf16 v[112:115], v[180:183], v[194:197], v[112:115]
	v_mfma_f32_16x16x32_bf16 v[104:107], v[172:175], v[202:205], v[104:107]
	v_mfma_f32_16x16x32_bf16 v[96:99], v[180:183], v[202:205], v[96:99]
	v_mfma_f32_16x16x32_bf16 v[88:91], v[172:175], v[210:213], v[88:91]
	v_mfma_f32_16x16x32_bf16 v[80:83], v[180:183], v[210:213], v[80:83]
	v_mfma_f32_16x16x32_bf16 v[72:75], v[172:175], v[218:221], v[72:75]
	s_barrier
; #define PG8_STAGE(bufoff, gbase, voff) do { _Pragma("unroll") for (int _i = 0; _i < 2; ++_i) \
;         __builtin_amdgcn_global_load_lds((const unsigned*)((const char*)(gbase) + (voff)[_i]), (PG8_LAS unsigned*)(lds + (bufoff) + ldsw + _i * 8192), 16, 0, 0); } while (0)
; #define PG8_LDA(dst, b, h) do { _Pragma("unroll") for (int m = 0; m < 4; ++m) _Pragma("unroll") for (int k = 0; k < 2; ++k) dst[m][k] = *(const PG8_LAS bf16x8*)(lds + PG8_SA(b, h) + aoff + m * 2048 + k * 1024); } while (0)
; #define PG8_LDB(dst, b, h) do { _Pragma("unroll") for (int n = 0; n < 2; ++n) _Pragma("unroll") for (int k = 0; k < 2; ++k) dst[n][k] = *(const PG8_LAS bf16x8*)(lds + PG8_SB(b, h) + boff + n * 2048 + k * 1024); } while (0)
; #define PG8_MMA(ai, bj, At, Bt) do { __builtin_amdgcn_s_setprio(1); _Pragma("unroll") for (int m = 0; m < 4; ++m) _Pragma("unroll") for (int n = 0; n < 2; ++n) _Pragma("unroll") for (int k = 0; k < 2; ++k) \
;         acc[ai][bj][m][n] = __builtin_amdgcn_mfma_f32_16x16x32_bf16(Bt[n][k], At[m][k], acc[ai][bj][m][n], 0, 0, 0); __builtin_amdgcn_s_setprio(0); } while (0)
; #define PG8_WAIT_V(n) asm volatile("s_waitcnt vmcnt(" #n ")" ::: "memory")
; template <class Epi, class Sched, bool ALIGN_EPI = false, bool SP2 = false>
; __device__ __forceinline__ void gemm_phase(PG8_LAS unsigned char* lds, const Gemm g, const Sched S, const Epi E) {
;     ...
;             PG8_LDB(B0, 0, 0); PG8_LDB(B1, 0, 1); PG8_SCHED; PG8_LDA(At, 0, 0); PG8_STAGE(PG8_SA(1, 1), a1 + hstep, voffA);
;             PG8_WAIT_V(8); PG8_WAIT_L(0); PG8_BAR; PG8_MMA(0, 0, At, B0); PG8_MMA(0, 1, At, B1); PG8_BAR; PG8_SCHED;
;             PG8_LDA(At, 0, 1); PG8_STAGE(PG8_SB(0, 0), b2, voffB); PG8_STAGE(PG8_SB(0, 1), b2 + hstep, voffB); PG8_STAGE(PG8_SA(0, 0), a2, voffA);
;             PG8_WAIT_V(8); PG8_WAIT_L(0); PG8_BAR; PG8_MMA(1, 0, At, B0); PG8_MMA(1, 1, At, B1); PG8_BAR; PG8_SCHED;
;             PG8_LDB(B0, 1, 0); PG8_LDB(B1, 1, 1); PG8_SCHED; PG8_LDA(At, 1, 0); PG8_STAGE(PG8_SA(0, 1), a2 + hstep, voffA);
;             PG8_WAIT_V(8); PG8_WAIT_L(0); PG8_BAR; PG8_MMA(0, 0, At, B0); PG8_MMA(0, 1, At, B1); PG8_BAR; PG8_SCHED;
;             PG8_LDA(At, 1, 1); PG8_STAGE(PG8_SB(1, 0), b3, voffB); PG8_STAGE(PG8_SB(1, 1), b3 + hstep, voffB); PG8_STAGE(PG8_SA(1, 0), a3, voffA);
;             PG8_WAIT_V(8); PG8_WAIT_L(0); PG8_BAR; PG8_MMA(1, 0, At, B0); PG8_MMA(1, 1, At, B1); PG8_BAR; PG8_SCHED;
	v_mfma_f32_16x16x32_bf16 v[64:67], v[180:183], v[218:221], v[64:67]
	s_setprio 0
	s_add_i32 s50, s82, s8
	v_lshl_add_u64 v[144:145], v[144:145], 0, s[12:13]
	s_mov_b32 m0, s50
	ds_read_b128 v[190:193], v151 offset:49152
	ds_read_b128 v[194:197], v151 offset:50176
	ds_read_b128 v[198:201], v151 offset:51200
	ds_read_b128 v[202:205], v151 offset:52224
	ds_read_b128 v[206:209], v151 offset:53248
	ds_read_b128 v[210:213], v151 offset:54272
	ds_read_b128 v[214:217], v151 offset:55296
	ds_read_b128 v[218:221], v151 offset:56320
	global_load_lds_dwordx4 v[144:145], off
	s_add_i32 m0, s50, 0x2000
	s_add_u32 s44, s44, 0x40080
	v_lshl_add_u64 v[144:145], v[184:185], 0, s[12:13]
	s_addc_u32 s45, s45, 0
	s_add_i32 s50, s83, s8
	global_load_lds_dwordx4 v[144:145], off
	v_lshl_add_u64 v[144:145], s[44:45], 0, v[132:133]
	s_mov_b32 m0, s50
	s_nop 0
	global_load_lds_dwordx4 v[144:145], off
	v_lshl_add_u64 v[144:145], s[44:45], 0, v[128:129]
	s_add_i32 m0, s50, 0x2000
	s_nop 0
	global_load_lds_dwordx4 v[144:145], off
	v_lshl_add_u64 v[144:145], v[222:223], 0, s[12:13]
	s_mov_b32 m0, s49
	s_nop 0
	global_load_lds_dwordx4 v[144:145], off
	v_lshl_add_u64 v[144:145], v[224:225], 0, s[12:13]
	s_mov_b32 m0, s54
	s_nop 0
	global_load_lds_dwordx4 v[144:145], off
	s_waitcnt vmcnt(8)
	s_waitcnt lgkmcnt(0)
	s_barrier
	s_setprio 1
	s_waitcnt lgkmcnt(0)
	v_mfma_f32_16x16x32_bf16 v[60:63], v[152:155], v[190:193], v[60:63]
	v_mfma_f32_16x16x32_bf16 v[52:55], v[160:163], v[190:193], v[52:55]
	v_mfma_f32_16x16x32_bf16 v[44:47], v[152:155], v[198:201], v[44:47]
	v_mfma_f32_16x16x32_bf16 v[36:39], v[160:163], v[198:201], v[36:39]
	v_mfma_f32_16x16x32_bf16 v[28:31], v[152:155], v[206:209], v[28:31]
	v_mfma_f32_16x16x32_bf16 v[20:23], v[160:163], v[206:209], v[20:23]
	v_mfma_f32_16x16x32_bf16 v[12:15], v[152:155], v[214:217], v[12:15]
	v_mfma_f32_16x16x32_bf16 v[4:7], v[160:163], v[214:217], v[4:7]
	v_mfma_f32_16x16x32_bf16 v[60:63], v[156:159], v[194:197], v[60:63]
	v_mfma_f32_16x16x32_bf16 v[52:55], v[164:167], v[194:197], v[52:55]
	v_mfma_f32_16x16x32_bf16 v[44:47], v[156:159], v[202:205], v[44:47]
	v_mfma_f32_16x16x32_bf16 v[36:39], v[164:167], v[202:205], v[36:39]
	v_mfma_f32_16x16x32_bf16 v[28:31], v[156:159], v[210:213], v[28:31]
	v_mfma_f32_16x16x32_bf16 v[20:23], v[164:167], v[210:213], v[20:23]
	v_mfma_f32_16x16x32_bf16 v[12:15], v[156:159], v[218:221], v[12:15]
	v_mfma_f32_16x16x32_bf16 v[4:7], v[164:167], v[218:221], v[4:7]
	s_setprio 0
	s_setprio 1
	v_mfma_f32_16x16x32_bf16 v[56:59], v[168:171], v[190:193], v[56:59]
	v_mfma_f32_16x16x32_bf16 v[48:51], v[176:179], v[190:193], v[48:51]
	v_mfma_f32_16x16x32_bf16 v[40:43], v[168:171], v[198:201], v[40:43]
	v_mfma_f32_16x16x32_bf16 v[32:35], v[176:179], v[198:201], v[32:35]
	v_mfma_f32_16x16x32_bf16 v[24:27], v[168:171], v[206:209], v[24:27]
	v_mfma_f32_16x16x32_bf16 v[16:19], v[176:179], v[206:209], v[16:19]
	v_mfma_f32_16x16x32_bf16 v[8:11], v[168:171], v[214:217], v[8:11]
	v_mfma_f32_16x16x32_bf16 v[0:3], v[176:179], v[214:217], v[0:3]
	v_mfma_f32_16x16x32_bf16 v[56:59], v[172:175], v[194:197], v[56:59]
	v_mfma_f32_16x16x32_bf16 v[48:51], v[180:183], v[194:197], v[48:51]
	v_mfma_f32_16x16x32_bf16 v[40:43], v[172:175], v[202:205], v[40:43]
	v_mfma_f32_16x16x32_bf16 v[32:35], v[180:183], v[202:205], v[32:35]
	v_mfma_f32_16x16x32_bf16 v[24:27], v[172:175], v[210:213], v[24:27]
	v_mfma_f32_16x16x32_bf16 v[16:19], v[180:183], v[210:213], v[16:19]
	v_mfma_f32_16x16x32_bf16 v[8:11], v[172:175], v[218:221], v[8:11]
	s_barrier
	v_mfma_f32_16x16x32_bf16 v[0:3], v[180:183], v[218:221], v[0:3]
	s_setprio 0
	s_add_i32 s69, s69, 2
	s_add_u32 s42, s42, 0x100
	s_addc_u32 s43, s43, 0
	s_add_u32 s65, s65, 0x100
	s_addc_u32 s68, s68, 0
	s_cmp_gt_u32 s69, 13
	s_cbranch_scc0 .LBB0_276
	s_and_b64 vcc, exec, s[14:15]
	s_cbranch_vccz .LBB0_279
	s_barrier

; #define PG8_STAGE(bufoff, gbase, voff) do { _Pragma("unroll") for (int _i = 0; _i < 2; ++_i) \
;         __builtin_amdgcn_global_load_lds((const unsigned*)((const char*)(gbase) + (voff)[_i]), (PG8_LAS unsigned*)(lds + (bufoff) + ldsw + _i * 8192), 16, 0, 0); } while (0)
; #define PG8_LDA(dst, b, h) do { _Pragma("unroll") for (int m = 0; m < 4; ++m) _Pragma("unroll") for (int k = 0; k < 2; ++k) dst[m][k] = *(const PG8_LAS bf16x8*)(lds + PG8_SA(b, h) + aoff + m * 2048 + k * 1024); } while (0)
; #define PG8_LDB(dst, b, h) do { _Pragma("unroll") for (int n = 0; n < 2; ++n) _Pragma("unroll") for (int k = 0; k < 2; ++k) dst[n][k] = *(const PG8_LAS bf16x8*)(lds + PG8_SB(b, h) + boff + n * 2048 + k * 1024); } while (0)
; #define PG8_MMA(ai, bj, At, Bt) do { __builtin_amdgcn_s_setprio(1); _Pragma("unroll") for (int m = 0; m < 4; ++m) _Pragma("unroll") for (int n = 0; n < 2; ++n) _Pragma("unroll") for (int k = 0; k < 2; ++k) \
;         acc[ai][bj][m][n] = __builtin_amdgcn_mfma_f32_16x16x32_bf16(Bt[n][k], At[m][k], acc[ai][bj][m][n], 0, 0, 0); __builtin_amdgcn_s_setprio(0); } while (0)
; #define PG8_WAIT_V(n) asm volatile("s_waitcnt vmcnt(" #n ")" ::: "memory")
; template <class Epi, class Sched, bool ALIGN_EPI = false, bool SP2 = false>
; __device__ __forceinline__ void gemm_phase(PG8_LAS unsigned char* lds, const Gemm g, const Sched S, const Epi E) {
;     ...
;             PG8_LDB(B0, 0, 0); PG8_LDB(B1, 0, 1); PG8_SCHED; PG8_LDA(At, 0, 0); PG8_STAGE(PG8_SA(1, 1), a1 + hstep, voffA);
;             PG8_WAIT_V(8); PG8_WAIT_L(0); PG8_BAR; PG8_MMA(0, 0, At, B0); PG8_MMA(0, 1, At, B1); PG8_BAR; PG8_SCHED;
;             PG8_LDA(At, 0, 1); PG8_STAGE(PG8_SB(0, 0), b2, voffB); PG8_STAGE(PG8_SB(0, 1), b2 + hstep, voffB); PG8_STAGE(PG8_SA(0, 0), a2, voffA);
;             PG8_WAIT_V(8); PG8_WAIT_L(0); PG8_BAR; PG8_MMA(1, 0, At, B0); PG8_MMA(1, 1, At, B1); PG8_BAR; PG8_SCHED;
;             PG8_LDB(B0, 1, 0); PG8_LDB(B1, 1, 1); PG8_SCHED; PG8_LDA(At, 1, 0); PG8_STAGE(PG8_SA(0, 1), a2 + hstep, voffA);
;             PG8_WAIT_V(8); PG8_WAIT_L(0); PG8_BAR; PG8_MMA(0, 0, At, B0); PG8_MMA(0, 1, At, B1); PG8_BAR; PG8_SCHED;
;             PG8_LDA(At, 1, 1); PG8_STAGE(PG8_SB(1, 0), b3, voffB); PG8_STAGE(PG8_SB(1, 1), b3 + hstep, voffB); PG8_STAGE(PG8_SA(1, 0), a3, voffA);
;             PG8_WAIT_V(8); PG8_WAIT_L(0); PG8_BAR; PG8_MMA(1, 0, At, B0); PG8_MMA(1, 1, At, B1); PG8_BAR; PG8_SCHED;
.LBB0_356:
	ds_read_b128 v[144:147], v157
	ds_read_b128 v[148:151], v157 offset:1024
	ds_read_b128 v[160:163], v157 offset:2048
	ds_read_b128 v[164:167], v157 offset:3072
	ds_read_b128 v[168:171], v158
	ds_read_b128 v[172:175], v158 offset:1024
	ds_read_b128 v[176:179], v158 offset:2048
	ds_read_b128 v[180:183], v158 offset:3072
	s_add_u32 s40, s38, 0x100
	s_addc_u32 s41, s39, 0
	s_cmp_eq_u32 s65, 40
	s_cselect_b32 s45, s5, s41
	s_cselect_b32 s44, s4, s40
	s_cselect_b32 s43, s17, s64
	s_cselect_b32 s42, s16, s63
	v_lshl_add_u64 v[152:153], s[38:39], 0, v[136:137]
	s_add_i32 m0, s9, 0xc000
	ds_read_b128 v[190:193], v159
	ds_read_b128 v[194:197], v159 offset:1024
	ds_read_b128 v[198:201], v159 offset:2048
	ds_read_b128 v[202:205], v159 offset:3072
	ds_read_b128 v[206:209], v159 offset:4096
	ds_read_b128 v[210:213], v159 offset:5120
	ds_read_b128 v[214:217], v159 offset:6144
	ds_read_b128 v[218:221], v159 offset:7168
	global_load_lds_dwordx4 v[152:153], off
	v_lshl_add_u64 v[152:153], s[38:39], 0, v[138:139]
	s_add_i32 m0, s9, 0xe000
	s_nop 0
	global_load_lds_dwordx4 v[152:153], off
	s_waitcnt vmcnt(8)
	s_waitcnt lgkmcnt(0)
	s_barrier
	s_setprio 1
	s_waitcnt lgkmcnt(0)
	v_mfma_f32_16x16x32_bf16 v[124:127], v[144:147], v[190:193], v[124:127]
	v_mfma_f32_16x16x32_bf16 v[120:123], v[160:163], v[190:193], v[120:123]
	v_mfma_f32_16x16x32_bf16 v[108:111], v[144:147], v[198:201], v[108:111]
	v_mfma_f32_16x16x32_bf16 v[104:107], v[160:163], v[198:201], v[104:107]
	v_mfma_f32_16x16x32_bf16 v[92:95], v[144:147], v[206:209], v[92:95]
	v_mfma_f32_16x16x32_bf16 v[88:91], v[160:163], v[206:209], v[88:91]
	v_mfma_f32_16x16x32_bf16 v[76:79], v[144:147], v[214:217], v[76:79]
	v_mfma_f32_16x16x32_bf16 v[72:75], v[160:163], v[214:217], v[72:75]
	v_mfma_f32_16x16x32_bf16 v[124:127], v[148:151], v[194:197], v[124:127]
	v_mfma_f32_16x16x32_bf16 v[120:123], v[164:167], v[194:197], v[120:123]
	v_mfma_f32_16x16x32_bf16 v[108:111], v[148:151], v[202:205], v[108:111]
	v_mfma_f32_16x16x32_bf16 v[104:107], v[164:167], v[202:205], v[104:107]
	v_mfma_f32_16x16x32_bf16 v[92:95], v[148:151], v[210:213], v[92:95]
	v_mfma_f32_16x16x32_bf16 v[88:91], v[164:167], v[210:213], v[88:91]
	v_mfma_f32_16x16x32_bf16 v[76:79], v[148:151], v[218:221], v[76:79]
	v_mfma_f32_16x16x32_bf16 v[72:75], v[164:167], v[218:221], v[72:75]
	s_setprio 0
	s_setprio 1
	v_mfma_f32_16x16x32_bf16 v[116:119], v[168:171], v[190:193], v[116:119]
	v_mfma_f32_16x16x32_bf16 v[112:115], v[176:179], v[190:193], v[112:115]
	v_mfma_f32_16x16x32_bf16 v[100:103], v[168:171], v[198:201], v[100:103]
	v_mfma_f32_16x16x32_bf16 v[96:99], v[176:179], v[198:201], v[96:99]
	v_mfma_f32_16x16x32_bf16 v[84:87], v[168:171], v[206:209], v[84:87]
	v_mfma_f32_16x16x32_bf16 v[80:83], v[176:179], v[206:209], v[80:83]
	v_mfma_f32_16x16x32_bf16 v[68:71], v[168:171], v[214:217], v[68:71]
	v_mfma_f32_16x16x32_bf16 v[64:67], v[176:179], v[214:217], v[64:67]
	v_mfma_f32_16x16x32_bf16 v[116:119], v[172:175], v[194:197], v[116:119]
	v_mfma_f32_16x16x32_bf16 v[112:115], v[180:183], v[194:197], v[112:115]
	v_mfma_f32_16x16x32_bf16 v[100:103], v[172:175], v[202:205], v[100:103]
	v_mfma_f32_16x16x32_bf16 v[96:99], v[180:183], v[202:205], v[96:99]
	v_mfma_f32_16x16x32_bf16 v[84:87], v[172:175], v[210:213], v[84:87]
	v_mfma_f32_16x16x32_bf16 v[80:83], v[180:183], v[210:213], v[80:83]
	v_mfma_f32_16x16x32_bf16 v[68:71], v[172:175], v[218:221], v[68:71]
	s_barrier
	v_mfma_f32_16x16x32_bf16 v[64:67], v[180:183], v[218:221], v[64:67]
	s_setprio 0
	s_add_i32 s38, s55, s8
	v_lshl_add_u64 v[152:153], s[42:43], 0, v[130:131]
	s_mov_b32 m0, s38
	ds_read_b128 v[190:193], v159 offset:16384
	ds_read_b128 v[194:197], v159 offset:17408
	ds_read_b128 v[198:201], v159 offset:18432
	ds_read_b128 v[202:205], v159 offset:19456
	ds_read_b128 v[206:209], v159 offset:20480
	ds_read_b128 v[210:213], v159 offset:21504
	ds_read_b128 v[214:217], v159 offset:22528
	ds_read_b128 v[218:221], v159 offset:23552
	global_load_lds_dwordx4 v[152:153], off
	s_add_i32 m0, s38, 0x2000
	s_add_u32 s38, s42, 0xb0000
	v_lshl_add_u64 v[184:185], s[42:43], 0, v[134:135]
	s_addc_u32 s39, s43, 0
	s_add_i32 s68, s58, s8
	global_load_lds_dwordx4 v[184:185], off
	v_lshl_add_u64 v[222:223], s[38:39], 0, v[130:131]
	s_mov_b32 m0, s68
	v_lshl_add_u64 v[224:225], s[44:45], 0, v[132:133]
	global_load_lds_dwordx4 v[222:223], off
	v_lshl_add_u64 v[222:223], s[38:39], 0, v[134:135]
	s_add_i32 m0, s68, 0x2000
	s_nop 0
	global_load_lds_dwordx4 v[222:223], off
	v_lshl_add_u64 v[222:223], s[44:45], 0, v[128:129]
	s_mov_b32 m0, s9
	s_nop 0
	global_load_lds_dwordx4 v[222:223], off
	s_mov_b32 m0, s18
	s_nop 0
	global_load_lds_dwordx4 v[224:225], off
	s_waitcnt vmcnt(8)
	s_waitcnt lgkmcnt(0)
	s_barrier
; #define PG8_STAGE(bufoff, gbase, voff) do { _Pragma("unroll") for (int _i = 0; _i < 2; ++_i) \
;         __builtin_amdgcn_global_load_lds((const unsigned*)((const char*)(gbase) + (voff)[_i]), (PG8_LAS unsigned*)(lds + (bufoff) + ldsw + _i * 8192), 16, 0, 0); } while (0)
; #define PG8_LDA(dst, b, h) do { _Pragma("unroll") for (int m = 0; m < 4; ++m) _Pragma("unroll") for (int k = 0; k < 2; ++k) dst[m][k] = *(const PG8_LAS bf16x8*)(lds + PG8_SA(b, h) + aoff + m * 2048 + k * 1024); } while (0)
; #define PG8_LDB(dst, b, h) do { _Pragma("unroll") for (int n = 0; n < 2; ++n) _Pragma("unroll") for (int k = 0; k < 2; ++k) dst[n][k] = *(const PG8_LAS bf16x8*)(lds + PG8_SB(b, h) + boff + n * 2048 + k * 1024); } while (0)
; #define PG8_MMA(ai, bj, At, Bt) do { __builtin_amdgcn_s_setprio(1); _Pragma("unroll") for (int m = 0; m < 4; ++m) _Pragma("unroll") for (int n = 0; n < 2; ++n) _Pragma("unroll") for (int k = 0; k < 2; ++k) \
;         acc[ai][bj][m][n] = __builtin_amdgcn_mfma_f32_16x16x32_bf16(Bt[n][k], At[m][k], acc[ai][bj][m][n], 0, 0, 0); __builtin_amdgcn_s_setprio(0); } while (0)
; #define PG8_WAIT_V(n) asm volatile("s_waitcnt vmcnt(" #n ")" ::: "memory")
; template <class Epi, class Sched, bool ALIGN_EPI = false, bool SP2 = false>
; __device__ __forceinline__ void gemm_phase(PG8_LAS unsigned char* lds, const Gemm g, const Sched S, const Epi E) {
;     ...
;             PG8_LDB(B0, 0, 0); PG8_LDB(B1, 0, 1); PG8_SCHED; PG8_LDA(At, 0, 0); PG8_STAGE(PG8_SA(1, 1), a1 + hstep, voffA);
;             PG8_WAIT_V(8); PG8_WAIT_L(0); PG8_BAR; PG8_MMA(0, 0, At, B0); PG8_MMA(0, 1, At, B1); PG8_BAR; PG8_SCHED;
;             PG8_LDA(At, 0, 1); PG8_STAGE(PG8_SB(0, 0), b2, voffB); PG8_STAGE(PG8_SB(0, 1), b2 + hstep, voffB); PG8_STAGE(PG8_SA(0, 0), a2, voffA);
;             PG8_WAIT_V(8); PG8_WAIT_L(0); PG8_BAR; PG8_MMA(1, 0, At, B0); PG8_MMA(1, 1, At, B1); PG8_BAR; PG8_SCHED;
;             PG8_LDB(B0, 1, 0); PG8_LDB(B1, 1, 1); PG8_SCHED; PG8_LDA(At, 1, 0); PG8_STAGE(PG8_SA(0, 1), a2 + hstep, voffA);
;             PG8_WAIT_V(8); PG8_WAIT_L(0); PG8_BAR; PG8_MMA(0, 0, At, B0); PG8_MMA(0, 1, At, B1); PG8_BAR; PG8_SCHED;
;             PG8_LDA(At, 1, 1); PG8_STAGE(PG8_SB(1, 0), b3, voffB); PG8_STAGE(PG8_SB(1, 1), b3 + hstep, voffB); PG8_STAGE(PG8_SA(1, 0), a3, voffA);
;             PG8_WAIT_V(8); PG8_WAIT_L(0); PG8_BAR; PG8_MMA(1, 0, At, B0); PG8_MMA(1, 1, At, B1); PG8_BAR; PG8_SCHED;
	s_setprio 1
	s_waitcnt lgkmcnt(0)
	v_mfma_f32_16x16x32_bf16 v[60:63], v[144:147], v[190:193], v[60:63]
	v_mfma_f32_16x16x32_bf16 v[56:59], v[160:163], v[190:193], v[56:59]
	v_mfma_f32_16x16x32_bf16 v[44:47], v[144:147], v[198:201], v[44:47]
	v_mfma_f32_16x16x32_bf16 v[40:43], v[160:163], v[198:201], v[40:43]
	v_mfma_f32_16x16x32_bf16 v[28:31], v[144:147], v[206:209], v[28:31]
	v_mfma_f32_16x16x32_bf16 v[24:27], v[160:163], v[206:209], v[24:27]
	v_mfma_f32_16x16x32_bf16 v[12:15], v[144:147], v[214:217], v[12:15]
	v_mfma_f32_16x16x32_bf16 v[8:11], v[160:163], v[214:217], v[8:11]
	v_mfma_f32_16x16x32_bf16 v[60:63], v[148:151], v[194:197], v[60:63]
	v_mfma_f32_16x16x32_bf16 v[56:59], v[164:167], v[194:197], v[56:59]
	v_mfma_f32_16x16x32_bf16 v[44:47], v[148:151], v[202:205], v[44:47]
	v_mfma_f32_16x16x32_bf16 v[40:43], v[164:167], v[202:205], v[40:43]
	v_mfma_f32_16x16x32_bf16 v[28:31], v[148:151], v[210:213], v[28:31]
	v_mfma_f32_16x16x32_bf16 v[24:27], v[164:167], v[210:213], v[24:27]
	v_mfma_f32_16x16x32_bf16 v[12:15], v[148:151], v[218:221], v[12:15]
	v_mfma_f32_16x16x32_bf16 v[8:11], v[164:167], v[218:221], v[8:11]
	s_setprio 0
	s_setprio 1
	v_mfma_f32_16x16x32_bf16 v[52:55], v[168:171], v[190:193], v[52:55]
	v_mfma_f32_16x16x32_bf16 v[48:51], v[176:179], v[190:193], v[48:51]
	v_mfma_f32_16x16x32_bf16 v[36:39], v[168:171], v[198:201], v[36:39]
	v_mfma_f32_16x16x32_bf16 v[32:35], v[176:179], v[198:201], v[32:35]
	v_mfma_f32_16x16x32_bf16 v[20:23], v[168:171], v[206:209], v[20:23]
	v_mfma_f32_16x16x32_bf16 v[16:19], v[176:179], v[206:209], v[16:19]
	v_mfma_f32_16x16x32_bf16 v[4:7], v[168:171], v[214:217], v[4:7]
	v_mfma_f32_16x16x32_bf16 v[0:3], v[176:179], v[214:217], v[0:3]
	v_mfma_f32_16x16x32_bf16 v[52:55], v[172:175], v[194:197], v[52:55]
	v_mfma_f32_16x16x32_bf16 v[48:51], v[180:183], v[194:197], v[48:51]
	v_mfma_f32_16x16x32_bf16 v[36:39], v[172:175], v[202:205], v[36:39]
	v_mfma_f32_16x16x32_bf16 v[32:35], v[180:183], v[202:205], v[32:35]
	v_mfma_f32_16x16x32_bf16 v[20:23], v[172:175], v[210:213], v[20:23]
	v_mfma_f32_16x16x32_bf16 v[16:19], v[180:183], v[210:213], v[16:19]
	v_mfma_f32_16x16x32_bf16 v[4:7], v[172:175], v[218:221], v[4:7]
	s_barrier
	v_mfma_f32_16x16x32_bf16 v[0:3], v[180:183], v[218:221], v[0:3]
	s_setprio 0
	s_add_i32 s68, 0, 0x18000
	s_add_i32 s69, 0, 0x1c000
	v_add_u32_e32 v164, s68, v156
	v_add_u32_e32 v180, s69, v156
	ds_read_b128 v[144:147], v164
	ds_read_b128 v[148:151], v164 offset:1024
	ds_read_b128 v[160:163], v164 offset:2048
	ds_read_b128 v[164:167], v164 offset:3072
	ds_read_b128 v[168:171], v180
	ds_read_b128 v[172:175], v180 offset:1024
	ds_read_b128 v[176:179], v180 offset:2048
	ds_read_b128 v[180:183], v180 offset:3072
	s_add_u32 s38, s44, 0xb0000
	s_addc_u32 s39, s45, 0
	s_mov_b32 m0, s19
	v_lshl_add_u64 v[226:227], s[38:39], 0, v[128:129]
	ds_read_b128 v[190:193], v159 offset:32768
	ds_read_b128 v[194:197], v159 offset:33792
	ds_read_b128 v[198:201], v159 offset:34816
	ds_read_b128 v[202:205], v159 offset:35840
	ds_read_b128 v[206:209], v159 offset:36864
	ds_read_b128 v[210:213], v159 offset:37888
	ds_read_b128 v[214:217], v159 offset:38912
	ds_read_b128 v[218:221], v159 offset:39936
	global_load_lds_dwordx4 v[226:227], off
	v_lshl_add_u64 v[226:227], s[38:39], 0, v[132:133]
	s_mov_b32 m0, s33
	s_nop 0
	global_load_lds_dwordx4 v[226:227], off
	s_waitcnt vmcnt(8)
	s_waitcnt lgkmcnt(0)
	s_barrier
	s_setprio 1
	s_waitcnt lgkmcnt(0)
	v_mfma_f32_16x16x32_bf16 v[124:127], v[144:147], v[190:193], v[124:127]
	v_mfma_f32_16x16x32_bf16 v[120:123], v[160:163], v[190:193], v[120:123]
	v_mfma_f32_16x16x32_bf16 v[108:111], v[144:147], v[198:201], v[108:111]
	v_mfma_f32_16x16x32_bf16 v[104:107], v[160:163], v[198:201], v[104:107]
	v_mfma_f32_16x16x32_bf16 v[92:95], v[144:147], v[206:209], v[92:95]
	v_mfma_f32_16x16x32_bf16 v[88:91], v[160:163], v[206:209], v[88:91]
	v_mfma_f32_16x16x32_bf16 v[76:79], v[144:147], v[214:217], v[76:79]
	v_mfma_f32_16x16x32_bf16 v[72:75], v[160:163], v[214:217], v[72:75]
	v_mfma_f32_16x16x32_bf16 v[124:127], v[148:151], v[194:197], v[124:127]
	v_mfma_f32_16x16x32_bf16 v[120:123], v[164:167], v[194:197], v[120:123]
	v_mfma_f32_16x16x32_bf16 v[108:111], v[148:151], v[202:205], v[108:111]
	v_mfma_f32_16x16x32_bf16 v[104:107], v[164:167], v[202:205], v[104:107]
	v_mfma_f32_16x16x32_bf16 v[92:95], v[148:151], v[210:213], v[92:95]
	v_mfma_f32_16x16x32_bf16 v[88:91], v[164:167], v[210:213], v[88:91]
	v_mfma_f32_16x16x32_bf16 v[76:79], v[148:151], v[218:221], v[76:79]
	v_mfma_f32_16x16x32_bf16 v[72:75], v[164:167], v[218:221], v[72:75]
	s_setprio 0
	s_setprio 1
	v_mfma_f32_16x16x32_bf16 v[116:119], v[168:171], v[190:193], v[116:119]
	v_mfma_f32_16x16x32_bf16 v[112:115], v[176:179], v[190:193], v[112:115]
	v_mfma_f32_16x16x32_bf16 v[100:103], v[168:171], v[198:201], v[100:103]
	v_mfma_f32_16x16x32_bf16 v[96:99], v[176:179], v[198:201], v[96:99]
	v_mfma_f32_16x16x32_bf16 v[84:87], v[168:171], v[206:209], v[84:87]
	v_mfma_f32_16x16x32_bf16 v[80:83], v[176:179], v[206:209], v[80:83]
	v_mfma_f32_16x16x32_bf16 v[68:71], v[168:171], v[214:217], v[68:71]
	v_mfma_f32_16x16x32_bf16 v[64:67], v[176:179], v[214:217], v[64:67]
	v_mfma_f32_16x16x32_bf16 v[116:119], v[172:175], v[194:197], v[116:119]
	v_mfma_f32_16x16x32_bf16 v[112:115], v[180:183], v[194:197], v[112:115]
	v_mfma_f32_16x16x32_bf16 v[100:103], v[172:175], v[202:205], v[100:103]
	v_mfma_f32_16x16x32_bf16 v[96:99], v[180:183], v[202:205], v[96:99]
	v_mfma_f32_16x16x32_bf16 v[84:87], v[172:175], v[210:213], v[84:87]
	v_mfma_f32_16x16x32_bf16 v[80:83], v[180:183], v[210:213], v[80:83]
	v_mfma_f32_16x16x32_bf16 v[68:71], v[172:175], v[218:221], v[68:71]
	s_barrier
; #define PG8_STAGE(bufoff, gbase, voff) do { _Pragma("unroll") for (int _i = 0; _i < 2; ++_i) \
;         __builtin_amdgcn_global_load_lds((const unsigned*)((const char*)(gbase) + (voff)[_i]), (PG8_LAS unsigned*)(lds + (bufoff) + ldsw + _i * 8192), 16, 0, 0); } while (0)
; #define PG8_LDA(dst, b, h) do { _Pragma("unroll") for (int m = 0; m < 4; ++m) _Pragma("unroll") for (int k = 0; k < 2; ++k) dst[m][k] = *(const PG8_LAS bf16x8*)(lds + PG8_SA(b, h) + aoff + m * 2048 + k * 1024); } while (0)
; #define PG8_LDB(dst, b, h) do { _Pragma("unroll") for (int n = 0; n < 2; ++n) _Pragma("unroll") for (int k = 0; k < 2; ++k) dst[n][k] = *(const PG8_LAS bf16x8*)(lds + PG8_SB(b, h) + boff + n * 2048 + k * 1024); } while (0)
; #define PG8_MMA(ai, bj, At, Bt) do { __builtin_amdgcn_s_setprio(1); _Pragma("unroll") for (int m = 0; m < 4; ++m) _Pragma("unroll") for (int n = 0; n < 2; ++n) _Pragma("unroll") for (int k = 0; k < 2; ++k) \
;         acc[ai][bj][m][n] = __builtin_amdgcn_mfma_f32_16x16x32_bf16(Bt[n][k], At[m][k], acc[ai][bj][m][n], 0, 0, 0); __builtin_amdgcn_s_setprio(0); } while (0)
; #define PG8_WAIT_V(n) asm volatile("s_waitcnt vmcnt(" #n ")" ::: "memory")
; template <class Epi, class Sched, bool ALIGN_EPI = false, bool SP2 = false>
; __device__ __forceinline__ void gemm_phase(PG8_LAS unsigned char* lds, const Gemm g, const Sched S, const Epi E) {
;     ...
;             PG8_LDB(B0, 0, 0); PG8_LDB(B1, 0, 1); PG8_SCHED; PG8_LDA(At, 0, 0); PG8_STAGE(PG8_SA(1, 1), a1 + hstep, voffA);
;             PG8_WAIT_V(8); PG8_WAIT_L(0); PG8_BAR; PG8_MMA(0, 0, At, B0); PG8_MMA(0, 1, At, B1); PG8_BAR; PG8_SCHED;
;             PG8_LDA(At, 0, 1); PG8_STAGE(PG8_SB(0, 0), b2, voffB); PG8_STAGE(PG8_SB(0, 1), b2 + hstep, voffB); PG8_STAGE(PG8_SA(0, 0), a2, voffA);
;             PG8_WAIT_V(8); PG8_WAIT_L(0); PG8_BAR; PG8_MMA(1, 0, At, B0); PG8_MMA(1, 1, At, B1); PG8_BAR; PG8_SCHED;
;             PG8_LDB(B0, 1, 0); PG8_LDB(B1, 1, 1); PG8_SCHED; PG8_LDA(At, 1, 0); PG8_STAGE(PG8_SA(0, 1), a2 + hstep, voffA);
;             PG8_WAIT_V(8); PG8_WAIT_L(0); PG8_BAR; PG8_MMA(0, 0, At, B0); PG8_MMA(0, 1, At, B1); PG8_BAR; PG8_SCHED;
;             PG8_LDA(At, 1, 1); PG8_STAGE(PG8_SB(1, 0), b3, voffB); PG8_STAGE(PG8_SB(1, 1), b3 + hstep, voffB); PG8_STAGE(PG8_SA(1, 0), a3, voffA);
;             PG8_WAIT_V(8); PG8_WAIT_L(0); PG8_BAR; PG8_MMA(1, 0, At, B0); PG8_MMA(1, 1, At, B1); PG8_BAR; PG8_SCHED;
	v_mfma_f32_16x16x32_bf16 v[64:67], v[180:183], v[218:221], v[64:67]
	s_setprio 0
	s_add_i32 s38, s68, s8
	v_lshl_add_u64 v[152:153], v[152:153], 0, s[12:13]
	s_mov_b32 m0, s38
	ds_read_b128 v[190:193], v159 offset:49152
	ds_read_b128 v[194:197], v159 offset:50176
	ds_read_b128 v[198:201], v159 offset:51200
	ds_read_b128 v[202:205], v159 offset:52224
	ds_read_b128 v[206:209], v159 offset:53248
	ds_read_b128 v[210:213], v159 offset:54272
	ds_read_b128 v[214:217], v159 offset:55296
	ds_read_b128 v[218:221], v159 offset:56320
	global_load_lds_dwordx4 v[152:153], off
	s_add_i32 m0, s38, 0x2000
	s_add_u32 s38, s42, 0xb0080
	v_lshl_add_u64 v[152:153], v[184:185], 0, s[12:13]
	s_addc_u32 s39, s43, 0
	s_add_i32 s42, s69, s8
	global_load_lds_dwordx4 v[152:153], off
	v_lshl_add_u64 v[152:153], s[38:39], 0, v[130:131]
	s_mov_b32 m0, s42
	s_nop 0
	global_load_lds_dwordx4 v[152:153], off
	v_lshl_add_u64 v[152:153], s[38:39], 0, v[134:135]
	s_add_i32 m0, s42, 0x2000
	s_nop 0
	global_load_lds_dwordx4 v[152:153], off
	v_lshl_add_u64 v[152:153], v[222:223], 0, s[12:13]
	s_mov_b32 m0, s49
	s_nop 0
	global_load_lds_dwordx4 v[152:153], off
	v_lshl_add_u64 v[152:153], v[224:225], 0, s[12:13]
	s_mov_b32 m0, s50
	s_nop 0
	global_load_lds_dwordx4 v[152:153], off
	s_waitcnt vmcnt(8)
	s_waitcnt lgkmcnt(0)
	s_barrier
	s_setprio 1
	s_waitcnt lgkmcnt(0)
	v_mfma_f32_16x16x32_bf16 v[60:63], v[144:147], v[190:193], v[60:63]
	v_mfma_f32_16x16x32_bf16 v[56:59], v[160:163], v[190:193], v[56:59]
	v_mfma_f32_16x16x32_bf16 v[44:47], v[144:147], v[198:201], v[44:47]
	v_mfma_f32_16x16x32_bf16 v[40:43], v[160:163], v[198:201], v[40:43]
	v_mfma_f32_16x16x32_bf16 v[28:31], v[144:147], v[206:209], v[28:31]
	v_mfma_f32_16x16x32_bf16 v[24:27], v[160:163], v[206:209], v[24:27]
	v_mfma_f32_16x16x32_bf16 v[12:15], v[144:147], v[214:217], v[12:15]
	v_mfma_f32_16x16x32_bf16 v[8:11], v[160:163], v[214:217], v[8:11]
	v_mfma_f32_16x16x32_bf16 v[60:63], v[148:151], v[194:197], v[60:63]
	v_mfma_f32_16x16x32_bf16 v[56:59], v[164:167], v[194:197], v[56:59]
	v_mfma_f32_16x16x32_bf16 v[44:47], v[148:151], v[202:205], v[44:47]
	v_mfma_f32_16x16x32_bf16 v[40:43], v[164:167], v[202:205], v[40:43]
	v_mfma_f32_16x16x32_bf16 v[28:31], v[148:151], v[210:213], v[28:31]
	v_mfma_f32_16x16x32_bf16 v[24:27], v[164:167], v[210:213], v[24:27]
	v_mfma_f32_16x16x32_bf16 v[12:15], v[148:151], v[218:221], v[12:15]
	v_mfma_f32_16x16x32_bf16 v[8:11], v[164:167], v[218:221], v[8:11]
	s_setprio 0
	s_setprio 1
	v_mfma_f32_16x16x32_bf16 v[52:55], v[168:171], v[190:193], v[52:55]
	v_mfma_f32_16x16x32_bf16 v[48:51], v[176:179], v[190:193], v[48:51]
	v_mfma_f32_16x16x32_bf16 v[36:39], v[168:171], v[198:201], v[36:39]
	v_mfma_f32_16x16x32_bf16 v[32:35], v[176:179], v[198:201], v[32:35]
	v_mfma_f32_16x16x32_bf16 v[20:23], v[168:171], v[206:209], v[20:23]
	v_mfma_f32_16x16x32_bf16 v[16:19], v[176:179], v[206:209], v[16:19]
	v_mfma_f32_16x16x32_bf16 v[4:7], v[168:171], v[214:217], v[4:7]
	v_mfma_f32_16x16x32_bf16 v[0:3], v[176:179], v[214:217], v[0:3]
	v_mfma_f32_16x16x32_bf16 v[52:55], v[172:175], v[194:197], v[52:55]
	v_mfma_f32_16x16x32_bf16 v[48:51], v[180:183], v[194:197], v[48:51]
	v_mfma_f32_16x16x32_bf16 v[36:39], v[172:175], v[202:205], v[36:39]
	v_mfma_f32_16x16x32_bf16 v[32:35], v[180:183], v[202:205], v[32:35]
	v_mfma_f32_16x16x32_bf16 v[20:23], v[172:175], v[210:213], v[20:23]
	v_mfma_f32_16x16x32_bf16 v[16:19], v[180:183], v[210:213], v[16:19]
	v_mfma_f32_16x16x32_bf16 v[4:7], v[172:175], v[218:221], v[4:7]
	s_barrier
	v_mfma_f32_16x16x32_bf16 v[0:3], v[180:183], v[218:221], v[0:3]
	s_setprio 0
	s_add_i32 s65, s65, 2
	s_add_u32 s63, s63, 0x100
	s_addc_u32 s64, s64, 0
	s_cmp_gt_u32 s65, 41
	s_mov_b64 s[38:39], s[40:41]
	s_cbranch_scc0 .LBB0_356
	s_and_b64 vcc, exec, s[14:15]
	s_cbranch_vccz .LBB0_359
	s_barrier

; #define PG8_STAGE(bufoff, gbase, voff) do { _Pragma("unroll") for (int _i = 0; _i < 2; ++_i) \
;         __builtin_amdgcn_global_load_lds((const unsigned*)((const char*)(gbase) + (voff)[_i]), (PG8_LAS unsigned*)(lds + (bufoff) + ldsw + _i * 8192), 16, 0, 0); } while (0)
; #define PG8_LDA(dst, b, h) do { _Pragma("unroll") for (int m = 0; m < 4; ++m) _Pragma("unroll") for (int k = 0; k < 2; ++k) dst[m][k] = *(const PG8_LAS bf16x8*)(lds + PG8_SA(b, h) + aoff + m * 2048 + k * 1024); } while (0)
; #define PG8_LDB(dst, b, h) do { _Pragma("unroll") for (int n = 0; n < 2; ++n) _Pragma("unroll") for (int k = 0; k < 2; ++k) dst[n][k] = *(const PG8_LAS bf16x8*)(lds + PG8_SB(b, h) + boff + n * 2048 + k * 1024); } while (0)
; #define PG8_MMA(ai, bj, At, Bt) do { __builtin_amdgcn_s_setprio(1); _Pragma("unroll") for (int m = 0; m < 4; ++m) _Pragma("unroll") for (int n = 0; n < 2; ++n) _Pragma("unroll") for (int k = 0; k < 2; ++k) \
;         acc[ai][bj][m][n] = __builtin_amdgcn_mfma_f32_16x16x32_bf16(Bt[n][k], At[m][k], acc[ai][bj][m][n], 0, 0, 0); __builtin_amdgcn_s_setprio(0); } while (0)
; #define PG8_WAIT_V(n) asm volatile("s_waitcnt vmcnt(" #n ")" ::: "memory")
; template <class Epi, class Sched, bool ALIGN_EPI = false, bool SP2 = false>
; __device__ __forceinline__ void gemm_phase(PG8_LAS unsigned char* lds, const Gemm g, const Sched S, const Epi E) {
;     ...
;             PG8_LDB(B0, 0, 0); PG8_LDB(B1, 0, 1); PG8_SCHED; PG8_LDA(At, 0, 0); PG8_STAGE(PG8_SA(1, 1), a1 + hstep, voffA);
;             PG8_WAIT_V(8); PG8_WAIT_L(0); PG8_BAR; PG8_MMA(0, 0, At, B0); PG8_MMA(0, 1, At, B1); PG8_BAR; PG8_SCHED;
;             PG8_LDA(At, 0, 1); PG8_STAGE(PG8_SB(0, 0), b2, voffB); PG8_STAGE(PG8_SB(0, 1), b2 + hstep, voffB); PG8_STAGE(PG8_SA(0, 0), a2, voffA);
;             PG8_WAIT_V(8); PG8_WAIT_L(0); PG8_BAR; PG8_MMA(1, 0, At, B0); PG8_MMA(1, 1, At, B1); PG8_BAR; PG8_SCHED;
;             PG8_LDB(B0, 1, 0); PG8_LDB(B1, 1, 1); PG8_SCHED; PG8_LDA(At, 1, 0); PG8_STAGE(PG8_SA(0, 1), a2 + hstep, voffA);
;             PG8_WAIT_V(8); PG8_WAIT_L(0); PG8_BAR; PG8_MMA(0, 0, At, B0); PG8_MMA(0, 1, At, B1); PG8_BAR; PG8_SCHED;
;             PG8_LDA(At, 1, 1); PG8_STAGE(PG8_SB(1, 0), b3, voffB); PG8_STAGE(PG8_SB(1, 1), b3 + hstep, voffB); PG8_STAGE(PG8_SA(1, 0), a3, voffA);
;             PG8_WAIT_V(8); PG8_WAIT_L(0); PG8_BAR; PG8_MMA(1, 0, At, B0); PG8_MMA(1, 1, At, B1); PG8_BAR; PG8_SCHED;
.LBB0_484:
	ds_read_b128 v[128:131], v193
	ds_read_b128 v[132:135], v193 offset:1024
	ds_read_b128 v[150:153], v193 offset:2048
	ds_read_b128 v[154:157], v193 offset:3072
	ds_read_b128 v[158:161], v194
	ds_read_b128 v[162:165], v194 offset:1024
	ds_read_b128 v[166:169], v194 offset:2048
	ds_read_b128 v[170:173], v194 offset:3072
	s_add_u32 s10, s6, 0xfffc0080
	s_addc_u32 s11, s7, -1
	s_cmp_eq_u32 s61, 12
	s_cselect_b32 s93, s1, s11
	s_cselect_b32 s92, s33, s10
	s_cselect_b32 s11, s36, s60
	s_cselect_b32 s10, s58, s59
	v_lshl_add_u64 v[220:221], s[6:7], 0, v[142:143]
	s_add_i32 m0, s19, 0xc000
	ds_read_b128 v[174:177], v195
	ds_read_b128 v[178:181], v195 offset:1024
	ds_read_b128 v[182:185], v195 offset:2048
	ds_read_b128 v[200:203], v195 offset:3072
	ds_read_b128 v[204:207], v195 offset:4096
	ds_read_b128 v[208:211], v195 offset:5120
	ds_read_b128 v[212:215], v195 offset:6144
	ds_read_b128 v[216:219], v195 offset:7168
	global_load_lds_dwordx4 v[220:221], off
	v_lshl_add_u64 v[220:221], s[6:7], 0, v[144:145]
	s_add_i32 m0, s19, 0xe000
	s_nop 0
	global_load_lds_dwordx4 v[220:221], off
	s_waitcnt vmcnt(8)
	s_waitcnt lgkmcnt(0)
	s_barrier
	s_setprio 1
	s_waitcnt lgkmcnt(0)
	v_mfma_f32_16x16x32_bf16 v[124:127], v[128:131], v[174:177], v[124:127]
	v_mfma_f32_16x16x32_bf16 v[120:123], v[150:153], v[174:177], v[120:123]
	v_mfma_f32_16x16x32_bf16 v[108:111], v[128:131], v[182:185], v[108:111]
	v_mfma_f32_16x16x32_bf16 v[104:107], v[150:153], v[182:185], v[104:107]
	v_mfma_f32_16x16x32_bf16 v[92:95], v[128:131], v[204:207], v[92:95]
	v_mfma_f32_16x16x32_bf16 v[88:91], v[150:153], v[204:207], v[88:91]
	v_mfma_f32_16x16x32_bf16 v[76:79], v[128:131], v[212:215], v[76:79]
	v_mfma_f32_16x16x32_bf16 v[72:75], v[150:153], v[212:215], v[72:75]
	v_mfma_f32_16x16x32_bf16 v[124:127], v[132:135], v[178:181], v[124:127]
	v_mfma_f32_16x16x32_bf16 v[120:123], v[154:157], v[178:181], v[120:123]
	v_mfma_f32_16x16x32_bf16 v[108:111], v[132:135], v[200:203], v[108:111]
	v_mfma_f32_16x16x32_bf16 v[104:107], v[154:157], v[200:203], v[104:107]
	v_mfma_f32_16x16x32_bf16 v[92:95], v[132:135], v[208:211], v[92:95]
	v_mfma_f32_16x16x32_bf16 v[88:91], v[154:157], v[208:211], v[88:91]
	v_mfma_f32_16x16x32_bf16 v[76:79], v[132:135], v[216:219], v[76:79]
	v_mfma_f32_16x16x32_bf16 v[72:75], v[154:157], v[216:219], v[72:75]
	s_setprio 0
	s_setprio 1
	v_mfma_f32_16x16x32_bf16 v[116:119], v[158:161], v[174:177], v[116:119]
	v_mfma_f32_16x16x32_bf16 v[112:115], v[166:169], v[174:177], v[112:115]
	v_mfma_f32_16x16x32_bf16 v[100:103], v[158:161], v[182:185], v[100:103]
	v_mfma_f32_16x16x32_bf16 v[96:99], v[166:169], v[182:185], v[96:99]
	v_mfma_f32_16x16x32_bf16 v[84:87], v[158:161], v[204:207], v[84:87]
	v_mfma_f32_16x16x32_bf16 v[80:83], v[166:169], v[204:207], v[80:83]
	v_mfma_f32_16x16x32_bf16 v[68:71], v[158:161], v[212:215], v[68:71]
	v_mfma_f32_16x16x32_bf16 v[64:67], v[166:169], v[212:215], v[64:67]
	v_mfma_f32_16x16x32_bf16 v[116:119], v[162:165], v[178:181], v[116:119]
	v_mfma_f32_16x16x32_bf16 v[112:115], v[170:173], v[178:181], v[112:115]
	v_mfma_f32_16x16x32_bf16 v[100:103], v[162:165], v[200:203], v[100:103]
	v_mfma_f32_16x16x32_bf16 v[96:99], v[170:173], v[200:203], v[96:99]
	v_mfma_f32_16x16x32_bf16 v[84:87], v[162:165], v[208:211], v[84:87]
	v_mfma_f32_16x16x32_bf16 v[80:83], v[170:173], v[208:211], v[80:83]
	v_mfma_f32_16x16x32_bf16 v[68:71], v[162:165], v[216:219], v[68:71]
	s_barrier
	v_mfma_f32_16x16x32_bf16 v[64:67], v[170:173], v[216:219], v[64:67]
	s_setprio 0
	s_add_i32 s85, s65, s18
	v_lshl_add_u64 v[220:221], s[10:11], 0, v[136:137]
	s_mov_b32 m0, s85
	ds_read_b128 v[174:177], v195 offset:16384
	ds_read_b128 v[178:181], v195 offset:17408
	ds_read_b128 v[182:185], v195 offset:18432
	ds_read_b128 v[200:203], v195 offset:19456
	ds_read_b128 v[204:207], v195 offset:20480
	ds_read_b128 v[208:211], v195 offset:21504
	ds_read_b128 v[212:215], v195 offset:22528
	ds_read_b128 v[216:219], v195 offset:23552
	global_load_lds_dwordx4 v[220:221], off
	s_add_i32 m0, s85, 0x2000
	s_add_u32 s96, s10, 0x40000
	v_lshl_add_u64 v[222:223], s[10:11], 0, v[138:139]
	s_addc_u32 s97, s11, 0
	s_add_i32 s85, s46, s18
	global_load_lds_dwordx4 v[222:223], off
	v_lshl_add_u64 v[224:225], s[96:97], 0, v[136:137]
	s_mov_b32 m0, s85
	v_lshl_add_u64 v[226:227], s[92:93], 0, v[138:139]
	global_load_lds_dwordx4 v[224:225], off
	v_lshl_add_u64 v[224:225], s[96:97], 0, v[138:139]
	s_add_i32 m0, s85, 0x2000
	s_nop 0
	global_load_lds_dwordx4 v[224:225], off
	v_lshl_add_u64 v[224:225], s[92:93], 0, v[136:137]
	s_mov_b32 m0, s19
	s_nop 0
	global_load_lds_dwordx4 v[224:225], off
	s_mov_b32 m0, s95
	s_nop 0
	global_load_lds_dwordx4 v[226:227], off
	s_waitcnt vmcnt(8)
	s_waitcnt lgkmcnt(0)
	s_barrier
; #define PG8_STAGE(bufoff, gbase, voff) do { _Pragma("unroll") for (int _i = 0; _i < 2; ++_i) \
;         __builtin_amdgcn_global_load_lds((const unsigned*)((const char*)(gbase) + (voff)[_i]), (PG8_LAS unsigned*)(lds + (bufoff) + ldsw + _i * 8192), 16, 0, 0); } while (0)
; #define PG8_LDA(dst, b, h) do { _Pragma("unroll") for (int m = 0; m < 4; ++m) _Pragma("unroll") for (int k = 0; k < 2; ++k) dst[m][k] = *(const PG8_LAS bf16x8*)(lds + PG8_SA(b, h) + aoff + m * 2048 + k * 1024); } while (0)
; #define PG8_LDB(dst, b, h) do { _Pragma("unroll") for (int n = 0; n < 2; ++n) _Pragma("unroll") for (int k = 0; k < 2; ++k) dst[n][k] = *(const PG8_LAS bf16x8*)(lds + PG8_SB(b, h) + boff + n * 2048 + k * 1024); } while (0)
; #define PG8_MMA(ai, bj, At, Bt) do { __builtin_amdgcn_s_setprio(1); _Pragma("unroll") for (int m = 0; m < 4; ++m) _Pragma("unroll") for (int n = 0; n < 2; ++n) _Pragma("unroll") for (int k = 0; k < 2; ++k) \
;         acc[ai][bj][m][n] = __builtin_amdgcn_mfma_f32_16x16x32_bf16(Bt[n][k], At[m][k], acc[ai][bj][m][n], 0, 0, 0); __builtin_amdgcn_s_setprio(0); } while (0)
; #define PG8_WAIT_V(n) asm volatile("s_waitcnt vmcnt(" #n ")" ::: "memory")
; template <class Epi, class Sched, bool ALIGN_EPI = false, bool SP2 = false>
; __device__ __forceinline__ void gemm_phase(PG8_LAS unsigned char* lds, const Gemm g, const Sched S, const Epi E) {
;     ...
;             PG8_LDB(B0, 0, 0); PG8_LDB(B1, 0, 1); PG8_SCHED; PG8_LDA(At, 0, 0); PG8_STAGE(PG8_SA(1, 1), a1 + hstep, voffA);
;             PG8_WAIT_V(8); PG8_WAIT_L(0); PG8_BAR; PG8_MMA(0, 0, At, B0); PG8_MMA(0, 1, At, B1); PG8_BAR; PG8_SCHED;
;             PG8_LDA(At, 0, 1); PG8_STAGE(PG8_SB(0, 0), b2, voffB); PG8_STAGE(PG8_SB(0, 1), b2 + hstep, voffB); PG8_STAGE(PG8_SA(0, 0), a2, voffA);
;             PG8_WAIT_V(8); PG8_WAIT_L(0); PG8_BAR; PG8_MMA(1, 0, At, B0); PG8_MMA(1, 1, At, B1); PG8_BAR; PG8_SCHED;
;             PG8_LDB(B0, 1, 0); PG8_LDB(B1, 1, 1); PG8_SCHED; PG8_LDA(At, 1, 0); PG8_STAGE(PG8_SA(0, 1), a2 + hstep, voffA);
;             PG8_WAIT_V(8); PG8_WAIT_L(0); PG8_BAR; PG8_MMA(0, 0, At, B0); PG8_MMA(0, 1, At, B1); PG8_BAR; PG8_SCHED;
;             PG8_LDA(At, 1, 1); PG8_STAGE(PG8_SB(1, 0), b3, voffB); PG8_STAGE(PG8_SB(1, 1), b3 + hstep, voffB); PG8_STAGE(PG8_SA(1, 0), a3, voffA);
;             PG8_WAIT_V(8); PG8_WAIT_L(0); PG8_BAR; PG8_MMA(1, 0, At, B0); PG8_MMA(1, 1, At, B1); PG8_BAR; PG8_SCHED;
	s_setprio 1
	s_waitcnt lgkmcnt(0)
	v_mfma_f32_16x16x32_bf16 v[60:63], v[128:131], v[174:177], v[60:63]
	v_mfma_f32_16x16x32_bf16 v[56:59], v[150:153], v[174:177], v[56:59]
	v_mfma_f32_16x16x32_bf16 v[44:47], v[128:131], v[182:185], v[44:47]
	v_mfma_f32_16x16x32_bf16 v[40:43], v[150:153], v[182:185], v[40:43]
	v_mfma_f32_16x16x32_bf16 v[28:31], v[128:131], v[204:207], v[28:31]
	v_mfma_f32_16x16x32_bf16 v[24:27], v[150:153], v[204:207], v[24:27]
	v_mfma_f32_16x16x32_bf16 v[12:15], v[128:131], v[212:215], v[12:15]
	v_mfma_f32_16x16x32_bf16 v[8:11], v[150:153], v[212:215], v[8:11]
	v_mfma_f32_16x16x32_bf16 v[60:63], v[132:135], v[178:181], v[60:63]
	v_mfma_f32_16x16x32_bf16 v[56:59], v[154:157], v[178:181], v[56:59]
	v_mfma_f32_16x16x32_bf16 v[44:47], v[132:135], v[200:203], v[44:47]
	v_mfma_f32_16x16x32_bf16 v[40:43], v[154:157], v[200:203], v[40:43]
	v_mfma_f32_16x16x32_bf16 v[28:31], v[132:135], v[208:211], v[28:31]
	v_mfma_f32_16x16x32_bf16 v[24:27], v[154:157], v[208:211], v[24:27]
	v_mfma_f32_16x16x32_bf16 v[12:15], v[132:135], v[216:219], v[12:15]
	v_mfma_f32_16x16x32_bf16 v[8:11], v[154:157], v[216:219], v[8:11]
	s_setprio 0
	s_setprio 1
	v_mfma_f32_16x16x32_bf16 v[52:55], v[158:161], v[174:177], v[52:55]
	v_mfma_f32_16x16x32_bf16 v[48:51], v[166:169], v[174:177], v[48:51]
	v_mfma_f32_16x16x32_bf16 v[36:39], v[158:161], v[182:185], v[36:39]
	v_mfma_f32_16x16x32_bf16 v[32:35], v[166:169], v[182:185], v[32:35]
	v_mfma_f32_16x16x32_bf16 v[20:23], v[158:161], v[204:207], v[20:23]
	v_mfma_f32_16x16x32_bf16 v[16:19], v[166:169], v[204:207], v[16:19]
	v_mfma_f32_16x16x32_bf16 v[4:7], v[158:161], v[212:215], v[4:7]
	v_mfma_f32_16x16x32_bf16 v[0:3], v[166:169], v[212:215], v[0:3]
	v_mfma_f32_16x16x32_bf16 v[52:55], v[162:165], v[178:181], v[52:55]
	v_mfma_f32_16x16x32_bf16 v[48:51], v[170:173], v[178:181], v[48:51]
	v_mfma_f32_16x16x32_bf16 v[36:39], v[162:165], v[200:203], v[36:39]
	v_mfma_f32_16x16x32_bf16 v[32:35], v[170:173], v[200:203], v[32:35]
	v_mfma_f32_16x16x32_bf16 v[20:23], v[162:165], v[208:211], v[20:23]
	v_mfma_f32_16x16x32_bf16 v[16:19], v[170:173], v[208:211], v[16:19]
	v_mfma_f32_16x16x32_bf16 v[4:7], v[162:165], v[216:219], v[4:7]
	s_barrier
	v_mfma_f32_16x16x32_bf16 v[0:3], v[170:173], v[216:219], v[0:3]
	s_setprio 0
	s_add_i32 s85, 0, 0x18000
	v_add_u32_e32 v140, s85, v191
	s_add_i32 s87, 0, 0x1c000
	ds_read_b128 v[128:131], v140
	ds_read_b128 v[132:135], v140 offset:1024
	ds_read_b128 v[150:153], v140 offset:2048
	ds_read_b128 v[154:157], v140 offset:3072
	v_add_u32_e32 v140, s87, v191
	ds_read_b128 v[158:161], v140
	ds_read_b128 v[162:165], v140 offset:1024
	ds_read_b128 v[166:169], v140 offset:2048
	ds_read_b128 v[170:173], v140 offset:3072
	s_add_u32 s92, s92, 0x40000
	s_addc_u32 s93, s93, 0
	s_mov_b32 m0, s8
	v_lshl_add_u64 v[228:229], s[92:93], 0, v[136:137]
	ds_read_b128 v[174:177], v195 offset:32768
	ds_read_b128 v[178:181], v195 offset:33792
	ds_read_b128 v[182:185], v195 offset:34816
	ds_read_b128 v[200:203], v195 offset:35840
	ds_read_b128 v[204:207], v195 offset:36864
	ds_read_b128 v[208:211], v195 offset:37888
	ds_read_b128 v[212:215], v195 offset:38912
	ds_read_b128 v[216:219], v195 offset:39936
	global_load_lds_dwordx4 v[228:229], off
	v_lshl_add_u64 v[228:229], s[92:93], 0, v[138:139]
	s_mov_b32 m0, s9
	s_nop 0
	global_load_lds_dwordx4 v[228:229], off
	s_waitcnt vmcnt(8)
	s_waitcnt lgkmcnt(0)
	s_barrier
	s_setprio 1
	s_waitcnt lgkmcnt(0)
	v_mfma_f32_16x16x32_bf16 v[124:127], v[128:131], v[174:177], v[124:127]
	v_mfma_f32_16x16x32_bf16 v[120:123], v[150:153], v[174:177], v[120:123]
	v_mfma_f32_16x16x32_bf16 v[108:111], v[128:131], v[182:185], v[108:111]
	v_mfma_f32_16x16x32_bf16 v[104:107], v[150:153], v[182:185], v[104:107]
	v_mfma_f32_16x16x32_bf16 v[92:95], v[128:131], v[204:207], v[92:95]
	v_mfma_f32_16x16x32_bf16 v[88:91], v[150:153], v[204:207], v[88:91]
	v_mfma_f32_16x16x32_bf16 v[76:79], v[128:131], v[212:215], v[76:79]
	v_mfma_f32_16x16x32_bf16 v[72:75], v[150:153], v[212:215], v[72:75]
	v_mfma_f32_16x16x32_bf16 v[124:127], v[132:135], v[178:181], v[124:127]
	v_mfma_f32_16x16x32_bf16 v[120:123], v[154:157], v[178:181], v[120:123]
	v_mfma_f32_16x16x32_bf16 v[108:111], v[132:135], v[200:203], v[108:111]
	v_mfma_f32_16x16x32_bf16 v[104:107], v[154:157], v[200:203], v[104:107]
	v_mfma_f32_16x16x32_bf16 v[92:95], v[132:135], v[208:211], v[92:95]
	v_mfma_f32_16x16x32_bf16 v[88:91], v[154:157], v[208:211], v[88:91]
	v_mfma_f32_16x16x32_bf16 v[76:79], v[132:135], v[216:219], v[76:79]
	v_mfma_f32_16x16x32_bf16 v[72:75], v[154:157], v[216:219], v[72:75]
	s_setprio 0
	s_setprio 1
	v_mfma_f32_16x16x32_bf16 v[116:119], v[158:161], v[174:177], v[116:119]
	v_mfma_f32_16x16x32_bf16 v[112:115], v[166:169], v[174:177], v[112:115]
	v_mfma_f32_16x16x32_bf16 v[100:103], v[158:161], v[182:185], v[100:103]
	v_mfma_f32_16x16x32_bf16 v[96:99], v[166:169], v[182:185], v[96:99]
	v_mfma_f32_16x16x32_bf16 v[84:87], v[158:161], v[204:207], v[84:87]
	v_mfma_f32_16x16x32_bf16 v[80:83], v[166:169], v[204:207], v[80:83]
	v_mfma_f32_16x16x32_bf16 v[68:71], v[158:161], v[212:215], v[68:71]
	v_mfma_f32_16x16x32_bf16 v[64:67], v[166:169], v[212:215], v[64:67]
	v_mfma_f32_16x16x32_bf16 v[116:119], v[162:165], v[178:181], v[116:119]
	v_mfma_f32_16x16x32_bf16 v[112:115], v[170:173], v[178:181], v[112:115]
	v_mfma_f32_16x16x32_bf16 v[100:103], v[162:165], v[200:203], v[100:103]
	v_mfma_f32_16x16x32_bf16 v[96:99], v[170:173], v[200:203], v[96:99]
	v_mfma_f32_16x16x32_bf16 v[84:87], v[162:165], v[208:211], v[84:87]
	v_mfma_f32_16x16x32_bf16 v[80:83], v[170:173], v[208:211], v[80:83]
	v_mfma_f32_16x16x32_bf16 v[68:71], v[162:165], v[216:219], v[68:71]
	s_barrier
; #define PG8_STAGE(bufoff, gbase, voff) do { _Pragma("unroll") for (int _i = 0; _i < 2; ++_i) \
;         __builtin_amdgcn_global_load_lds((const unsigned*)((const char*)(gbase) + (voff)[_i]), (PG8_LAS unsigned*)(lds + (bufoff) + ldsw + _i * 8192), 16, 0, 0); } while (0)
; #define PG8_LDA(dst, b, h) do { _Pragma("unroll") for (int m = 0; m < 4; ++m) _Pragma("unroll") for (int k = 0; k < 2; ++k) dst[m][k] = *(const PG8_LAS bf16x8*)(lds + PG8_SA(b, h) + aoff + m * 2048 + k * 1024); } while (0)
; #define PG8_LDB(dst, b, h) do { _Pragma("unroll") for (int n = 0; n < 2; ++n) _Pragma("unroll") for (int k = 0; k < 2; ++k) dst[n][k] = *(const PG8_LAS bf16x8*)(lds + PG8_SB(b, h) + boff + n * 2048 + k * 1024); } while (0)
; #define PG8_MMA(ai, bj, At, Bt) do { __builtin_amdgcn_s_setprio(1); _Pragma("unroll") for (int m = 0; m < 4; ++m) _Pragma("unroll") for (int n = 0; n < 2; ++n) _Pragma("unroll") for (int k = 0; k < 2; ++k) \
;         acc[ai][bj][m][n] = __builtin_amdgcn_mfma_f32_16x16x32_bf16(Bt[n][k], At[m][k], acc[ai][bj][m][n], 0, 0, 0); __builtin_amdgcn_s_setprio(0); } while (0)
; #define PG8_WAIT_V(n) asm volatile("s_waitcnt vmcnt(" #n ")" ::: "memory")
; template <class Epi, class Sched, bool ALIGN_EPI = false, bool SP2 = false>
; __device__ __forceinline__ void gemm_phase(PG8_LAS unsigned char* lds, const Gemm g, const Sched S, const Epi E) {
;     ...
;             PG8_LDB(B0, 0, 0); PG8_LDB(B1, 0, 1); PG8_SCHED; PG8_LDA(At, 0, 0); PG8_STAGE(PG8_SA(1, 1), a1 + hstep, voffA);
;             PG8_WAIT_V(8); PG8_WAIT_L(0); PG8_BAR; PG8_MMA(0, 0, At, B0); PG8_MMA(0, 1, At, B1); PG8_BAR; PG8_SCHED;
;             PG8_LDA(At, 0, 1); PG8_STAGE(PG8_SB(0, 0), b2, voffB); PG8_STAGE(PG8_SB(0, 1), b2 + hstep, voffB); PG8_STAGE(PG8_SA(0, 0), a2, voffA);
;             PG8_WAIT_V(8); PG8_WAIT_L(0); PG8_BAR; PG8_MMA(1, 0, At, B0); PG8_MMA(1, 1, At, B1); PG8_BAR; PG8_SCHED;
;             PG8_LDB(B0, 1, 0); PG8_LDB(B1, 1, 1); PG8_SCHED; PG8_LDA(At, 1, 0); PG8_STAGE(PG8_SA(0, 1), a2 + hstep, voffA);
;             PG8_WAIT_V(8); PG8_WAIT_L(0); PG8_BAR; PG8_MMA(0, 0, At, B0); PG8_MMA(0, 1, At, B1); PG8_BAR; PG8_SCHED;
;             PG8_LDA(At, 1, 1); PG8_STAGE(PG8_SB(1, 0), b3, voffB); PG8_STAGE(PG8_SB(1, 1), b3 + hstep, voffB); PG8_STAGE(PG8_SA(1, 0), a3, voffA);
;             PG8_WAIT_V(8); PG8_WAIT_L(0); PG8_BAR; PG8_MMA(1, 0, At, B0); PG8_MMA(1, 1, At, B1); PG8_BAR; PG8_SCHED;
	v_mfma_f32_16x16x32_bf16 v[64:67], v[170:173], v[216:219], v[64:67]
	s_setprio 0
	s_add_i32 s85, s85, s18
	v_lshl_add_u64 v[220:221], v[220:221], 0, s[52:53]
	s_mov_b32 m0, s85
	ds_read_b128 v[174:177], v195 offset:49152
	ds_read_b128 v[178:181], v195 offset:50176
	ds_read_b128 v[182:185], v195 offset:51200
	ds_read_b128 v[200:203], v195 offset:52224
	ds_read_b128 v[204:207], v195 offset:53248
	ds_read_b128 v[208:211], v195 offset:54272
	ds_read_b128 v[212:215], v195 offset:55296
	ds_read_b128 v[216:219], v195 offset:56320
	global_load_lds_dwordx4 v[220:221], off
	s_add_i32 m0, s85, 0x2000
	s_add_u32 s10, s10, 0x40080
	v_lshl_add_u64 v[220:221], v[222:223], 0, s[52:53]
	s_addc_u32 s11, s11, 0
	s_add_i32 s85, s87, s18
	global_load_lds_dwordx4 v[220:221], off
	v_lshl_add_u64 v[220:221], s[10:11], 0, v[136:137]
	s_mov_b32 m0, s85
	s_nop 0
	global_load_lds_dwordx4 v[220:221], off
	v_lshl_add_u64 v[220:221], s[10:11], 0, v[138:139]
	s_add_i32 m0, s85, 0x2000
	s_nop 0
	global_load_lds_dwordx4 v[220:221], off
	v_lshl_add_u64 v[220:221], v[224:225], 0, s[52:53]
	s_mov_b32 m0, s67
	s_nop 0
	global_load_lds_dwordx4 v[220:221], off
	v_lshl_add_u64 v[220:221], v[226:227], 0, s[52:53]
	s_mov_b32 m0, s54
	s_nop 0
	global_load_lds_dwordx4 v[220:221], off
	s_waitcnt vmcnt(8)
	s_waitcnt lgkmcnt(0)
	s_barrier
	s_setprio 1
	s_waitcnt lgkmcnt(0)
	v_mfma_f32_16x16x32_bf16 v[60:63], v[128:131], v[174:177], v[60:63]
	v_mfma_f32_16x16x32_bf16 v[56:59], v[150:153], v[174:177], v[56:59]
	v_mfma_f32_16x16x32_bf16 v[44:47], v[128:131], v[182:185], v[44:47]
	v_mfma_f32_16x16x32_bf16 v[40:43], v[150:153], v[182:185], v[40:43]
	v_mfma_f32_16x16x32_bf16 v[28:31], v[128:131], v[204:207], v[28:31]
	v_mfma_f32_16x16x32_bf16 v[24:27], v[150:153], v[204:207], v[24:27]
	v_mfma_f32_16x16x32_bf16 v[12:15], v[128:131], v[212:215], v[12:15]
	v_mfma_f32_16x16x32_bf16 v[8:11], v[150:153], v[212:215], v[8:11]
	v_mfma_f32_16x16x32_bf16 v[60:63], v[132:135], v[178:181], v[60:63]
	v_mfma_f32_16x16x32_bf16 v[56:59], v[154:157], v[178:181], v[56:59]
	v_mfma_f32_16x16x32_bf16 v[44:47], v[132:135], v[200:203], v[44:47]
	v_mfma_f32_16x16x32_bf16 v[40:43], v[154:157], v[200:203], v[40:43]
	v_mfma_f32_16x16x32_bf16 v[28:31], v[132:135], v[208:211], v[28:31]
	v_mfma_f32_16x16x32_bf16 v[24:27], v[154:157], v[208:211], v[24:27]
	v_mfma_f32_16x16x32_bf16 v[12:15], v[132:135], v[216:219], v[12:15]
	v_mfma_f32_16x16x32_bf16 v[8:11], v[154:157], v[216:219], v[8:11]
	s_setprio 0
	s_setprio 1
	v_mfma_f32_16x16x32_bf16 v[52:55], v[158:161], v[174:177], v[52:55]
	v_mfma_f32_16x16x32_bf16 v[48:51], v[166:169], v[174:177], v[48:51]
	v_mfma_f32_16x16x32_bf16 v[36:39], v[158:161], v[182:185], v[36:39]
	v_mfma_f32_16x16x32_bf16 v[32:35], v[166:169], v[182:185], v[32:35]
	v_mfma_f32_16x16x32_bf16 v[20:23], v[158:161], v[204:207], v[20:23]
	v_mfma_f32_16x16x32_bf16 v[16:19], v[166:169], v[204:207], v[16:19]
	v_mfma_f32_16x16x32_bf16 v[4:7], v[158:161], v[212:215], v[4:7]
	v_mfma_f32_16x16x32_bf16 v[0:3], v[166:169], v[212:215], v[0:3]
	v_mfma_f32_16x16x32_bf16 v[52:55], v[162:165], v[178:181], v[52:55]
	v_mfma_f32_16x16x32_bf16 v[48:51], v[170:173], v[178:181], v[48:51]
	v_mfma_f32_16x16x32_bf16 v[36:39], v[162:165], v[200:203], v[36:39]
	v_mfma_f32_16x16x32_bf16 v[32:35], v[170:173], v[200:203], v[32:35]
	v_mfma_f32_16x16x32_bf16 v[20:23], v[162:165], v[208:211], v[20:23]
	v_mfma_f32_16x16x32_bf16 v[16:19], v[170:173], v[208:211], v[16:19]
	v_mfma_f32_16x16x32_bf16 v[4:7], v[162:165], v[216:219], v[4:7]
	s_barrier
	v_mfma_f32_16x16x32_bf16 v[0:3], v[170:173], v[216:219], v[0:3]
	s_setprio 0
	s_add_i32 s61, s61, 2
	s_add_u32 s6, s6, 0x100
	s_addc_u32 s7, s7, 0
	s_add_u32 s59, s59, 0x100
	s_addc_u32 s60, s60, 0
	s_cmp_gt_u32 s61, 13
	s_cbranch_scc0 .LBB0_484
	s_and_b64 vcc, exec, s[62:63]
	s_cbranch_vccz .LBB0_487
	s_barrier

; #define PG8_STAGE(bufoff, gbase, voff) do { _Pragma("unroll") for (int _i = 0; _i < 2; ++_i) \
;         __builtin_amdgcn_global_load_lds((const unsigned*)((const char*)(gbase) + (voff)[_i]), (PG8_LAS unsigned*)(lds + (bufoff) + ldsw + _i * 8192), 16, 0, 0); } while (0)
; #define PG8_LDA(dst, b, h) do { _Pragma("unroll") for (int m = 0; m < 4; ++m) _Pragma("unroll") for (int k = 0; k < 2; ++k) dst[m][k] = *(const PG8_LAS bf16x8*)(lds + PG8_SA(b, h) + aoff + m * 2048 + k * 1024); } while (0)
; #define PG8_LDB(dst, b, h) do { _Pragma("unroll") for (int n = 0; n < 2; ++n) _Pragma("unroll") for (int k = 0; k < 2; ++k) dst[n][k] = *(const PG8_LAS bf16x8*)(lds + PG8_SB(b, h) + boff + n * 2048 + k * 1024); } while (0)
; #define PG8_MMA(ai, bj, At, Bt) do { __builtin_amdgcn_s_setprio(1); _Pragma("unroll") for (int m = 0; m < 4; ++m) _Pragma("unroll") for (int n = 0; n < 2; ++n) _Pragma("unroll") for (int k = 0; k < 2; ++k) \
;         acc[ai][bj][m][n] = __builtin_amdgcn_mfma_f32_16x16x32_bf16(Bt[n][k], At[m][k], acc[ai][bj][m][n], 0, 0, 0); __builtin_amdgcn_s_setprio(0); } while (0)
; #define PG8_WAIT_V(n) asm volatile("s_waitcnt vmcnt(" #n ")" ::: "memory")
; template <class Epi, class Sched, bool ALIGN_EPI = false, bool SP2 = false>
; __device__ __forceinline__ void gemm_phase(PG8_LAS unsigned char* lds, const Gemm g, const Sched S, const Epi E) {
;     ...
;             PG8_LDB(B0, 0, 0); PG8_LDB(B1, 0, 1); PG8_SCHED; PG8_LDA(At, 0, 0); PG8_STAGE(PG8_SA(1, 1), a1 + hstep, voffA);
;             PG8_WAIT_V(8); PG8_WAIT_L(0); PG8_BAR; PG8_MMA(0, 0, At, B0); PG8_MMA(0, 1, At, B1); PG8_BAR; PG8_SCHED;
;             PG8_LDA(At, 0, 1); PG8_STAGE(PG8_SB(0, 0), b2, voffB); PG8_STAGE(PG8_SB(0, 1), b2 + hstep, voffB); PG8_STAGE(PG8_SA(0, 0), a2, voffA);
;             PG8_WAIT_V(8); PG8_WAIT_L(0); PG8_BAR; PG8_MMA(1, 0, At, B0); PG8_MMA(1, 1, At, B1); PG8_BAR; PG8_SCHED;
;             PG8_LDB(B0, 1, 0); PG8_LDB(B1, 1, 1); PG8_SCHED; PG8_LDA(At, 1, 0); PG8_STAGE(PG8_SA(0, 1), a2 + hstep, voffA);
;             PG8_WAIT_V(8); PG8_WAIT_L(0); PG8_BAR; PG8_MMA(0, 0, At, B0); PG8_MMA(0, 1, At, B1); PG8_BAR; PG8_SCHED;
;             PG8_LDA(At, 1, 1); PG8_STAGE(PG8_SB(1, 0), b3, voffB); PG8_STAGE(PG8_SB(1, 1), b3 + hstep, voffB); PG8_STAGE(PG8_SA(1, 0), a3, voffA);
;             PG8_WAIT_V(8); PG8_WAIT_L(0); PG8_BAR; PG8_MMA(1, 0, At, B0); PG8_MMA(1, 1, At, B1); PG8_BAR; PG8_SCHED;
.LBB0_616:
	ds_read_b128 v[0:3], v150
	ds_read_b128 v[4:7], v150 offset:1024
	ds_read_b128 v[8:11], v150 offset:2048
	ds_read_b128 v[12:15], v150 offset:3072
	ds_read_b128 v[16:19], v151
	ds_read_b128 v[20:23], v151 offset:1024
	ds_read_b128 v[24:27], v151 offset:2048
	ds_read_b128 v[28:31], v151 offset:3072
	s_ashr_i32 s79, s78, 31
	s_lshl_b64 s[80:81], s[78:79], 17
	s_add_u32 s80, s37, s80
	s_addc_u32 s81, s34, s81
	s_and_b64 s[82:83], s[4:5], exec
	s_cselect_b32 s89, s81, s7
	s_cselect_b32 s88, s80, s6
	s_ashr_i32 s77, s76, 31
	s_lshl_b64 s[82:83], s[76:77], 17
	s_add_u32 s82, s12, s82
	s_addc_u32 s83, s13, s83
	s_and_b64 s[84:85], s[4:5], exec
	s_cselect_b32 s85, s83, s87
	s_cselect_b32 s84, s82, s86
	s_add_u32 vcc_lo, s6, 0x10080
	s_addc_u32 vcc_hi, s7, 0
	s_mov_b32 m0, s96
	v_lshl_add_u64 v[64:65], vcc, 0, v[128:129]
	ds_read_b128 v[32:35], v152
	ds_read_b128 v[36:39], v152 offset:1024
	ds_read_b128 v[40:43], v152 offset:2048
	ds_read_b128 v[44:47], v152 offset:3072
	ds_read_b128 v[48:51], v152 offset:4096
	ds_read_b128 v[52:55], v152 offset:5120
	ds_read_b128 v[56:59], v152 offset:6144
	ds_read_b128 v[60:63], v152 offset:7168
	global_load_lds_dwordx4 v[64:65], off
	v_lshl_add_u64 v[64:65], vcc, 0, v[130:131]
	s_mov_b32 m0, s97
	s_nop 0
	global_load_lds_dwordx4 v[64:65], off
	s_waitcnt vmcnt(8)
	s_waitcnt lgkmcnt(0)
	s_barrier
	s_setprio 1
	s_waitcnt lgkmcnt(0)
	v_mfma_f32_16x16x32_bf16 v[64:67], v[0:3], v[32:35], 0
	v_mfma_f32_16x16x32_bf16 v[68:71], v[8:11], v[32:35], 0
	v_mfma_f32_16x16x32_bf16 v[72:75], v[0:3], v[40:43], 0
	v_mfma_f32_16x16x32_bf16 v[76:79], v[8:11], v[40:43], 0
	v_mfma_f32_16x16x32_bf16 v[80:83], v[0:3], v[48:51], 0
	v_mfma_f32_16x16x32_bf16 v[84:87], v[8:11], v[48:51], 0
	v_mfma_f32_16x16x32_bf16 v[88:91], v[0:3], v[56:59], 0
	v_mfma_f32_16x16x32_bf16 v[92:95], v[8:11], v[56:59], 0
	v_mfma_f32_16x16x32_bf16 v[64:67], v[4:7], v[36:39], v[64:67]
	v_mfma_f32_16x16x32_bf16 v[68:71], v[12:15], v[36:39], v[68:71]
	v_mfma_f32_16x16x32_bf16 v[72:75], v[4:7], v[44:47], v[72:75]
	v_mfma_f32_16x16x32_bf16 v[76:79], v[12:15], v[44:47], v[76:79]
	v_mfma_f32_16x16x32_bf16 v[80:83], v[4:7], v[52:55], v[80:83]
	v_mfma_f32_16x16x32_bf16 v[84:87], v[12:15], v[52:55], v[84:87]
	v_mfma_f32_16x16x32_bf16 v[88:91], v[4:7], v[60:63], v[88:91]
	v_mfma_f32_16x16x32_bf16 v[92:95], v[12:15], v[60:63], v[92:95]
	s_setprio 0
	s_setprio 1
	v_mfma_f32_16x16x32_bf16 v[96:99], v[16:19], v[32:35], 0
	v_mfma_f32_16x16x32_bf16 v[32:35], v[24:27], v[32:35], 0
	v_mfma_f32_16x16x32_bf16 v[96:99], v[20:23], v[36:39], v[96:99]
	v_mfma_f32_16x16x32_bf16 v[32:35], v[28:31], v[36:39], v[32:35]
	v_mfma_f32_16x16x32_bf16 v[36:39], v[16:19], v[40:43], 0
	v_mfma_f32_16x16x32_bf16 v[40:43], v[24:27], v[40:43], 0
	v_mfma_f32_16x16x32_bf16 v[36:39], v[20:23], v[44:47], v[36:39]
	v_mfma_f32_16x16x32_bf16 v[40:43], v[28:31], v[44:47], v[40:43]
	v_mfma_f32_16x16x32_bf16 v[44:47], v[16:19], v[48:51], 0
	v_mfma_f32_16x16x32_bf16 v[48:51], v[24:27], v[48:51], 0
	v_mfma_f32_16x16x32_bf16 v[44:47], v[20:23], v[52:55], v[44:47]
	v_mfma_f32_16x16x32_bf16 v[48:51], v[28:31], v[52:55], v[48:51]
	v_mfma_f32_16x16x32_bf16 v[52:55], v[16:19], v[56:59], 0
	v_mfma_f32_16x16x32_bf16 v[56:59], v[24:27], v[56:59], 0
	v_mfma_f32_16x16x32_bf16 v[52:55], v[20:23], v[60:63], v[52:55]
	s_barrier
	v_mfma_f32_16x16x32_bf16 v[56:59], v[28:31], v[60:63], v[56:59]
	s_setprio 0
	v_lshl_add_u64 v[142:143], s[86:87], 0, v[128:129]
	s_mov_b32 m0, s61
	v_lshl_add_u64 v[138:139], v[142:143], 0, s[66:67]
	v_lshl_add_u64 v[146:147], s[86:87], 0, v[130:131]
	s_add_u32 vcc_lo, s86, 0x10100
	ds_read_b128 v[60:63], v152 offset:16384
	ds_read_b128 v[100:103], v152 offset:17408
	ds_read_b128 v[104:107], v152 offset:18432
	ds_read_b128 v[108:111], v152 offset:19456
	ds_read_b128 v[112:115], v152 offset:20480
	ds_read_b128 v[116:119], v152 offset:21504
	ds_read_b128 v[120:123], v152 offset:22528
	ds_read_b128 v[124:127], v152 offset:23552
	global_load_lds_dwordx4 v[138:139], off
	v_lshl_add_u64 v[138:139], v[146:147], 0, s[66:67]
	s_mov_b32 m0, s36
	s_addc_u32 vcc_hi, s87, 0
	s_add_i32 s1, s95, s8
	global_load_lds_dwordx4 v[138:139], off
	v_lshl_add_u64 v[138:139], vcc, 0, v[128:129]
	s_mov_b32 m0, s1
	s_add_i32 s11, s1, 0x2000
	global_load_lds_dwordx4 v[138:139], off
	v_lshl_add_u64 v[138:139], vcc, 0, v[130:131]
	s_mov_b32 m0, s11
	v_lshl_add_u64 v[184:185], s[6:7], 0, v[128:129]
	global_load_lds_dwordx4 v[138:139], off
	v_lshl_add_u64 v[138:139], v[184:185], 0, s[66:67]
	s_mov_b32 m0, s9
	v_lshl_add_u64 v[222:223], s[6:7], 0, v[130:131]
	global_load_lds_dwordx4 v[138:139], off
	v_lshl_add_u64 v[138:139], v[222:223], 0, s[66:67]
	s_mov_b32 m0, s18
	s_nop 0
	global_load_lds_dwordx4 v[138:139], off
	s_waitcnt vmcnt(8)
	s_waitcnt lgkmcnt(0)
	s_barrier
; #define PG8_STAGE(bufoff, gbase, voff) do { _Pragma("unroll") for (int _i = 0; _i < 2; ++_i) \
;         __builtin_amdgcn_global_load_lds((const unsigned*)((const char*)(gbase) + (voff)[_i]), (PG8_LAS unsigned*)(lds + (bufoff) + ldsw + _i * 8192), 16, 0, 0); } while (0)
; #define PG8_LDA(dst, b, h) do { _Pragma("unroll") for (int m = 0; m < 4; ++m) _Pragma("unroll") for (int k = 0; k < 2; ++k) dst[m][k] = *(const PG8_LAS bf16x8*)(lds + PG8_SA(b, h) + aoff + m * 2048 + k * 1024); } while (0)
; #define PG8_LDB(dst, b, h) do { _Pragma("unroll") for (int n = 0; n < 2; ++n) _Pragma("unroll") for (int k = 0; k < 2; ++k) dst[n][k] = *(const PG8_LAS bf16x8*)(lds + PG8_SB(b, h) + boff + n * 2048 + k * 1024); } while (0)
; #define PG8_MMA(ai, bj, At, Bt) do { __builtin_amdgcn_s_setprio(1); _Pragma("unroll") for (int m = 0; m < 4; ++m) _Pragma("unroll") for (int n = 0; n < 2; ++n) _Pragma("unroll") for (int k = 0; k < 2; ++k) \
;         acc[ai][bj][m][n] = __builtin_amdgcn_mfma_f32_16x16x32_bf16(Bt[n][k], At[m][k], acc[ai][bj][m][n], 0, 0, 0); __builtin_amdgcn_s_setprio(0); } while (0)
; #define PG8_WAIT_V(n) asm volatile("s_waitcnt vmcnt(" #n ")" ::: "memory")
; template <class Epi, class Sched, bool ALIGN_EPI = false, bool SP2 = false>
; __device__ __forceinline__ void gemm_phase(PG8_LAS unsigned char* lds, const Gemm g, const Sched S, const Epi E) {
;     ...
;             PG8_LDB(B0, 0, 0); PG8_LDB(B1, 0, 1); PG8_SCHED; PG8_LDA(At, 0, 0); PG8_STAGE(PG8_SA(1, 1), a1 + hstep, voffA);
;             PG8_WAIT_V(8); PG8_WAIT_L(0); PG8_BAR; PG8_MMA(0, 0, At, B0); PG8_MMA(0, 1, At, B1); PG8_BAR; PG8_SCHED;
;             PG8_LDA(At, 0, 1); PG8_STAGE(PG8_SB(0, 0), b2, voffB); PG8_STAGE(PG8_SB(0, 1), b2 + hstep, voffB); PG8_STAGE(PG8_SA(0, 0), a2, voffA);
;             PG8_WAIT_V(8); PG8_WAIT_L(0); PG8_BAR; PG8_MMA(1, 0, At, B0); PG8_MMA(1, 1, At, B1); PG8_BAR; PG8_SCHED;
;             PG8_LDB(B0, 1, 0); PG8_LDB(B1, 1, 1); PG8_SCHED; PG8_LDA(At, 1, 0); PG8_STAGE(PG8_SA(0, 1), a2 + hstep, voffA);
;             PG8_WAIT_V(8); PG8_WAIT_L(0); PG8_BAR; PG8_MMA(0, 0, At, B0); PG8_MMA(0, 1, At, B1); PG8_BAR; PG8_SCHED;
;             PG8_LDA(At, 1, 1); PG8_STAGE(PG8_SB(1, 0), b3, voffB); PG8_STAGE(PG8_SB(1, 1), b3 + hstep, voffB); PG8_STAGE(PG8_SA(1, 0), a3, voffA);
;             PG8_WAIT_V(8); PG8_WAIT_L(0); PG8_BAR; PG8_MMA(1, 0, At, B0); PG8_MMA(1, 1, At, B1); PG8_BAR; PG8_SCHED;
	s_setprio 1
	s_waitcnt lgkmcnt(0)
	v_mfma_f32_16x16x32_bf16 v[138:141], v[0:3], v[60:63], 0
	v_mfma_f32_16x16x32_bf16 v[160:163], v[0:3], v[104:107], 0
	v_mfma_f32_16x16x32_bf16 v[168:171], v[0:3], v[112:115], 0
	v_mfma_f32_16x16x32_bf16 v[0:3], v[0:3], v[120:123], 0
	v_mfma_f32_16x16x32_bf16 v[138:141], v[4:7], v[100:103], v[138:141]
	v_mfma_f32_16x16x32_bf16 v[160:163], v[4:7], v[108:111], v[160:163]
	v_mfma_f32_16x16x32_bf16 v[168:171], v[4:7], v[116:119], v[168:171]
	v_mfma_f32_16x16x32_bf16 v[0:3], v[4:7], v[124:127], v[0:3]
	v_mfma_f32_16x16x32_bf16 v[4:7], v[8:11], v[120:123], 0
	v_mfma_f32_16x16x32_bf16 v[156:159], v[8:11], v[60:63], 0
	v_mfma_f32_16x16x32_bf16 v[164:167], v[8:11], v[104:107], 0
	v_mfma_f32_16x16x32_bf16 v[172:175], v[8:11], v[112:115], 0
	v_mfma_f32_16x16x32_bf16 v[4:7], v[12:15], v[124:127], v[4:7]
	v_mfma_f32_16x16x32_bf16 v[156:159], v[12:15], v[100:103], v[156:159]
	v_mfma_f32_16x16x32_bf16 v[164:167], v[12:15], v[108:111], v[164:167]
	v_mfma_f32_16x16x32_bf16 v[172:175], v[12:15], v[116:119], v[172:175]
	s_setprio 0
	s_setprio 1
	v_mfma_f32_16x16x32_bf16 v[8:11], v[16:19], v[60:63], 0
	v_mfma_f32_16x16x32_bf16 v[12:15], v[24:27], v[60:63], 0
	v_mfma_f32_16x16x32_bf16 v[8:11], v[20:23], v[100:103], v[8:11]
	v_mfma_f32_16x16x32_bf16 v[12:15], v[28:31], v[100:103], v[12:15]
	v_mfma_f32_16x16x32_bf16 v[60:63], v[16:19], v[104:107], 0
	v_mfma_f32_16x16x32_bf16 v[100:103], v[24:27], v[104:107], 0
	v_mfma_f32_16x16x32_bf16 v[104:107], v[16:19], v[112:115], 0
	v_mfma_f32_16x16x32_bf16 v[16:19], v[16:19], v[120:123], 0
	v_mfma_f32_16x16x32_bf16 v[60:63], v[20:23], v[108:111], v[60:63]
	v_mfma_f32_16x16x32_bf16 v[100:103], v[28:31], v[108:111], v[100:103]
	v_mfma_f32_16x16x32_bf16 v[104:107], v[20:23], v[116:119], v[104:107]
	v_mfma_f32_16x16x32_bf16 v[108:111], v[24:27], v[112:115], 0
	v_mfma_f32_16x16x32_bf16 v[16:19], v[20:23], v[124:127], v[16:19]
	v_mfma_f32_16x16x32_bf16 v[20:23], v[24:27], v[120:123], 0
	v_mfma_f32_16x16x32_bf16 v[108:111], v[28:31], v[116:119], v[108:111]
	s_barrier
	v_mfma_f32_16x16x32_bf16 v[20:23], v[28:31], v[124:127], v[20:23]
	s_setprio 0
	s_add_i32 s46, 0, 0x18000
	s_add_i32 s77, 0, 0x1c000
	v_add_u32_e32 v132, s46, v149
	v_add_u32_e32 v144, s77, v149
	ds_read_b128 v[24:27], v132
	ds_read_b128 v[28:31], v132 offset:1024
	ds_read_b128 v[112:115], v132 offset:2048
	ds_read_b128 v[116:119], v132 offset:3072
	ds_read_b128 v[120:123], v144
	ds_read_b128 v[124:127], v144 offset:1024
	ds_read_b128 v[176:179], v144 offset:2048
	ds_read_b128 v[180:183], v144 offset:3072
	s_add_u32 vcc_lo, s6, 0x10100
	s_addc_u32 vcc_hi, s7, 0
	s_mov_b32 m0, s19
	v_lshl_add_u64 v[224:225], vcc, 0, v[128:129]
	ds_read_b128 v[190:193], v152 offset:32768
	ds_read_b128 v[194:197], v152 offset:33792
	ds_read_b128 v[198:201], v152 offset:34816
	ds_read_b128 v[202:205], v152 offset:35840
	ds_read_b128 v[206:209], v152 offset:36864
	ds_read_b128 v[210:213], v152 offset:37888
	ds_read_b128 v[214:217], v152 offset:38912
	ds_read_b128 v[218:221], v152 offset:39936
	global_load_lds_dwordx4 v[224:225], off
	v_lshl_add_u64 v[224:225], vcc, 0, v[130:131]
	s_mov_b32 m0, s54
	s_nop 0
	global_load_lds_dwordx4 v[224:225], off
	s_waitcnt vmcnt(8)
	s_waitcnt lgkmcnt(0)
	s_barrier
	s_setprio 1
	s_waitcnt lgkmcnt(0)
	v_mfma_f32_16x16x32_bf16 v[64:67], v[24:27], v[190:193], v[64:67]
	v_mfma_f32_16x16x32_bf16 v[68:71], v[112:115], v[190:193], v[68:71]
	v_mfma_f32_16x16x32_bf16 v[72:75], v[24:27], v[198:201], v[72:75]
	v_mfma_f32_16x16x32_bf16 v[76:79], v[112:115], v[198:201], v[76:79]
	v_mfma_f32_16x16x32_bf16 v[80:83], v[24:27], v[206:209], v[80:83]
	v_mfma_f32_16x16x32_bf16 v[84:87], v[112:115], v[206:209], v[84:87]
	v_mfma_f32_16x16x32_bf16 v[88:91], v[24:27], v[214:217], v[88:91]
	v_mfma_f32_16x16x32_bf16 v[92:95], v[112:115], v[214:217], v[92:95]
	v_mfma_f32_16x16x32_bf16 v[64:67], v[28:31], v[194:197], v[64:67]
	v_mfma_f32_16x16x32_bf16 v[68:71], v[116:119], v[194:197], v[68:71]
	v_mfma_f32_16x16x32_bf16 v[72:75], v[28:31], v[202:205], v[72:75]
	v_mfma_f32_16x16x32_bf16 v[76:79], v[116:119], v[202:205], v[76:79]
	v_mfma_f32_16x16x32_bf16 v[80:83], v[28:31], v[210:213], v[80:83]
	v_mfma_f32_16x16x32_bf16 v[84:87], v[116:119], v[210:213], v[84:87]
	v_mfma_f32_16x16x32_bf16 v[88:91], v[28:31], v[218:221], v[88:91]
	v_mfma_f32_16x16x32_bf16 v[92:95], v[116:119], v[218:221], v[92:95]
	s_setprio 0
	s_setprio 1
	v_mfma_f32_16x16x32_bf16 v[96:99], v[120:123], v[190:193], v[96:99]
	v_mfma_f32_16x16x32_bf16 v[32:35], v[176:179], v[190:193], v[32:35]
	v_mfma_f32_16x16x32_bf16 v[36:39], v[120:123], v[198:201], v[36:39]
	v_mfma_f32_16x16x32_bf16 v[40:43], v[176:179], v[198:201], v[40:43]
	v_mfma_f32_16x16x32_bf16 v[44:47], v[120:123], v[206:209], v[44:47]
	v_mfma_f32_16x16x32_bf16 v[48:51], v[176:179], v[206:209], v[48:51]
	v_mfma_f32_16x16x32_bf16 v[52:55], v[120:123], v[214:217], v[52:55]
	v_mfma_f32_16x16x32_bf16 v[56:59], v[176:179], v[214:217], v[56:59]
	v_mfma_f32_16x16x32_bf16 v[96:99], v[124:127], v[194:197], v[96:99]
	v_mfma_f32_16x16x32_bf16 v[32:35], v[180:183], v[194:197], v[32:35]
	v_mfma_f32_16x16x32_bf16 v[36:39], v[124:127], v[202:205], v[36:39]
	v_mfma_f32_16x16x32_bf16 v[40:43], v[180:183], v[202:205], v[40:43]
	v_mfma_f32_16x16x32_bf16 v[44:47], v[124:127], v[210:213], v[44:47]
	v_mfma_f32_16x16x32_bf16 v[48:51], v[180:183], v[210:213], v[48:51]
	v_mfma_f32_16x16x32_bf16 v[52:55], v[124:127], v[218:221], v[52:55]
	s_barrier
; #define PG8_STAGE(bufoff, gbase, voff) do { _Pragma("unroll") for (int _i = 0; _i < 2; ++_i) \
;         __builtin_amdgcn_global_load_lds((const unsigned*)((const char*)(gbase) + (voff)[_i]), (PG8_LAS unsigned*)(lds + (bufoff) + ldsw + _i * 8192), 16, 0, 0); } while (0)
; #define PG8_LDA(dst, b, h) do { _Pragma("unroll") for (int m = 0; m < 4; ++m) _Pragma("unroll") for (int k = 0; k < 2; ++k) dst[m][k] = *(const PG8_LAS bf16x8*)(lds + PG8_SA(b, h) + aoff + m * 2048 + k * 1024); } while (0)
; #define PG8_LDB(dst, b, h) do { _Pragma("unroll") for (int n = 0; n < 2; ++n) _Pragma("unroll") for (int k = 0; k < 2; ++k) dst[n][k] = *(const PG8_LAS bf16x8*)(lds + PG8_SB(b, h) + boff + n * 2048 + k * 1024); } while (0)
; #define PG8_MMA(ai, bj, At, Bt) do { __builtin_amdgcn_s_setprio(1); _Pragma("unroll") for (int m = 0; m < 4; ++m) _Pragma("unroll") for (int n = 0; n < 2; ++n) _Pragma("unroll") for (int k = 0; k < 2; ++k) \
;         acc[ai][bj][m][n] = __builtin_amdgcn_mfma_f32_16x16x32_bf16(Bt[n][k], At[m][k], acc[ai][bj][m][n], 0, 0, 0); __builtin_amdgcn_s_setprio(0); } while (0)
; #define PG8_WAIT_V(n) asm volatile("s_waitcnt vmcnt(" #n ")" ::: "memory")
; template <class Epi, class Sched, bool ALIGN_EPI = false, bool SP2 = false>
; __device__ __forceinline__ void gemm_phase(PG8_LAS unsigned char* lds, const Gemm g, const Sched S, const Epi E) {
;     ...
;             PG8_LDB(B0, 0, 0); PG8_LDB(B1, 0, 1); PG8_SCHED; PG8_LDA(At, 0, 0); PG8_STAGE(PG8_SA(1, 1), a1 + hstep, voffA);
;             PG8_WAIT_V(8); PG8_WAIT_L(0); PG8_BAR; PG8_MMA(0, 0, At, B0); PG8_MMA(0, 1, At, B1); PG8_BAR; PG8_SCHED;
;             PG8_LDA(At, 0, 1); PG8_STAGE(PG8_SB(0, 0), b2, voffB); PG8_STAGE(PG8_SB(0, 1), b2 + hstep, voffB); PG8_STAGE(PG8_SA(0, 0), a2, voffA);
;             PG8_WAIT_V(8); PG8_WAIT_L(0); PG8_BAR; PG8_MMA(1, 0, At, B0); PG8_MMA(1, 1, At, B1); PG8_BAR; PG8_SCHED;
;             PG8_LDB(B0, 1, 0); PG8_LDB(B1, 1, 1); PG8_SCHED; PG8_LDA(At, 1, 0); PG8_STAGE(PG8_SA(0, 1), a2 + hstep, voffA);
;             PG8_WAIT_V(8); PG8_WAIT_L(0); PG8_BAR; PG8_MMA(0, 0, At, B0); PG8_MMA(0, 1, At, B1); PG8_BAR; PG8_SCHED;
;             PG8_LDA(At, 1, 1); PG8_STAGE(PG8_SB(1, 0), b3, voffB); PG8_STAGE(PG8_SB(1, 1), b3 + hstep, voffB); PG8_STAGE(PG8_SA(1, 0), a3, voffA);
;             PG8_WAIT_V(8); PG8_WAIT_L(0); PG8_BAR; PG8_MMA(1, 0, At, B0); PG8_MMA(1, 1, At, B1); PG8_BAR; PG8_SCHED;
	v_mfma_f32_16x16x32_bf16 v[56:59], v[180:183], v[218:221], v[56:59]
	s_setprio 0
	s_add_i32 vcc_lo, s46, s8
	s_add_i32 s46, vcc_lo, 0x2000
	v_lshl_add_u64 v[142:143], v[142:143], 0, s[64:65]
	s_mov_b32 m0, vcc_lo
	s_add_u32 s86, s86, 0x10180
	ds_read_b128 v[190:193], v152 offset:49152
	ds_read_b128 v[194:197], v152 offset:50176
	ds_read_b128 v[198:201], v152 offset:51200
	ds_read_b128 v[202:205], v152 offset:52224
	ds_read_b128 v[206:209], v152 offset:53248
	ds_read_b128 v[210:213], v152 offset:54272
	ds_read_b128 v[214:217], v152 offset:55296
	ds_read_b128 v[218:221], v152 offset:56320
	global_load_lds_dwordx4 v[142:143], off
	v_lshl_add_u64 v[142:143], v[146:147], 0, s[64:65]
	s_mov_b32 m0, s46
	s_addc_u32 s87, s87, 0
	s_add_i32 s77, s77, s8
	global_load_lds_dwordx4 v[142:143], off
	v_lshl_add_u64 v[142:143], s[86:87], 0, v[128:129]
	s_mov_b32 m0, s77
	s_add_i32 s79, s77, 0x2000
	global_load_lds_dwordx4 v[142:143], off
	v_lshl_add_u64 v[142:143], s[86:87], 0, v[130:131]
	s_mov_b32 m0, s79
	s_nop 0
	global_load_lds_dwordx4 v[142:143], off
	v_lshl_add_u64 v[142:143], v[184:185], 0, s[64:65]
	s_mov_b32 m0, s69
	s_nop 0
	global_load_lds_dwordx4 v[142:143], off
	v_lshl_add_u64 v[142:143], v[222:223], 0, s[64:65]
	s_mov_b32 m0, s90
	s_nop 0
	global_load_lds_dwordx4 v[142:143], off
	s_waitcnt vmcnt(8)
	s_waitcnt lgkmcnt(0)
	s_barrier
	s_setprio 1
	s_waitcnt lgkmcnt(0)
	v_mfma_f32_16x16x32_bf16 v[0:3], v[24:27], v[214:217], v[0:3]
	v_mfma_f32_16x16x32_bf16 v[4:7], v[112:115], v[214:217], v[4:7]
	v_mfma_f32_16x16x32_bf16 v[138:141], v[24:27], v[190:193], v[138:141]
	v_mfma_f32_16x16x32_bf16 v[156:159], v[112:115], v[190:193], v[156:159]
	v_mfma_f32_16x16x32_bf16 v[160:163], v[24:27], v[198:201], v[160:163]
	v_mfma_f32_16x16x32_bf16 v[164:167], v[112:115], v[198:201], v[164:167]
	v_mfma_f32_16x16x32_bf16 v[168:171], v[24:27], v[206:209], v[168:171]
	v_mfma_f32_16x16x32_bf16 v[172:175], v[112:115], v[206:209], v[172:175]
	v_mfma_f32_16x16x32_bf16 v[0:3], v[28:31], v[218:221], v[0:3]
	v_mfma_f32_16x16x32_bf16 v[4:7], v[116:119], v[218:221], v[4:7]
	v_mfma_f32_16x16x32_bf16 v[138:141], v[28:31], v[194:197], v[138:141]
	v_mfma_f32_16x16x32_bf16 v[156:159], v[116:119], v[194:197], v[156:159]
	v_mfma_f32_16x16x32_bf16 v[160:163], v[28:31], v[202:205], v[160:163]
	v_mfma_f32_16x16x32_bf16 v[164:167], v[116:119], v[202:205], v[164:167]
	v_mfma_f32_16x16x32_bf16 v[168:171], v[28:31], v[210:213], v[168:171]
	v_mfma_f32_16x16x32_bf16 v[172:175], v[116:119], v[210:213], v[172:175]
	s_setprio 0
	s_setprio 1
	v_mfma_f32_16x16x32_bf16 v[8:11], v[120:123], v[190:193], v[8:11]
	v_mfma_f32_16x16x32_bf16 v[12:15], v[176:179], v[190:193], v[12:15]
	v_mfma_f32_16x16x32_bf16 v[24:27], v[120:123], v[198:201], v[60:63]
	v_mfma_f32_16x16x32_bf16 v[28:31], v[176:179], v[198:201], v[100:103]
	v_mfma_f32_16x16x32_bf16 v[60:63], v[120:123], v[206:209], v[104:107]
	v_mfma_f32_16x16x32_bf16 v[100:103], v[176:179], v[206:209], v[108:111]
	v_mfma_f32_16x16x32_bf16 v[16:19], v[120:123], v[214:217], v[16:19]
	v_mfma_f32_16x16x32_bf16 v[20:23], v[176:179], v[214:217], v[20:23]
	v_mfma_f32_16x16x32_bf16 v[8:11], v[124:127], v[194:197], v[8:11]
	v_mfma_f32_16x16x32_bf16 v[12:15], v[180:183], v[194:197], v[12:15]
	v_mfma_f32_16x16x32_bf16 v[24:27], v[124:127], v[202:205], v[24:27]
	v_mfma_f32_16x16x32_bf16 v[28:31], v[180:183], v[202:205], v[28:31]
	v_mfma_f32_16x16x32_bf16 v[60:63], v[124:127], v[210:213], v[60:63]
	v_mfma_f32_16x16x32_bf16 v[100:103], v[180:183], v[210:213], v[100:103]
	v_mfma_f32_16x16x32_bf16 v[16:19], v[124:127], v[218:221], v[16:19]
	s_barrier
	v_mfma_f32_16x16x32_bf16 v[20:23], v[180:183], v[218:221], v[20:23]
	s_setprio 0
	ds_read_b128 v[104:107], v150
	ds_read_b128 v[108:111], v150 offset:1024
	ds_read_b128 v[112:115], v150 offset:2048
	ds_read_b128 v[116:119], v150 offset:3072
	ds_read_b128 v[120:123], v151
	ds_read_b128 v[124:127], v151 offset:1024
	ds_read_b128 v[176:179], v151 offset:2048
	ds_read_b128 v[180:183], v151 offset:3072
	s_add_u32 s6, s6, 0x10180
	s_addc_u32 s7, s7, 0
	s_mov_b32 m0, s96
	v_lshl_add_u64 v[142:143], s[6:7], 0, v[128:129]
	ds_read_b128 v[190:193], v152
	ds_read_b128 v[194:197], v152 offset:1024
	ds_read_b128 v[198:201], v152 offset:2048
	ds_read_b128 v[202:205], v152 offset:3072
	ds_read_b128 v[206:209], v152 offset:4096
	ds_read_b128 v[210:213], v152 offset:5120
	ds_read_b128 v[214:217], v152 offset:6144
	ds_read_b128 v[218:221], v152 offset:7168
	global_load_lds_dwordx4 v[142:143], off
	v_lshl_add_u64 v[142:143], s[6:7], 0, v[130:131]
	s_mov_b32 m0, s97
	s_nop 0
	global_load_lds_dwordx4 v[142:143], off
	s_waitcnt vmcnt(8)
	s_waitcnt lgkmcnt(0)
	s_barrier
; #define PG8_STAGE(bufoff, gbase, voff) do { _Pragma("unroll") for (int _i = 0; _i < 2; ++_i) \
;         __builtin_amdgcn_global_load_lds((const unsigned*)((const char*)(gbase) + (voff)[_i]), (PG8_LAS unsigned*)(lds + (bufoff) + ldsw + _i * 8192), 16, 0, 0); } while (0)
; #define PG8_LDA(dst, b, h) do { _Pragma("unroll") for (int m = 0; m < 4; ++m) _Pragma("unroll") for (int k = 0; k < 2; ++k) dst[m][k] = *(const PG8_LAS bf16x8*)(lds + PG8_SA(b, h) + aoff + m * 2048 + k * 1024); } while (0)
; #define PG8_LDB(dst, b, h) do { _Pragma("unroll") for (int n = 0; n < 2; ++n) _Pragma("unroll") for (int k = 0; k < 2; ++k) dst[n][k] = *(const PG8_LAS bf16x8*)(lds + PG8_SB(b, h) + boff + n * 2048 + k * 1024); } while (0)
; #define PG8_MMA(ai, bj, At, Bt) do { __builtin_amdgcn_s_setprio(1); _Pragma("unroll") for (int m = 0; m < 4; ++m) _Pragma("unroll") for (int n = 0; n < 2; ++n) _Pragma("unroll") for (int k = 0; k < 2; ++k) \
;         acc[ai][bj][m][n] = __builtin_amdgcn_mfma_f32_16x16x32_bf16(Bt[n][k], At[m][k], acc[ai][bj][m][n], 0, 0, 0); __builtin_amdgcn_s_setprio(0); } while (0)
; #define PG8_WAIT_V(n) asm volatile("s_waitcnt vmcnt(" #n ")" ::: "memory")
; template <class Epi, class Sched, bool ALIGN_EPI = false, bool SP2 = false>
; __device__ __forceinline__ void gemm_phase(PG8_LAS unsigned char* lds, const Gemm g, const Sched S, const Epi E) {
;     ...
;             PG8_LDB(B0, 0, 0); PG8_LDB(B1, 0, 1); PG8_SCHED; PG8_LDA(At, 0, 0); PG8_STAGE(PG8_SA(1, 1), a1 + hstep, voffA);
;             PG8_WAIT_V(8); PG8_WAIT_L(0); PG8_BAR; PG8_MMA(0, 0, At, B0); PG8_MMA(0, 1, At, B1); PG8_BAR; PG8_SCHED;
;             PG8_LDA(At, 0, 1); PG8_STAGE(PG8_SB(0, 0), b2, voffB); PG8_STAGE(PG8_SB(0, 1), b2 + hstep, voffB); PG8_STAGE(PG8_SA(0, 0), a2, voffA);
;             PG8_WAIT_V(8); PG8_WAIT_L(0); PG8_BAR; PG8_MMA(1, 0, At, B0); PG8_MMA(1, 1, At, B1); PG8_BAR; PG8_SCHED;
;             PG8_LDB(B0, 1, 0); PG8_LDB(B1, 1, 1); PG8_SCHED; PG8_LDA(At, 1, 0); PG8_STAGE(PG8_SA(0, 1), a2 + hstep, voffA);
;             PG8_WAIT_V(8); PG8_WAIT_L(0); PG8_BAR; PG8_MMA(0, 0, At, B0); PG8_MMA(0, 1, At, B1); PG8_BAR; PG8_SCHED;
;             PG8_LDA(At, 1, 1); PG8_STAGE(PG8_SB(1, 0), b3, voffB); PG8_STAGE(PG8_SB(1, 1), b3 + hstep, voffB); PG8_STAGE(PG8_SA(1, 0), a3, voffA);
;             PG8_WAIT_V(8); PG8_WAIT_L(0); PG8_BAR; PG8_MMA(1, 0, At, B0); PG8_MMA(1, 1, At, B1); PG8_BAR; PG8_SCHED;
	s_setprio 1
	s_waitcnt lgkmcnt(0)
	v_mfma_f32_16x16x32_bf16 v[64:67], v[104:107], v[190:193], v[64:67]
	v_mfma_f32_16x16x32_bf16 v[68:71], v[112:115], v[190:193], v[68:71]
	v_mfma_f32_16x16x32_bf16 v[72:75], v[104:107], v[198:201], v[72:75]
	v_mfma_f32_16x16x32_bf16 v[76:79], v[112:115], v[198:201], v[76:79]
	v_mfma_f32_16x16x32_bf16 v[80:83], v[104:107], v[206:209], v[80:83]
	v_mfma_f32_16x16x32_bf16 v[84:87], v[112:115], v[206:209], v[84:87]
	v_mfma_f32_16x16x32_bf16 v[88:91], v[104:107], v[214:217], v[88:91]
	v_mfma_f32_16x16x32_bf16 v[64:67], v[108:111], v[194:197], v[64:67]
	v_mfma_f32_16x16x32_bf16 v[68:71], v[116:119], v[194:197], v[68:71]
	v_mfma_f32_16x16x32_bf16 v[72:75], v[108:111], v[202:205], v[72:75]
	v_mfma_f32_16x16x32_bf16 v[76:79], v[116:119], v[202:205], v[76:79]
	v_mfma_f32_16x16x32_bf16 v[80:83], v[108:111], v[210:213], v[80:83]
	v_mfma_f32_16x16x32_bf16 v[84:87], v[116:119], v[210:213], v[84:87]
	v_mfma_f32_16x16x32_bf16 v[88:91], v[108:111], v[218:221], v[88:91]
	v_mfma_f32_16x16x32_bf16 v[92:95], v[112:115], v[214:217], v[92:95]
	v_mfma_f32_16x16x32_bf16 v[222:225], v[116:119], v[218:221], v[92:95]
	s_setprio 0
	s_setprio 1
	v_mfma_f32_16x16x32_bf16 v[92:95], v[120:123], v[190:193], v[96:99]
	v_mfma_f32_16x16x32_bf16 v[32:35], v[176:179], v[190:193], v[32:35]
	v_mfma_f32_16x16x32_bf16 v[36:39], v[120:123], v[198:201], v[36:39]
	v_mfma_f32_16x16x32_bf16 v[40:43], v[176:179], v[198:201], v[40:43]
	v_mfma_f32_16x16x32_bf16 v[44:47], v[120:123], v[206:209], v[44:47]
	v_mfma_f32_16x16x32_bf16 v[48:51], v[176:179], v[206:209], v[48:51]
	v_mfma_f32_16x16x32_bf16 v[52:55], v[120:123], v[214:217], v[52:55]
	v_mfma_f32_16x16x32_bf16 v[56:59], v[176:179], v[214:217], v[56:59]
	v_mfma_f32_16x16x32_bf16 v[96:99], v[124:127], v[194:197], v[92:95]
	v_mfma_f32_16x16x32_bf16 v[32:35], v[180:183], v[194:197], v[32:35]
	v_mfma_f32_16x16x32_bf16 v[36:39], v[124:127], v[202:205], v[36:39]
	v_mfma_f32_16x16x32_bf16 v[40:43], v[180:183], v[202:205], v[40:43]
	v_mfma_f32_16x16x32_bf16 v[44:47], v[124:127], v[210:213], v[44:47]
	v_mfma_f32_16x16x32_bf16 v[48:51], v[180:183], v[210:213], v[48:51]
	v_mfma_f32_16x16x32_bf16 v[52:55], v[124:127], v[218:221], v[52:55]
	s_barrier
	v_mfma_f32_16x16x32_bf16 v[56:59], v[180:183], v[218:221], v[56:59]
	s_setprio 0
	s_mov_b32 m0, s61
	v_lshl_add_u64 v[142:143], s[84:85], 0, v[128:129]
	s_add_u32 s6, s84, 0x10000
	ds_read_b128 v[92:95], v152 offset:16384
	ds_read_b128 v[190:193], v152 offset:17408
	ds_read_b128 v[194:197], v152 offset:18432
	ds_read_b128 v[198:201], v152 offset:19456
	ds_read_b128 v[202:205], v152 offset:20480
	ds_read_b128 v[206:209], v152 offset:21504
	ds_read_b128 v[210:213], v152 offset:22528
	ds_read_b128 v[214:217], v152 offset:23552
	global_load_lds_dwordx4 v[142:143], off
	v_lshl_add_u64 v[146:147], s[84:85], 0, v[130:131]
	s_mov_b32 m0, s36
	s_addc_u32 s7, s85, 0
	global_load_lds_dwordx4 v[146:147], off
	v_lshl_add_u64 v[184:185], s[6:7], 0, v[128:129]
	s_mov_b32 m0, s1
	v_lshl_add_u64 v[186:187], s[88:89], 0, v[130:131]
	global_load_lds_dwordx4 v[184:185], off
	v_lshl_add_u64 v[184:185], s[6:7], 0, v[130:131]
	s_mov_b32 m0, s11
	s_nop 0
	global_load_lds_dwordx4 v[184:185], off
	v_lshl_add_u64 v[184:185], s[88:89], 0, v[128:129]
	s_mov_b32 m0, s9
	s_nop 0
	global_load_lds_dwordx4 v[184:185], off
	s_mov_b32 m0, s18
	s_nop 0
	global_load_lds_dwordx4 v[186:187], off
	s_waitcnt vmcnt(8)
	s_waitcnt lgkmcnt(0)
	s_barrier
	s_setprio 1
	s_waitcnt lgkmcnt(0)
	v_mfma_f32_16x16x32_bf16 v[0:3], v[104:107], v[210:213], v[0:3]
	v_mfma_f32_16x16x32_bf16 v[4:7], v[112:115], v[210:213], v[4:7]
	v_mfma_f32_16x16x32_bf16 v[138:141], v[104:107], v[92:95], v[138:141]
	v_mfma_f32_16x16x32_bf16 v[156:159], v[112:115], v[92:95], v[156:159]
	v_mfma_f32_16x16x32_bf16 v[160:163], v[104:107], v[194:197], v[160:163]
	v_mfma_f32_16x16x32_bf16 v[164:167], v[112:115], v[194:197], v[164:167]
	v_mfma_f32_16x16x32_bf16 v[168:171], v[104:107], v[202:205], v[168:171]
	v_mfma_f32_16x16x32_bf16 v[172:175], v[112:115], v[202:205], v[172:175]
	v_mfma_f32_16x16x32_bf16 v[0:3], v[108:111], v[214:217], v[0:3]
	v_mfma_f32_16x16x32_bf16 v[4:7], v[116:119], v[214:217], v[4:7]
	v_mfma_f32_16x16x32_bf16 v[138:141], v[108:111], v[190:193], v[138:141]
	v_mfma_f32_16x16x32_bf16 v[156:159], v[116:119], v[190:193], v[156:159]
	v_mfma_f32_16x16x32_bf16 v[160:163], v[108:111], v[198:201], v[160:163]
	v_mfma_f32_16x16x32_bf16 v[164:167], v[116:119], v[198:201], v[164:167]
	v_mfma_f32_16x16x32_bf16 v[168:171], v[108:111], v[206:209], v[168:171]
	v_mfma_f32_16x16x32_bf16 v[172:175], v[116:119], v[206:209], v[172:175]
	s_setprio 0
	s_setprio 1
	v_mfma_f32_16x16x32_bf16 v[8:11], v[120:123], v[92:95], v[8:11]
	v_mfma_f32_16x16x32_bf16 v[12:15], v[176:179], v[92:95], v[12:15]
	v_mfma_f32_16x16x32_bf16 v[8:11], v[124:127], v[190:193], v[8:11]
	v_mfma_f32_16x16x32_bf16 v[190:193], v[180:183], v[190:193], v[12:15]
	v_mfma_f32_16x16x32_bf16 v[12:15], v[120:123], v[194:197], v[24:27]
	v_mfma_f32_16x16x32_bf16 v[24:27], v[124:127], v[198:201], v[12:15]
	v_mfma_f32_16x16x32_bf16 v[12:15], v[176:179], v[194:197], v[28:31]
	v_mfma_f32_16x16x32_bf16 v[194:197], v[180:183], v[198:201], v[12:15]
	v_mfma_f32_16x16x32_bf16 v[12:15], v[120:123], v[202:205], v[60:63]
	v_mfma_f32_16x16x32_bf16 v[198:201], v[124:127], v[206:209], v[12:15]
	v_mfma_f32_16x16x32_bf16 v[12:15], v[176:179], v[202:205], v[100:103]
	v_mfma_f32_16x16x32_bf16 v[202:205], v[180:183], v[206:209], v[12:15]
	v_mfma_f32_16x16x32_bf16 v[12:15], v[120:123], v[210:213], v[16:19]
	v_mfma_f32_16x16x32_bf16 v[206:209], v[124:127], v[214:217], v[12:15]
	v_mfma_f32_16x16x32_bf16 v[12:15], v[176:179], v[210:213], v[20:23]
	s_barrier
; #define PG8_STAGE(bufoff, gbase, voff) do { _Pragma("unroll") for (int _i = 0; _i < 2; ++_i) \
;         __builtin_amdgcn_global_load_lds((const unsigned*)((const char*)(gbase) + (voff)[_i]), (PG8_LAS unsigned*)(lds + (bufoff) + ldsw + _i * 8192), 16, 0, 0); } while (0)
; #define PG8_LDA(dst, b, h) do { _Pragma("unroll") for (int m = 0; m < 4; ++m) _Pragma("unroll") for (int k = 0; k < 2; ++k) dst[m][k] = *(const PG8_LAS bf16x8*)(lds + PG8_SA(b, h) + aoff + m * 2048 + k * 1024); } while (0)
; #define PG8_LDB(dst, b, h) do { _Pragma("unroll") for (int n = 0; n < 2; ++n) _Pragma("unroll") for (int k = 0; k < 2; ++k) dst[n][k] = *(const PG8_LAS bf16x8*)(lds + PG8_SB(b, h) + boff + n * 2048 + k * 1024); } while (0)
; #define PG8_MMA(ai, bj, At, Bt) do { __builtin_amdgcn_s_setprio(1); _Pragma("unroll") for (int m = 0; m < 4; ++m) _Pragma("unroll") for (int n = 0; n < 2; ++n) _Pragma("unroll") for (int k = 0; k < 2; ++k) \
;         acc[ai][bj][m][n] = __builtin_amdgcn_mfma_f32_16x16x32_bf16(Bt[n][k], At[m][k], acc[ai][bj][m][n], 0, 0, 0); __builtin_amdgcn_s_setprio(0); } while (0)
; #define PG8_WAIT_V(n) asm volatile("s_waitcnt vmcnt(" #n ")" ::: "memory")
; template <class Epi, class Sched, bool ALIGN_EPI = false, bool SP2 = false>
; __device__ __forceinline__ void gemm_phase(PG8_LAS unsigned char* lds, const Gemm g, const Sched S, const Epi E) {
;     ...
;             PG8_LDB(B0, 0, 0); PG8_LDB(B1, 0, 1); PG8_SCHED; PG8_LDA(At, 0, 0); PG8_STAGE(PG8_SA(1, 1), a1 + hstep, voffA);
;             PG8_WAIT_V(8); PG8_WAIT_L(0); PG8_BAR; PG8_MMA(0, 0, At, B0); PG8_MMA(0, 1, At, B1); PG8_BAR; PG8_SCHED;
;             PG8_LDA(At, 0, 1); PG8_STAGE(PG8_SB(0, 0), b2, voffB); PG8_STAGE(PG8_SB(0, 1), b2 + hstep, voffB); PG8_STAGE(PG8_SA(0, 0), a2, voffA);
;             PG8_WAIT_V(8); PG8_WAIT_L(0); PG8_BAR; PG8_MMA(1, 0, At, B0); PG8_MMA(1, 1, At, B1); PG8_BAR; PG8_SCHED;
;             PG8_LDB(B0, 1, 0); PG8_LDB(B1, 1, 1); PG8_SCHED; PG8_LDA(At, 1, 0); PG8_STAGE(PG8_SA(0, 1), a2 + hstep, voffA);
;             PG8_WAIT_V(8); PG8_WAIT_L(0); PG8_BAR; PG8_MMA(0, 0, At, B0); PG8_MMA(0, 1, At, B1); PG8_BAR; PG8_SCHED;
;             PG8_LDA(At, 1, 1); PG8_STAGE(PG8_SB(1, 0), b3, voffB); PG8_STAGE(PG8_SB(1, 1), b3 + hstep, voffB); PG8_STAGE(PG8_SA(1, 0), a3, voffA);
;             PG8_WAIT_V(8); PG8_WAIT_L(0); PG8_BAR; PG8_MMA(1, 0, At, B0); PG8_MMA(1, 1, At, B1); PG8_BAR; PG8_SCHED;
	v_mfma_f32_16x16x32_bf16 v[176:179], v[180:183], v[214:217], v[12:15]
	s_setprio 0
	s_nop 4
	ds_read_b128 v[12:15], v132
	ds_read_b128 v[16:19], v132 offset:1024
	ds_read_b128 v[180:183], v132 offset:2048
	ds_read_b128 v[210:213], v132 offset:3072
	ds_read_b128 v[214:217], v144
	ds_read_b128 v[218:221], v144 offset:1024
	ds_read_b128 v[226:229], v144 offset:2048
	ds_read_b128 v[230:233], v144 offset:3072
	s_add_u32 s6, s88, 0x10000
	s_addc_u32 s7, s89, 0
	s_mov_b32 m0, s19
	v_lshl_add_u64 v[92:93], s[6:7], 0, v[128:129]
	ds_read_b128 v[20:23], v152 offset:32768
	ds_read_b128 v[28:31], v152 offset:33792
	ds_read_b128 v[60:63], v152 offset:34816
	ds_read_b128 v[234:237], v152 offset:35840
	ds_read_b128 v[238:241], v152 offset:36864
	ds_read_b128 v[242:245], v152 offset:37888
	ds_read_b128 v[246:249], v152 offset:38912
	ds_read_b128 v[250:253], v152 offset:39936
	global_load_lds_dwordx4 v[92:93], off
	v_lshl_add_u64 v[92:93], s[6:7], 0, v[130:131]
	s_mov_b32 m0, s54
	s_nop 0
	global_load_lds_dwordx4 v[92:93], off
	s_waitcnt vmcnt(8)
	s_waitcnt lgkmcnt(0)
	s_barrier
	s_setprio 1
	s_waitcnt lgkmcnt(0)
	v_mfma_f32_16x16x32_bf16 v[64:67], v[12:15], v[20:23], v[64:67]
	v_mfma_f32_16x16x32_bf16 v[124:127], v[16:19], v[28:31], v[64:67]
	v_mfma_f32_16x16x32_bf16 v[64:67], v[180:183], v[20:23], v[68:71]
	v_mfma_f32_16x16x32_bf16 v[116:119], v[210:213], v[28:31], v[64:67]
	v_mfma_f32_16x16x32_bf16 v[64:67], v[12:15], v[60:63], v[72:75]
	v_mfma_f32_16x16x32_bf16 v[108:111], v[16:19], v[234:237], v[64:67]
	v_mfma_f32_16x16x32_bf16 v[64:67], v[180:183], v[60:63], v[76:79]
	v_mfma_f32_16x16x32_bf16 v[100:103], v[210:213], v[234:237], v[64:67]
	v_mfma_f32_16x16x32_bf16 v[64:67], v[12:15], v[238:241], v[80:83]
	v_mfma_f32_16x16x32_bf16 v[92:95], v[16:19], v[242:245], v[64:67]
	v_mfma_f32_16x16x32_bf16 v[64:67], v[180:183], v[238:241], v[84:87]
	v_mfma_f32_16x16x32_bf16 v[84:87], v[210:213], v[242:245], v[64:67]
	v_mfma_f32_16x16x32_bf16 v[64:67], v[12:15], v[246:249], v[88:91]
	v_mfma_f32_16x16x32_bf16 v[76:79], v[16:19], v[250:253], v[64:67]
	v_mfma_f32_16x16x32_bf16 v[64:67], v[180:183], v[246:249], v[222:225]
	v_mfma_f32_16x16x32_bf16 v[68:71], v[210:213], v[250:253], v[64:67]
	s_setprio 0
	s_setprio 1
	v_mfma_f32_16x16x32_bf16 v[64:67], v[214:217], v[20:23], v[96:99]
	v_mfma_f32_16x16x32_bf16 v[20:23], v[226:229], v[20:23], v[32:35]
	v_mfma_f32_16x16x32_bf16 v[112:115], v[230:233], v[28:31], v[20:23]
	v_mfma_f32_16x16x32_bf16 v[20:23], v[214:217], v[60:63], v[36:39]
	v_mfma_f32_16x16x32_bf16 v[104:107], v[218:221], v[234:237], v[20:23]
	v_mfma_f32_16x16x32_bf16 v[20:23], v[226:229], v[60:63], v[40:43]
	v_mfma_f32_16x16x32_bf16 v[96:99], v[230:233], v[234:237], v[20:23]
	v_mfma_f32_16x16x32_bf16 v[20:23], v[214:217], v[238:241], v[44:47]
	v_mfma_f32_16x16x32_bf16 v[88:91], v[218:221], v[242:245], v[20:23]
	v_mfma_f32_16x16x32_bf16 v[20:23], v[226:229], v[238:241], v[48:51]
	v_mfma_f32_16x16x32_bf16 v[80:83], v[230:233], v[242:245], v[20:23]
	v_mfma_f32_16x16x32_bf16 v[20:23], v[214:217], v[246:249], v[52:55]
	v_mfma_f32_16x16x32_bf16 v[72:75], v[218:221], v[250:253], v[20:23]
	v_mfma_f32_16x16x32_bf16 v[20:23], v[226:229], v[246:249], v[56:59]
	v_mfma_f32_16x16x32_bf16 v[120:123], v[218:221], v[28:31], v[64:67]
	s_barrier
	v_mfma_f32_16x16x32_bf16 v[64:67], v[230:233], v[250:253], v[20:23]
	s_setprio 0
	s_mov_b32 m0, vcc_lo
	s_nop 2
	v_lshl_add_u64 v[20:21], v[142:143], 0, s[50:51]
	s_add_u32 s6, s84, 0x10080
	ds_read_b128 v[32:35], v152 offset:49152
	ds_read_b128 v[40:43], v152 offset:50176
	ds_read_b128 v[222:225], v152 offset:51200
	ds_read_b128 v[234:237], v152 offset:52224
	ds_read_b128 v[238:241], v152 offset:53248
	ds_read_b128 v[242:245], v152 offset:54272
	ds_read_b128 v[246:249], v152 offset:55296
	ds_read_b128 v[250:253], v152 offset:56320
	global_load_lds_dwordx4 v[20:21], off
	v_lshl_add_u64 v[20:21], v[146:147], 0, s[50:51]
	s_mov_b32 m0, s46
	s_addc_u32 s7, s85, 0
	global_load_lds_dwordx4 v[20:21], off
	v_lshl_add_u64 v[20:21], s[6:7], 0, v[128:129]
	s_mov_b32 m0, s77
	s_nop 0
	global_load_lds_dwordx4 v[20:21], off
	v_lshl_add_u64 v[20:21], s[6:7], 0, v[130:131]
	s_mov_b32 m0, s79
	s_nop 0
	global_load_lds_dwordx4 v[20:21], off
	v_lshl_add_u64 v[20:21], v[184:185], 0, s[50:51]
	s_mov_b32 m0, s69
	s_nop 0
	global_load_lds_dwordx4 v[20:21], off
	v_lshl_add_u64 v[20:21], v[186:187], 0, s[50:51]
	s_mov_b32 m0, s90
	s_nop 0
	global_load_lds_dwordx4 v[20:21], off
	s_waitcnt vmcnt(8)
	s_waitcnt lgkmcnt(0)
	s_barrier
	s_setprio 1
	s_waitcnt lgkmcnt(0)
	v_mfma_f32_16x16x32_bf16 v[20:23], v[12:15], v[32:35], v[138:141]
	v_mfma_f32_16x16x32_bf16 v[60:63], v[16:19], v[40:43], v[20:23]
	v_mfma_f32_16x16x32_bf16 v[20:23], v[180:183], v[32:35], v[156:159]
	v_mfma_f32_16x16x32_bf16 v[52:55], v[210:213], v[40:43], v[20:23]
	v_mfma_f32_16x16x32_bf16 v[20:23], v[12:15], v[222:225], v[160:163]
	v_mfma_f32_16x16x32_bf16 v[44:47], v[16:19], v[234:237], v[20:23]
	v_mfma_f32_16x16x32_bf16 v[20:23], v[180:183], v[222:225], v[164:167]
	v_mfma_f32_16x16x32_bf16 v[36:39], v[210:213], v[234:237], v[20:23]
	v_mfma_f32_16x16x32_bf16 v[20:23], v[12:15], v[238:241], v[168:171]
	v_mfma_f32_16x16x32_bf16 v[0:3], v[12:15], v[246:249], v[0:3]
	v_mfma_f32_16x16x32_bf16 v[28:31], v[16:19], v[242:245], v[20:23]
	v_mfma_f32_16x16x32_bf16 v[20:23], v[180:183], v[238:241], v[172:175]
	v_mfma_f32_16x16x32_bf16 v[12:15], v[16:19], v[250:253], v[0:3]
	v_mfma_f32_16x16x32_bf16 v[0:3], v[180:183], v[246:249], v[4:7]
	v_mfma_f32_16x16x32_bf16 v[20:23], v[210:213], v[242:245], v[20:23]
	v_mfma_f32_16x16x32_bf16 v[4:7], v[210:213], v[250:253], v[0:3]
	s_setprio 0
	s_setprio 1
	v_mfma_f32_16x16x32_bf16 v[0:3], v[214:217], v[32:35], v[8:11]
	v_mfma_f32_16x16x32_bf16 v[56:59], v[218:221], v[40:43], v[0:3]
	v_mfma_f32_16x16x32_bf16 v[0:3], v[226:229], v[32:35], v[190:193]
	v_mfma_f32_16x16x32_bf16 v[48:51], v[230:233], v[40:43], v[0:3]
	v_mfma_f32_16x16x32_bf16 v[0:3], v[214:217], v[222:225], v[24:27]
	v_mfma_f32_16x16x32_bf16 v[40:43], v[218:221], v[234:237], v[0:3]
	v_mfma_f32_16x16x32_bf16 v[0:3], v[226:229], v[222:225], v[194:197]
	v_mfma_f32_16x16x32_bf16 v[32:35], v[230:233], v[234:237], v[0:3]
	v_mfma_f32_16x16x32_bf16 v[0:3], v[214:217], v[238:241], v[198:201]
	v_mfma_f32_16x16x32_bf16 v[24:27], v[218:221], v[242:245], v[0:3]
	v_mfma_f32_16x16x32_bf16 v[0:3], v[226:229], v[238:241], v[202:205]
	v_mfma_f32_16x16x32_bf16 v[16:19], v[230:233], v[242:245], v[0:3]
	v_mfma_f32_16x16x32_bf16 v[0:3], v[214:217], v[246:249], v[206:209]
	v_mfma_f32_16x16x32_bf16 v[8:11], v[218:221], v[250:253], v[0:3]
	v_mfma_f32_16x16x32_bf16 v[0:3], v[226:229], v[246:249], v[176:179]
	s_barrier
	v_mfma_f32_16x16x32_bf16 v[0:3], v[230:233], v[250:253], v[0:3]
	s_setprio 0
	s_andn2_b64 vcc, exec, s[52:53]
	s_cbranch_vccnz .LBB0_618
	s_barrier

; #define PG8_STAGE(bufoff, gbase, voff) do { _Pragma("unroll") for (int _i = 0; _i < 2; ++_i) \
;         __builtin_amdgcn_global_load_lds((const unsigned*)((const char*)(gbase) + (voff)[_i]), (PG8_LAS unsigned*)(lds + (bufoff) + ldsw + _i * 8192), 16, 0, 0); } while (0)
; #define PG8_LDA(dst, b, h) do { _Pragma("unroll") for (int m = 0; m < 4; ++m) _Pragma("unroll") for (int k = 0; k < 2; ++k) dst[m][k] = *(const PG8_LAS bf16x8*)(lds + PG8_SA(b, h) + aoff + m * 2048 + k * 1024); } while (0)
; #define PG8_LDB(dst, b, h) do { _Pragma("unroll") for (int n = 0; n < 2; ++n) _Pragma("unroll") for (int k = 0; k < 2; ++k) dst[n][k] = *(const PG8_LAS bf16x8*)(lds + PG8_SB(b, h) + boff + n * 2048 + k * 1024); } while (0)
; #define PG8_MMA(ai, bj, At, Bt) do { __builtin_amdgcn_s_setprio(1); _Pragma("unroll") for (int m = 0; m < 4; ++m) _Pragma("unroll") for (int n = 0; n < 2; ++n) _Pragma("unroll") for (int k = 0; k < 2; ++k) \
;         acc[ai][bj][m][n] = __builtin_amdgcn_mfma_f32_16x16x32_bf16(Bt[n][k], At[m][k], acc[ai][bj][m][n], 0, 0, 0); __builtin_amdgcn_s_setprio(0); } while (0)
; #define PG8_WAIT_V(n) asm volatile("s_waitcnt vmcnt(" #n ")" ::: "memory")
; template <class Epi, class Sched, bool ALIGN_EPI = false, bool SP2 = false>
; __device__ __forceinline__ void gemm_phase(PG8_LAS unsigned char* lds, const Gemm g, const Sched S, const Epi E) {
;     ...
;             PG8_LDB(B0, 0, 0); PG8_LDB(B1, 0, 1); PG8_SCHED; PG8_LDA(At, 0, 0); PG8_STAGE(PG8_SA(1, 1), a1 + hstep, voffA);
;             PG8_WAIT_V(8); PG8_WAIT_L(0); PG8_BAR; PG8_MMA(0, 0, At, B0); PG8_MMA(0, 1, At, B1); PG8_BAR; PG8_SCHED;
;             PG8_LDA(At, 0, 1); PG8_STAGE(PG8_SB(0, 0), b2, voffB); PG8_STAGE(PG8_SB(0, 1), b2 + hstep, voffB); PG8_STAGE(PG8_SA(0, 0), a2, voffA);
;             PG8_WAIT_V(8); PG8_WAIT_L(0); PG8_BAR; PG8_MMA(1, 0, At, B0); PG8_MMA(1, 1, At, B1); PG8_BAR; PG8_SCHED;
;             PG8_LDB(B0, 1, 0); PG8_LDB(B1, 1, 1); PG8_SCHED; PG8_LDA(At, 1, 0); PG8_STAGE(PG8_SA(0, 1), a2 + hstep, voffA);
;             PG8_WAIT_V(8); PG8_WAIT_L(0); PG8_BAR; PG8_MMA(0, 0, At, B0); PG8_MMA(0, 1, At, B1); PG8_BAR; PG8_SCHED;
;             PG8_LDA(At, 1, 1); PG8_STAGE(PG8_SB(1, 0), b3, voffB); PG8_STAGE(PG8_SB(1, 1), b3 + hstep, voffB); PG8_STAGE(PG8_SA(1, 0), a3, voffA);
;             PG8_WAIT_V(8); PG8_WAIT_L(0); PG8_BAR; PG8_MMA(1, 0, At, B0); PG8_MMA(1, 1, At, B1); PG8_BAR; PG8_SCHED;
.LBB0_672:
	s_ashr_i32 s65, s64, 31
	s_lshl_b64 s[66:67], s[64:65], 16
	s_add_u32 s66, s37, s66
	s_addc_u32 s67, s72, s67
	s_and_b64 s[70:71], s[0:1], exec
	s_cselect_b32 s79, s67, s77
	s_cselect_b32 s78, s66, s76
	s_ashr_i32 s63, s62, 31
	s_lshl_b64 s[70:71], s[62:63], 16
	v_readlane_b32 s38, v255, 32
	v_readlane_b32 s39, v255, 33
	s_add_u32 s70, s38, s70
	s_addc_u32 s71, s39, s71
	s_add_u32 s84, s76, 0x8080
	ds_read_b128 v[0:3], v144
	ds_read_b128 v[4:7], v144 offset:1024
	ds_read_b128 v[8:11], v144 offset:2048
	ds_read_b128 v[12:15], v144 offset:3072
	ds_read_b128 v[16:19], v145
	ds_read_b128 v[20:23], v145 offset:1024
	ds_read_b128 v[24:27], v145 offset:2048
	ds_read_b128 v[28:31], v145 offset:3072
	s_addc_u32 s85, s77, 0
	s_add_u32 s76, s78, 0x8000
	s_addc_u32 s77, s79, 0
	s_and_b64 s[86:87], s[0:1], exec
	s_cselect_b32 s74, s70, s74
	s_cselect_b32 s75, s71, s75
	s_add_u32 s86, s74, 0x8000
	s_addc_u32 s87, s75, 0
	s_mov_b32 m0, s80
	v_lshl_add_u64 v[64:65], s[84:85], 0, v[128:129]
	ds_read_b128 v[32:35], v146
	ds_read_b128 v[36:39], v146 offset:1024
	ds_read_b128 v[40:43], v146 offset:2048
	ds_read_b128 v[44:47], v146 offset:3072
	ds_read_b128 v[48:51], v146 offset:4096
	ds_read_b128 v[52:55], v146 offset:5120
	ds_read_b128 v[56:59], v146 offset:6144
	ds_read_b128 v[60:63], v146 offset:7168
	global_load_lds_dwordx4 v[64:65], off
	v_lshl_add_u64 v[64:65], s[84:85], 0, v[130:131]
	s_mov_b32 m0, s81
	s_nop 0
	global_load_lds_dwordx4 v[64:65], off
	s_waitcnt vmcnt(8)
	s_waitcnt lgkmcnt(0)
	s_barrier
	s_setprio 1
	s_waitcnt lgkmcnt(0)
	v_mfma_f32_16x16x32_bf16 v[88:91], v[0:3], v[56:59], 0
	v_mfma_f32_16x16x32_bf16 v[64:67], v[0:3], v[32:35], 0
	v_mfma_f32_16x16x32_bf16 v[68:71], v[8:11], v[32:35], 0
	v_mfma_f32_16x16x32_bf16 v[72:75], v[0:3], v[40:43], 0
	v_mfma_f32_16x16x32_bf16 v[76:79], v[8:11], v[40:43], 0
	v_mfma_f32_16x16x32_bf16 v[80:83], v[0:3], v[48:51], 0
	v_mfma_f32_16x16x32_bf16 v[84:87], v[8:11], v[48:51], 0
	v_mfma_f32_16x16x32_bf16 v[96:99], v[4:7], v[60:63], v[88:91]
	v_mfma_f32_16x16x32_bf16 v[88:91], v[8:11], v[56:59], 0
	v_mfma_f32_16x16x32_bf16 v[64:67], v[4:7], v[36:39], v[64:67]
	v_mfma_f32_16x16x32_bf16 v[68:71], v[12:15], v[36:39], v[68:71]
	v_mfma_f32_16x16x32_bf16 v[72:75], v[4:7], v[44:47], v[72:75]
	v_mfma_f32_16x16x32_bf16 v[76:79], v[12:15], v[44:47], v[76:79]
	v_mfma_f32_16x16x32_bf16 v[80:83], v[4:7], v[52:55], v[80:83]
	v_mfma_f32_16x16x32_bf16 v[84:87], v[12:15], v[52:55], v[84:87]
	v_mfma_f32_16x16x32_bf16 v[100:103], v[12:15], v[60:63], v[88:91]
	s_setprio 0
	s_setprio 1
	v_mfma_f32_16x16x32_bf16 v[88:91], v[16:19], v[32:35], 0
	v_mfma_f32_16x16x32_bf16 v[32:35], v[24:27], v[32:35], 0
	v_mfma_f32_16x16x32_bf16 v[112:115], v[20:23], v[36:39], v[88:91]
	v_mfma_f32_16x16x32_bf16 v[32:35], v[28:31], v[36:39], v[32:35]
	v_mfma_f32_16x16x32_bf16 v[36:39], v[16:19], v[40:43], 0
	v_mfma_f32_16x16x32_bf16 v[40:43], v[24:27], v[40:43], 0
	v_mfma_f32_16x16x32_bf16 v[36:39], v[20:23], v[44:47], v[36:39]
	v_mfma_f32_16x16x32_bf16 v[40:43], v[28:31], v[44:47], v[40:43]
	v_mfma_f32_16x16x32_bf16 v[44:47], v[16:19], v[48:51], 0
	v_mfma_f32_16x16x32_bf16 v[48:51], v[24:27], v[48:51], 0
	v_mfma_f32_16x16x32_bf16 v[44:47], v[20:23], v[52:55], v[44:47]
	v_mfma_f32_16x16x32_bf16 v[48:51], v[28:31], v[52:55], v[48:51]
	v_mfma_f32_16x16x32_bf16 v[52:55], v[16:19], v[56:59], 0
	v_mfma_f32_16x16x32_bf16 v[56:59], v[24:27], v[56:59], 0
	v_mfma_f32_16x16x32_bf16 v[52:55], v[20:23], v[60:63], v[52:55]
	s_barrier
	v_mfma_f32_16x16x32_bf16 v[56:59], v[28:31], v[60:63], v[56:59]
	s_setprio 0
	s_mov_b32 m0, s82
	v_lshl_add_u64 v[138:139], s[74:75], 0, v[128:129]
	ds_read_b128 v[60:63], v146 offset:16384
	ds_read_b128 v[88:91], v146 offset:17408
	ds_read_b128 v[92:95], v146 offset:18432
	ds_read_b128 v[104:107], v146 offset:19456
	ds_read_b128 v[108:111], v146 offset:20480
	ds_read_b128 v[116:119], v146 offset:21504
	ds_read_b128 v[120:123], v146 offset:22528
	ds_read_b128 v[124:127], v146 offset:23552
	global_load_lds_dwordx4 v[138:139], off
	v_lshl_add_u64 v[186:187], s[74:75], 0, v[130:131]
	s_mov_b32 m0, s83
	s_add_i32 s7, s68, s8
	global_load_lds_dwordx4 v[186:187], off
	v_lshl_add_u64 v[150:151], s[86:87], 0, v[128:129]
	s_mov_b32 m0, s7
	v_lshl_add_u64 v[250:251], s[78:79], 0, v[128:129]
	global_load_lds_dwordx4 v[150:151], off
	v_lshl_add_u64 v[150:151], s[86:87], 0, v[130:131]
	s_add_i32 m0, s7, 0x2000
	v_lshl_add_u64 v[252:253], s[78:79], 0, v[130:131]
	global_load_lds_dwordx4 v[150:151], off
	s_mov_b32 m0, s9
	s_nop 0
	global_load_lds_dwordx4 v[250:251], off
	s_mov_b32 m0, s12
	s_nop 0
	global_load_lds_dwordx4 v[252:253], off
	s_waitcnt vmcnt(8)
	s_waitcnt lgkmcnt(0)
	s_barrier
; #define PG8_STAGE(bufoff, gbase, voff) do { _Pragma("unroll") for (int _i = 0; _i < 2; ++_i) \
;         __builtin_amdgcn_global_load_lds((const unsigned*)((const char*)(gbase) + (voff)[_i]), (PG8_LAS unsigned*)(lds + (bufoff) + ldsw + _i * 8192), 16, 0, 0); } while (0)
; #define PG8_LDA(dst, b, h) do { _Pragma("unroll") for (int m = 0; m < 4; ++m) _Pragma("unroll") for (int k = 0; k < 2; ++k) dst[m][k] = *(const PG8_LAS bf16x8*)(lds + PG8_SA(b, h) + aoff + m * 2048 + k * 1024); } while (0)
; #define PG8_LDB(dst, b, h) do { _Pragma("unroll") for (int n = 0; n < 2; ++n) _Pragma("unroll") for (int k = 0; k < 2; ++k) dst[n][k] = *(const PG8_LAS bf16x8*)(lds + PG8_SB(b, h) + boff + n * 2048 + k * 1024); } while (0)
; #define PG8_MMA(ai, bj, At, Bt) do { __builtin_amdgcn_s_setprio(1); _Pragma("unroll") for (int m = 0; m < 4; ++m) _Pragma("unroll") for (int n = 0; n < 2; ++n) _Pragma("unroll") for (int k = 0; k < 2; ++k) \
;         acc[ai][bj][m][n] = __builtin_amdgcn_mfma_f32_16x16x32_bf16(Bt[n][k], At[m][k], acc[ai][bj][m][n], 0, 0, 0); __builtin_amdgcn_s_setprio(0); } while (0)
; #define PG8_WAIT_V(n) asm volatile("s_waitcnt vmcnt(" #n ")" ::: "memory")
; template <class Epi, class Sched, bool ALIGN_EPI = false, bool SP2 = false>
; __device__ __forceinline__ void gemm_phase(PG8_LAS unsigned char* lds, const Gemm g, const Sched S, const Epi E) {
;     ...
;             PG8_LDB(B0, 0, 0); PG8_LDB(B1, 0, 1); PG8_SCHED; PG8_LDA(At, 0, 0); PG8_STAGE(PG8_SA(1, 1), a1 + hstep, voffA);
;             PG8_WAIT_V(8); PG8_WAIT_L(0); PG8_BAR; PG8_MMA(0, 0, At, B0); PG8_MMA(0, 1, At, B1); PG8_BAR; PG8_SCHED;
;             PG8_LDA(At, 0, 1); PG8_STAGE(PG8_SB(0, 0), b2, voffB); PG8_STAGE(PG8_SB(0, 1), b2 + hstep, voffB); PG8_STAGE(PG8_SA(0, 0), a2, voffA);
;             PG8_WAIT_V(8); PG8_WAIT_L(0); PG8_BAR; PG8_MMA(1, 0, At, B0); PG8_MMA(1, 1, At, B1); PG8_BAR; PG8_SCHED;
;             PG8_LDB(B0, 1, 0); PG8_LDB(B1, 1, 1); PG8_SCHED; PG8_LDA(At, 1, 0); PG8_STAGE(PG8_SA(0, 1), a2 + hstep, voffA);
;             PG8_WAIT_V(8); PG8_WAIT_L(0); PG8_BAR; PG8_MMA(0, 0, At, B0); PG8_MMA(0, 1, At, B1); PG8_BAR; PG8_SCHED;
;             PG8_LDA(At, 1, 1); PG8_STAGE(PG8_SB(1, 0), b3, voffB); PG8_STAGE(PG8_SB(1, 1), b3 + hstep, voffB); PG8_STAGE(PG8_SA(1, 0), a3, voffA);
;             PG8_WAIT_V(8); PG8_WAIT_L(0); PG8_BAR; PG8_MMA(1, 0, At, B0); PG8_MMA(1, 1, At, B1); PG8_BAR; PG8_SCHED;
	s_setprio 1
	s_waitcnt lgkmcnt(0)
	v_mfma_f32_16x16x32_bf16 v[150:153], v[0:3], v[60:63], 0
	v_mfma_f32_16x16x32_bf16 v[158:161], v[0:3], v[92:95], 0
	v_mfma_f32_16x16x32_bf16 v[166:169], v[0:3], v[108:111], 0
	v_mfma_f32_16x16x32_bf16 v[0:3], v[0:3], v[120:123], 0
	v_mfma_f32_16x16x32_bf16 v[150:153], v[4:7], v[88:91], v[150:153]
	v_mfma_f32_16x16x32_bf16 v[158:161], v[4:7], v[104:107], v[158:161]
	v_mfma_f32_16x16x32_bf16 v[166:169], v[4:7], v[116:119], v[166:169]
	v_mfma_f32_16x16x32_bf16 v[0:3], v[4:7], v[124:127], v[0:3]
	v_mfma_f32_16x16x32_bf16 v[4:7], v[8:11], v[120:123], 0
	v_mfma_f32_16x16x32_bf16 v[154:157], v[8:11], v[60:63], 0
	v_mfma_f32_16x16x32_bf16 v[162:165], v[8:11], v[92:95], 0
	v_mfma_f32_16x16x32_bf16 v[170:173], v[8:11], v[108:111], 0
	v_mfma_f32_16x16x32_bf16 v[4:7], v[12:15], v[124:127], v[4:7]
	v_mfma_f32_16x16x32_bf16 v[154:157], v[12:15], v[88:91], v[154:157]
	v_mfma_f32_16x16x32_bf16 v[162:165], v[12:15], v[104:107], v[162:165]
	v_mfma_f32_16x16x32_bf16 v[170:173], v[12:15], v[116:119], v[170:173]
	s_setprio 0
	s_setprio 1
	v_mfma_f32_16x16x32_bf16 v[8:11], v[16:19], v[60:63], 0
	v_mfma_f32_16x16x32_bf16 v[174:177], v[20:23], v[88:91], v[8:11]
	v_mfma_f32_16x16x32_bf16 v[8:11], v[24:27], v[60:63], 0
	v_mfma_f32_16x16x32_bf16 v[178:181], v[28:31], v[88:91], v[8:11]
	v_mfma_f32_16x16x32_bf16 v[8:11], v[16:19], v[92:95], 0
	v_mfma_f32_16x16x32_bf16 v[182:185], v[20:23], v[104:107], v[8:11]
	v_mfma_f32_16x16x32_bf16 v[8:11], v[24:27], v[92:95], 0
	v_mfma_f32_16x16x32_bf16 v[190:193], v[28:31], v[104:107], v[8:11]
	v_mfma_f32_16x16x32_bf16 v[8:11], v[16:19], v[108:111], 0
	v_mfma_f32_16x16x32_bf16 v[194:197], v[20:23], v[116:119], v[8:11]
	v_mfma_f32_16x16x32_bf16 v[8:11], v[24:27], v[108:111], 0
	v_mfma_f32_16x16x32_bf16 v[198:201], v[28:31], v[116:119], v[8:11]
	v_mfma_f32_16x16x32_bf16 v[8:11], v[16:19], v[120:123], 0
	v_mfma_f32_16x16x32_bf16 v[202:205], v[20:23], v[124:127], v[8:11]
	v_mfma_f32_16x16x32_bf16 v[8:11], v[24:27], v[120:123], 0
	s_barrier
	v_mfma_f32_16x16x32_bf16 v[206:209], v[28:31], v[124:127], v[8:11]
	s_setprio 0
	s_add_i32 s7, 0, 0x18000
	s_add_i32 s11, 0, 0x1c000
	v_add_u32_e32 v20, s7, v143
	v_add_u32_e32 v24, s11, v143
	s_nop 0
	ds_read_b128 v[8:11], v20
	ds_read_b128 v[12:15], v20 offset:1024
	ds_read_b128 v[16:19], v20 offset:2048
	ds_read_b128 v[20:23], v20 offset:3072
	ds_read_b128 v[210:213], v24
	ds_read_b128 v[214:217], v24 offset:1024
	ds_read_b128 v[218:221], v24 offset:2048
	ds_read_b128 v[222:225], v24 offset:3072
	s_mov_b32 m0, s13
	v_lshl_add_u64 v[88:89], s[76:77], 0, v[128:129]
	ds_read_b128 v[24:27], v146 offset:32768
	ds_read_b128 v[28:31], v146 offset:33792
	ds_read_b128 v[60:63], v146 offset:34816
	ds_read_b128 v[226:229], v146 offset:35840
	ds_read_b128 v[230:233], v146 offset:36864
	ds_read_b128 v[234:237], v146 offset:37888
	ds_read_b128 v[238:241], v146 offset:38912
	ds_read_b128 v[242:245], v146 offset:39936
	global_load_lds_dwordx4 v[88:89], off
	v_lshl_add_u64 v[88:89], s[76:77], 0, v[130:131]
	s_mov_b32 m0, s33
	s_nop 0
	global_load_lds_dwordx4 v[88:89], off
	s_waitcnt vmcnt(8)
	s_waitcnt lgkmcnt(0)
	s_barrier
	s_setprio 1
	s_waitcnt lgkmcnt(0)
	v_mfma_f32_16x16x32_bf16 v[64:67], v[8:11], v[24:27], v[64:67]
	v_mfma_f32_16x16x32_bf16 v[124:127], v[12:15], v[28:31], v[64:67]
	v_mfma_f32_16x16x32_bf16 v[64:67], v[16:19], v[24:27], v[68:71]
	v_mfma_f32_16x16x32_bf16 v[120:123], v[20:23], v[28:31], v[64:67]
	v_mfma_f32_16x16x32_bf16 v[64:67], v[8:11], v[60:63], v[72:75]
	v_mfma_f32_16x16x32_bf16 v[108:111], v[12:15], v[226:229], v[64:67]
	v_mfma_f32_16x16x32_bf16 v[64:67], v[16:19], v[60:63], v[76:79]
	v_mfma_f32_16x16x32_bf16 v[104:107], v[20:23], v[226:229], v[64:67]
	v_mfma_f32_16x16x32_bf16 v[64:67], v[8:11], v[230:233], v[80:83]
	v_mfma_f32_16x16x32_bf16 v[92:95], v[12:15], v[234:237], v[64:67]
	v_mfma_f32_16x16x32_bf16 v[64:67], v[16:19], v[230:233], v[84:87]
	v_mfma_f32_16x16x32_bf16 v[88:91], v[20:23], v[234:237], v[64:67]
	v_mfma_f32_16x16x32_bf16 v[64:67], v[8:11], v[238:241], v[96:99]
	v_mfma_f32_16x16x32_bf16 v[76:79], v[12:15], v[242:245], v[64:67]
	v_mfma_f32_16x16x32_bf16 v[64:67], v[16:19], v[238:241], v[100:103]
	v_mfma_f32_16x16x32_bf16 v[72:75], v[20:23], v[242:245], v[64:67]
	s_setprio 0
	s_setprio 1
	v_mfma_f32_16x16x32_bf16 v[64:67], v[210:213], v[24:27], v[112:115]
	v_mfma_f32_16x16x32_bf16 v[24:27], v[218:221], v[24:27], v[32:35]
	v_mfma_f32_16x16x32_bf16 v[112:115], v[222:225], v[28:31], v[24:27]
	v_mfma_f32_16x16x32_bf16 v[24:27], v[210:213], v[60:63], v[36:39]
	v_mfma_f32_16x16x32_bf16 v[100:103], v[214:217], v[226:229], v[24:27]
	v_mfma_f32_16x16x32_bf16 v[24:27], v[218:221], v[60:63], v[40:43]
	v_mfma_f32_16x16x32_bf16 v[96:99], v[222:225], v[226:229], v[24:27]
	v_mfma_f32_16x16x32_bf16 v[24:27], v[210:213], v[230:233], v[44:47]
	v_mfma_f32_16x16x32_bf16 v[84:87], v[214:217], v[234:237], v[24:27]
	v_mfma_f32_16x16x32_bf16 v[24:27], v[218:221], v[230:233], v[48:51]
	v_mfma_f32_16x16x32_bf16 v[80:83], v[222:225], v[234:237], v[24:27]
	v_mfma_f32_16x16x32_bf16 v[24:27], v[210:213], v[238:241], v[52:55]
	v_mfma_f32_16x16x32_bf16 v[68:71], v[214:217], v[242:245], v[24:27]
	v_mfma_f32_16x16x32_bf16 v[24:27], v[218:221], v[238:241], v[56:59]
	v_mfma_f32_16x16x32_bf16 v[116:119], v[214:217], v[28:31], v[64:67]
	s_barrier
; #define PG8_STAGE(bufoff, gbase, voff) do { _Pragma("unroll") for (int _i = 0; _i < 2; ++_i) \
;         __builtin_amdgcn_global_load_lds((const unsigned*)((const char*)(gbase) + (voff)[_i]), (PG8_LAS unsigned*)(lds + (bufoff) + ldsw + _i * 8192), 16, 0, 0); } while (0)
; #define PG8_LDA(dst, b, h) do { _Pragma("unroll") for (int m = 0; m < 4; ++m) _Pragma("unroll") for (int k = 0; k < 2; ++k) dst[m][k] = *(const PG8_LAS bf16x8*)(lds + PG8_SA(b, h) + aoff + m * 2048 + k * 1024); } while (0)
; #define PG8_LDB(dst, b, h) do { _Pragma("unroll") for (int n = 0; n < 2; ++n) _Pragma("unroll") for (int k = 0; k < 2; ++k) dst[n][k] = *(const PG8_LAS bf16x8*)(lds + PG8_SB(b, h) + boff + n * 2048 + k * 1024); } while (0)
; #define PG8_MMA(ai, bj, At, Bt) do { __builtin_amdgcn_s_setprio(1); _Pragma("unroll") for (int m = 0; m < 4; ++m) _Pragma("unroll") for (int n = 0; n < 2; ++n) _Pragma("unroll") for (int k = 0; k < 2; ++k) \
;         acc[ai][bj][m][n] = __builtin_amdgcn_mfma_f32_16x16x32_bf16(Bt[n][k], At[m][k], acc[ai][bj][m][n], 0, 0, 0); __builtin_amdgcn_s_setprio(0); } while (0)
; #define PG8_WAIT_V(n) asm volatile("s_waitcnt vmcnt(" #n ")" ::: "memory")
; template <class Epi, class Sched, bool ALIGN_EPI = false, bool SP2 = false>
; __device__ __forceinline__ void gemm_phase(PG8_LAS unsigned char* lds, const Gemm g, const Sched S, const Epi E) {
;     ...
;             PG8_LDB(B0, 0, 0); PG8_LDB(B1, 0, 1); PG8_SCHED; PG8_LDA(At, 0, 0); PG8_STAGE(PG8_SA(1, 1), a1 + hstep, voffA);
;             PG8_WAIT_V(8); PG8_WAIT_L(0); PG8_BAR; PG8_MMA(0, 0, At, B0); PG8_MMA(0, 1, At, B1); PG8_BAR; PG8_SCHED;
;             PG8_LDA(At, 0, 1); PG8_STAGE(PG8_SB(0, 0), b2, voffB); PG8_STAGE(PG8_SB(0, 1), b2 + hstep, voffB); PG8_STAGE(PG8_SA(0, 0), a2, voffA);
;             PG8_WAIT_V(8); PG8_WAIT_L(0); PG8_BAR; PG8_MMA(1, 0, At, B0); PG8_MMA(1, 1, At, B1); PG8_BAR; PG8_SCHED;
;             PG8_LDB(B0, 1, 0); PG8_LDB(B1, 1, 1); PG8_SCHED; PG8_LDA(At, 1, 0); PG8_STAGE(PG8_SA(0, 1), a2 + hstep, voffA);
;             PG8_WAIT_V(8); PG8_WAIT_L(0); PG8_BAR; PG8_MMA(0, 0, At, B0); PG8_MMA(0, 1, At, B1); PG8_BAR; PG8_SCHED;
;             PG8_LDA(At, 1, 1); PG8_STAGE(PG8_SB(1, 0), b3, voffB); PG8_STAGE(PG8_SB(1, 1), b3 + hstep, voffB); PG8_STAGE(PG8_SA(1, 0), a3, voffA);
;             PG8_WAIT_V(8); PG8_WAIT_L(0); PG8_BAR; PG8_MMA(1, 0, At, B0); PG8_MMA(1, 1, At, B1); PG8_BAR; PG8_SCHED;
	v_mfma_f32_16x16x32_bf16 v[64:67], v[222:225], v[242:245], v[24:27]
	s_setprio 0
	s_add_i32 s7, s7, s8
	s_nop 2
	v_lshl_add_u64 v[24:25], v[138:139], 0, s[18:19]
	s_mov_b32 m0, s7
	ds_read_b128 v[32:35], v146 offset:49152
	ds_read_b128 v[36:39], v146 offset:50176
	ds_read_b128 v[226:229], v146 offset:51200
	ds_read_b128 v[230:233], v146 offset:52224
	ds_read_b128 v[234:237], v146 offset:53248
	ds_read_b128 v[238:241], v146 offset:54272
	ds_read_b128 v[242:245], v146 offset:55296
	ds_read_b128 v[246:249], v146 offset:56320
	global_load_lds_dwordx4 v[24:25], off
	s_add_i32 m0, s7, 0x2000
	s_add_u32 s74, s74, 0x8080
	v_lshl_add_u64 v[24:25], v[186:187], 0, s[18:19]
	s_addc_u32 s75, s75, 0
	s_add_i32 s7, s11, s8
	global_load_lds_dwordx4 v[24:25], off
	v_lshl_add_u64 v[24:25], s[74:75], 0, v[128:129]
	s_mov_b32 m0, s7
	s_nop 0
	global_load_lds_dwordx4 v[24:25], off
	v_lshl_add_u64 v[24:25], s[74:75], 0, v[130:131]
	s_add_i32 m0, s7, 0x2000
	s_nop 0
	global_load_lds_dwordx4 v[24:25], off
	v_lshl_add_u64 v[24:25], v[250:251], 0, s[18:19]
	s_mov_b32 m0, s55
	s_nop 0
	global_load_lds_dwordx4 v[24:25], off
	v_lshl_add_u64 v[24:25], v[252:253], 0, s[18:19]
	s_mov_b32 m0, s58
	s_nop 0
	global_load_lds_dwordx4 v[24:25], off
	s_waitcnt vmcnt(8)
	s_waitcnt lgkmcnt(0)
	s_barrier
	s_setprio 1
	s_waitcnt lgkmcnt(0)
	v_mfma_f32_16x16x32_bf16 v[24:27], v[8:11], v[32:35], v[150:153]
	v_mfma_f32_16x16x32_bf16 v[60:63], v[12:15], v[36:39], v[24:27]
	v_mfma_f32_16x16x32_bf16 v[24:27], v[16:19], v[32:35], v[154:157]
	v_mfma_f32_16x16x32_bf16 v[56:59], v[20:23], v[36:39], v[24:27]
	v_mfma_f32_16x16x32_bf16 v[24:27], v[8:11], v[226:229], v[158:161]
	v_mfma_f32_16x16x32_bf16 v[44:47], v[12:15], v[230:233], v[24:27]
	v_mfma_f32_16x16x32_bf16 v[24:27], v[16:19], v[226:229], v[162:165]
	v_mfma_f32_16x16x32_bf16 v[40:43], v[20:23], v[230:233], v[24:27]
	v_mfma_f32_16x16x32_bf16 v[24:27], v[8:11], v[234:237], v[166:169]
	v_mfma_f32_16x16x32_bf16 v[0:3], v[8:11], v[242:245], v[0:3]
	v_mfma_f32_16x16x32_bf16 v[28:31], v[12:15], v[238:241], v[24:27]
	v_mfma_f32_16x16x32_bf16 v[24:27], v[16:19], v[234:237], v[170:173]
	v_mfma_f32_16x16x32_bf16 v[12:15], v[12:15], v[246:249], v[0:3]
	v_mfma_f32_16x16x32_bf16 v[0:3], v[16:19], v[242:245], v[4:7]
	v_mfma_f32_16x16x32_bf16 v[24:27], v[20:23], v[238:241], v[24:27]
	v_mfma_f32_16x16x32_bf16 v[8:11], v[20:23], v[246:249], v[0:3]
	s_setprio 0
	s_setprio 1
	v_mfma_f32_16x16x32_bf16 v[0:3], v[210:213], v[32:35], v[174:177]
	v_mfma_f32_16x16x32_bf16 v[52:55], v[214:217], v[36:39], v[0:3]
	v_mfma_f32_16x16x32_bf16 v[0:3], v[218:221], v[32:35], v[178:181]
	v_mfma_f32_16x16x32_bf16 v[48:51], v[222:225], v[36:39], v[0:3]
	v_mfma_f32_16x16x32_bf16 v[0:3], v[210:213], v[226:229], v[182:185]
	v_mfma_f32_16x16x32_bf16 v[36:39], v[214:217], v[230:233], v[0:3]
	v_mfma_f32_16x16x32_bf16 v[0:3], v[218:221], v[226:229], v[190:193]
	v_mfma_f32_16x16x32_bf16 v[32:35], v[222:225], v[230:233], v[0:3]
	v_mfma_f32_16x16x32_bf16 v[0:3], v[210:213], v[234:237], v[194:197]
	v_mfma_f32_16x16x32_bf16 v[20:23], v[214:217], v[238:241], v[0:3]
	v_mfma_f32_16x16x32_bf16 v[0:3], v[218:221], v[234:237], v[198:201]
	v_mfma_f32_16x16x32_bf16 v[16:19], v[222:225], v[238:241], v[0:3]
	v_mfma_f32_16x16x32_bf16 v[0:3], v[210:213], v[242:245], v[202:205]
	v_mfma_f32_16x16x32_bf16 v[4:7], v[214:217], v[246:249], v[0:3]
	v_mfma_f32_16x16x32_bf16 v[0:3], v[218:221], v[242:245], v[206:209]
	s_barrier
	v_mfma_f32_16x16x32_bf16 v[0:3], v[222:225], v[246:249], v[0:3]
	s_setprio 0
	s_andn2_b64 vcc, exec, s[46:47]
	s_cbranch_vccnz .LBB0_674
	s_barrier

; #define PG8_STAGE(bufoff, gbase, voff) do { _Pragma("unroll") for (int _i = 0; _i < 2; ++_i) \
;         __builtin_amdgcn_global_load_lds((const unsigned*)((const char*)(gbase) + (voff)[_i]), (PG8_LAS unsigned*)(lds + (bufoff) + ldsw + _i * 8192), 16, 0, 0); } while (0)
; #define PG8_LDA(dst, b, h) do { _Pragma("unroll") for (int m = 0; m < 4; ++m) _Pragma("unroll") for (int k = 0; k < 2; ++k) dst[m][k] = *(const PG8_LAS bf16x8*)(lds + PG8_SA(b, h) + aoff + m * 2048 + k * 1024); } while (0)
; #define PG8_LDB(dst, b, h) do { _Pragma("unroll") for (int n = 0; n < 2; ++n) _Pragma("unroll") for (int k = 0; k < 2; ++k) dst[n][k] = *(const PG8_LAS bf16x8*)(lds + PG8_SB(b, h) + boff + n * 2048 + k * 1024); } while (0)
; #define PG8_MMA(ai, bj, At, Bt) do { __builtin_amdgcn_s_setprio(1); _Pragma("unroll") for (int m = 0; m < 4; ++m) _Pragma("unroll") for (int n = 0; n < 2; ++n) _Pragma("unroll") for (int k = 0; k < 2; ++k) \
;         acc[ai][bj][m][n] = __builtin_amdgcn_mfma_f32_16x16x32_bf16(Bt[n][k], At[m][k], acc[ai][bj][m][n], 0, 0, 0); __builtin_amdgcn_s_setprio(0); } while (0)
; #define PG8_WAIT_V(n) asm volatile("s_waitcnt vmcnt(" #n ")" ::: "memory")
; template <class Epi, class Sched, bool ALIGN_EPI = false, bool SP2 = false>
; __device__ __forceinline__ void gemm_phase(PG8_LAS unsigned char* lds, const Gemm g, const Sched S, const Epi E) {
;     ...
;             PG8_LDB(B0, 0, 0); PG8_LDB(B1, 0, 1); PG8_SCHED; PG8_LDA(At, 0, 0); PG8_STAGE(PG8_SA(1, 1), a1 + hstep, voffA);
;             PG8_WAIT_V(8); PG8_WAIT_L(0); PG8_BAR; PG8_MMA(0, 0, At, B0); PG8_MMA(0, 1, At, B1); PG8_BAR; PG8_SCHED;
;             PG8_LDA(At, 0, 1); PG8_STAGE(PG8_SB(0, 0), b2, voffB); PG8_STAGE(PG8_SB(0, 1), b2 + hstep, voffB); PG8_STAGE(PG8_SA(0, 0), a2, voffA);
;             PG8_WAIT_V(8); PG8_WAIT_L(0); PG8_BAR; PG8_MMA(1, 0, At, B0); PG8_MMA(1, 1, At, B1); PG8_BAR; PG8_SCHED;
;             PG8_LDB(B0, 1, 0); PG8_LDB(B1, 1, 1); PG8_SCHED; PG8_LDA(At, 1, 0); PG8_STAGE(PG8_SA(0, 1), a2 + hstep, voffA);
;             PG8_WAIT_V(8); PG8_WAIT_L(0); PG8_BAR; PG8_MMA(0, 0, At, B0); PG8_MMA(0, 1, At, B1); PG8_BAR; PG8_SCHED;
;             PG8_LDA(At, 1, 1); PG8_STAGE(PG8_SB(1, 0), b3, voffB); PG8_STAGE(PG8_SB(1, 1), b3 + hstep, voffB); PG8_STAGE(PG8_SA(1, 0), a3, voffA);
;             PG8_WAIT_V(8); PG8_WAIT_L(0); PG8_BAR; PG8_MMA(1, 0, At, B0); PG8_MMA(1, 1, At, B1); PG8_BAR; PG8_SCHED;
.LBB0_898:
	v_add_u32_e32 v1, s65, v170
	ds_read_b128 v[120:123], v1
	ds_read_b128 v[176:179], v1 offset:1024
	ds_read_b128 v[180:183], v1 offset:2048
	ds_read_b128 v[190:193], v1 offset:3072
	v_add_u32_e32 v1, s68, v170
	s_add_u32 s6, s66, s70
	ds_read_b128 v[194:197], v1
	ds_read_b128 v[198:201], v1 offset:1024
	ds_read_b128 v[202:205], v1 offset:2048
	ds_read_b128 v[206:209], v1 offset:3072
	s_addc_u32 s7, s67, s71
	s_add_u32 s6, s6, 0x100
	s_addc_u32 s7, s7, 0
	s_add_u32 s14, s74, s70
	s_addc_u32 s15, s75, s71
	s_cmpk_eq_i32 s70, 0x700
	s_cselect_b32 s11, s51, s7
	s_cselect_b32 s10, s72, s6
	s_cselect_b32 s7, s45, s15
	s_cselect_b32 s6, s73, s14
	v_lshl_add_u64 v[2:3], v[138:139], 0, s[70:71]
	s_add_i32 m0, s9, 0xc000
	ds_read_b128 v[210:213], v173
	ds_read_b128 v[214:217], v173 offset:1024
	ds_read_b128 v[218:221], v173 offset:2048
	ds_read_b128 v[222:225], v173 offset:3072
	ds_read_b128 v[226:229], v173 offset:4096
	ds_read_b128 v[230:233], v173 offset:5120
	ds_read_b128 v[234:237], v173 offset:6144
	ds_read_b128 v[238:241], v173 offset:7168
	global_load_lds_dwordx4 v[2:3], off
	v_lshl_add_u64 v[2:3], v[164:165], 0, s[70:71]
	s_add_i32 m0, s9, 0xe000
	s_nop 0
	global_load_lds_dwordx4 v[2:3], off
	s_waitcnt vmcnt(8)
	s_waitcnt lgkmcnt(0)
	s_barrier
	s_setprio 1
	s_waitcnt lgkmcnt(0)
	v_mfma_f32_16x16x32_bf16 v[144:147], v[120:123], v[210:213], v[144:147]
	v_mfma_f32_16x16x32_bf16 v[140:143], v[180:183], v[210:213], v[140:143]
	v_mfma_f32_16x16x32_bf16 v[112:115], v[120:123], v[218:221], v[112:115]
	v_mfma_f32_16x16x32_bf16 v[108:111], v[180:183], v[218:221], v[108:111]
	v_mfma_f32_16x16x32_bf16 v[96:99], v[120:123], v[226:229], v[96:99]
	v_mfma_f32_16x16x32_bf16 v[92:95], v[180:183], v[226:229], v[92:95]
	v_mfma_f32_16x16x32_bf16 v[80:83], v[120:123], v[234:237], v[80:83]
	v_mfma_f32_16x16x32_bf16 v[76:79], v[180:183], v[234:237], v[76:79]
	v_mfma_f32_16x16x32_bf16 v[144:147], v[176:179], v[214:217], v[144:147]
	v_mfma_f32_16x16x32_bf16 v[140:143], v[190:193], v[214:217], v[140:143]
	v_mfma_f32_16x16x32_bf16 v[112:115], v[176:179], v[222:225], v[112:115]
	v_mfma_f32_16x16x32_bf16 v[108:111], v[190:193], v[222:225], v[108:111]
	v_mfma_f32_16x16x32_bf16 v[96:99], v[176:179], v[230:233], v[96:99]
	v_mfma_f32_16x16x32_bf16 v[92:95], v[190:193], v[230:233], v[92:95]
	v_mfma_f32_16x16x32_bf16 v[80:83], v[176:179], v[238:241], v[80:83]
	v_mfma_f32_16x16x32_bf16 v[76:79], v[190:193], v[238:241], v[76:79]
	s_setprio 0
	s_setprio 1
	v_mfma_f32_16x16x32_bf16 v[124:127], v[194:197], v[210:213], v[124:127]
	v_mfma_f32_16x16x32_bf16 v[116:119], v[202:205], v[210:213], v[116:119]
	v_mfma_f32_16x16x32_bf16 v[104:107], v[194:197], v[218:221], v[104:107]
	v_mfma_f32_16x16x32_bf16 v[100:103], v[202:205], v[218:221], v[100:103]
	v_mfma_f32_16x16x32_bf16 v[88:91], v[194:197], v[226:229], v[88:91]
	v_mfma_f32_16x16x32_bf16 v[84:87], v[202:205], v[226:229], v[84:87]
	v_mfma_f32_16x16x32_bf16 v[72:75], v[194:197], v[234:237], v[72:75]
	v_mfma_f32_16x16x32_bf16 v[68:71], v[202:205], v[234:237], v[68:71]
	v_mfma_f32_16x16x32_bf16 v[124:127], v[198:201], v[214:217], v[124:127]
	v_mfma_f32_16x16x32_bf16 v[116:119], v[206:209], v[214:217], v[116:119]
	v_mfma_f32_16x16x32_bf16 v[104:107], v[198:201], v[222:225], v[104:107]
	v_mfma_f32_16x16x32_bf16 v[100:103], v[206:209], v[222:225], v[100:103]
	v_mfma_f32_16x16x32_bf16 v[88:91], v[198:201], v[230:233], v[88:91]
	v_mfma_f32_16x16x32_bf16 v[84:87], v[206:209], v[230:233], v[84:87]
	v_mfma_f32_16x16x32_bf16 v[72:75], v[198:201], v[238:241], v[72:75]
	s_barrier
	v_mfma_f32_16x16x32_bf16 v[68:71], v[206:209], v[238:241], v[68:71]
	s_setprio 0
	s_add_i32 s14, s65, s8
	v_lshl_add_u64 v[166:167], s[6:7], 0, v[150:151]
	s_mov_b32 m0, s14
	ds_read_b128 v[210:213], v173 offset:16384
	ds_read_b128 v[214:217], v173 offset:17408
	ds_read_b128 v[218:221], v173 offset:18432
	ds_read_b128 v[222:225], v173 offset:19456
	ds_read_b128 v[226:229], v173 offset:20480
	ds_read_b128 v[230:233], v173 offset:21504
	ds_read_b128 v[234:237], v173 offset:22528
	ds_read_b128 v[238:241], v173 offset:23552
	global_load_lds_dwordx4 v[166:167], off
	s_add_i32 m0, s14, 0x2000
	s_add_u32 s14, s6, 0x40000
	v_lshl_add_u64 v[184:185], s[6:7], 0, v[154:155]
	s_addc_u32 s15, s7, 0
	s_add_i32 s77, s68, s8
	global_load_lds_dwordx4 v[184:185], off
	v_lshl_add_u64 v[2:3], s[14:15], 0, v[150:151]
	s_mov_b32 m0, s77
	v_lshl_add_u64 v[186:187], s[10:11], 0, v[148:149]
	global_load_lds_dwordx4 v[2:3], off
	v_lshl_add_u64 v[2:3], s[14:15], 0, v[154:155]
	s_add_i32 m0, s77, 0x2000
	v_lshl_add_u64 v[242:243], s[10:11], 0, v[152:153]
	global_load_lds_dwordx4 v[2:3], off
	s_mov_b32 m0, s9
	s_nop 0
	global_load_lds_dwordx4 v[186:187], off
	s_mov_b32 m0, s12
	s_nop 0
	global_load_lds_dwordx4 v[242:243], off
	s_waitcnt vmcnt(8)
	s_waitcnt lgkmcnt(0)
	s_barrier
; #define PG8_STAGE(bufoff, gbase, voff) do { _Pragma("unroll") for (int _i = 0; _i < 2; ++_i) \
;         __builtin_amdgcn_global_load_lds((const unsigned*)((const char*)(gbase) + (voff)[_i]), (PG8_LAS unsigned*)(lds + (bufoff) + ldsw + _i * 8192), 16, 0, 0); } while (0)
; #define PG8_LDA(dst, b, h) do { _Pragma("unroll") for (int m = 0; m < 4; ++m) _Pragma("unroll") for (int k = 0; k < 2; ++k) dst[m][k] = *(const PG8_LAS bf16x8*)(lds + PG8_SA(b, h) + aoff + m * 2048 + k * 1024); } while (0)
; #define PG8_LDB(dst, b, h) do { _Pragma("unroll") for (int n = 0; n < 2; ++n) _Pragma("unroll") for (int k = 0; k < 2; ++k) dst[n][k] = *(const PG8_LAS bf16x8*)(lds + PG8_SB(b, h) + boff + n * 2048 + k * 1024); } while (0)
; #define PG8_MMA(ai, bj, At, Bt) do { __builtin_amdgcn_s_setprio(1); _Pragma("unroll") for (int m = 0; m < 4; ++m) _Pragma("unroll") for (int n = 0; n < 2; ++n) _Pragma("unroll") for (int k = 0; k < 2; ++k) \
;         acc[ai][bj][m][n] = __builtin_amdgcn_mfma_f32_16x16x32_bf16(Bt[n][k], At[m][k], acc[ai][bj][m][n], 0, 0, 0); __builtin_amdgcn_s_setprio(0); } while (0)
; #define PG8_WAIT_V(n) asm volatile("s_waitcnt vmcnt(" #n ")" ::: "memory")
; template <class Epi, class Sched, bool ALIGN_EPI = false, bool SP2 = false>
; __device__ __forceinline__ void gemm_phase(PG8_LAS unsigned char* lds, const Gemm g, const Sched S, const Epi E) {
;     ...
;             PG8_LDB(B0, 0, 0); PG8_LDB(B1, 0, 1); PG8_SCHED; PG8_LDA(At, 0, 0); PG8_STAGE(PG8_SA(1, 1), a1 + hstep, voffA);
;             PG8_WAIT_V(8); PG8_WAIT_L(0); PG8_BAR; PG8_MMA(0, 0, At, B0); PG8_MMA(0, 1, At, B1); PG8_BAR; PG8_SCHED;
;             PG8_LDA(At, 0, 1); PG8_STAGE(PG8_SB(0, 0), b2, voffB); PG8_STAGE(PG8_SB(0, 1), b2 + hstep, voffB); PG8_STAGE(PG8_SA(0, 0), a2, voffA);
;             PG8_WAIT_V(8); PG8_WAIT_L(0); PG8_BAR; PG8_MMA(1, 0, At, B0); PG8_MMA(1, 1, At, B1); PG8_BAR; PG8_SCHED;
;             PG8_LDB(B0, 1, 0); PG8_LDB(B1, 1, 1); PG8_SCHED; PG8_LDA(At, 1, 0); PG8_STAGE(PG8_SA(0, 1), a2 + hstep, voffA);
;             PG8_WAIT_V(8); PG8_WAIT_L(0); PG8_BAR; PG8_MMA(0, 0, At, B0); PG8_MMA(0, 1, At, B1); PG8_BAR; PG8_SCHED;
;             PG8_LDA(At, 1, 1); PG8_STAGE(PG8_SB(1, 0), b3, voffB); PG8_STAGE(PG8_SB(1, 1), b3 + hstep, voffB); PG8_STAGE(PG8_SA(1, 0), a3, voffA);
;             PG8_WAIT_V(8); PG8_WAIT_L(0); PG8_BAR; PG8_MMA(1, 0, At, B0); PG8_MMA(1, 1, At, B1); PG8_BAR; PG8_SCHED;
	s_setprio 1
	s_waitcnt lgkmcnt(0)
	v_mfma_f32_16x16x32_bf16 v[64:67], v[120:123], v[210:213], v[64:67]
	v_mfma_f32_16x16x32_bf16 v[60:63], v[180:183], v[210:213], v[60:63]
	v_mfma_f32_16x16x32_bf16 v[48:51], v[120:123], v[218:221], v[48:51]
	v_mfma_f32_16x16x32_bf16 v[44:47], v[180:183], v[218:221], v[44:47]
	v_mfma_f32_16x16x32_bf16 v[32:35], v[120:123], v[226:229], v[32:35]
	v_mfma_f32_16x16x32_bf16 v[28:31], v[180:183], v[226:229], v[28:31]
	v_mfma_f32_16x16x32_bf16 v[16:19], v[120:123], v[234:237], v[16:19]
	v_mfma_f32_16x16x32_bf16 v[12:15], v[180:183], v[234:237], v[12:15]
	v_mfma_f32_16x16x32_bf16 v[64:67], v[176:179], v[214:217], v[64:67]
	v_mfma_f32_16x16x32_bf16 v[60:63], v[190:193], v[214:217], v[60:63]
	v_mfma_f32_16x16x32_bf16 v[48:51], v[176:179], v[222:225], v[48:51]
	v_mfma_f32_16x16x32_bf16 v[44:47], v[190:193], v[222:225], v[44:47]
	v_mfma_f32_16x16x32_bf16 v[32:35], v[176:179], v[230:233], v[32:35]
	v_mfma_f32_16x16x32_bf16 v[28:31], v[190:193], v[230:233], v[28:31]
	v_mfma_f32_16x16x32_bf16 v[16:19], v[176:179], v[238:241], v[16:19]
	v_mfma_f32_16x16x32_bf16 v[12:15], v[190:193], v[238:241], v[12:15]
	s_setprio 0
	s_setprio 1
	v_mfma_f32_16x16x32_bf16 v[56:59], v[194:197], v[210:213], v[56:59]
	v_mfma_f32_16x16x32_bf16 v[52:55], v[202:205], v[210:213], v[52:55]
	v_mfma_f32_16x16x32_bf16 v[40:43], v[194:197], v[218:221], v[40:43]
	v_mfma_f32_16x16x32_bf16 v[36:39], v[202:205], v[218:221], v[36:39]
	v_mfma_f32_16x16x32_bf16 v[24:27], v[194:197], v[226:229], v[24:27]
	v_mfma_f32_16x16x32_bf16 v[20:23], v[202:205], v[226:229], v[20:23]
	v_mfma_f32_16x16x32_bf16 v[8:11], v[194:197], v[234:237], v[8:11]
	v_mfma_f32_16x16x32_bf16 v[2:5], v[202:205], v[234:237], v[4:7]
	v_mfma_f32_16x16x32_bf16 v[56:59], v[198:201], v[214:217], v[56:59]
	v_mfma_f32_16x16x32_bf16 v[52:55], v[206:209], v[214:217], v[52:55]
	v_mfma_f32_16x16x32_bf16 v[40:43], v[198:201], v[222:225], v[40:43]
	v_mfma_f32_16x16x32_bf16 v[36:39], v[206:209], v[222:225], v[36:39]
	v_mfma_f32_16x16x32_bf16 v[24:27], v[198:201], v[230:233], v[24:27]
	v_mfma_f32_16x16x32_bf16 v[20:23], v[206:209], v[230:233], v[20:23]
	v_mfma_f32_16x16x32_bf16 v[8:11], v[198:201], v[238:241], v[8:11]
	s_barrier
	v_mfma_f32_16x16x32_bf16 v[2:5], v[206:209], v[238:241], v[2:5]
	s_setprio 0
	s_add_i32 s14, 0, 0x18000
	v_add_u32_e32 v1, s14, v170
	s_add_i32 s15, 0, 0x1c000
	ds_read_b128 v[120:123], v1
	ds_read_b128 v[176:179], v1 offset:1024
	ds_read_b128 v[180:183], v1 offset:2048
	ds_read_b128 v[190:193], v1 offset:3072
	v_add_u32_e32 v1, s15, v170
	ds_read_b128 v[194:197], v1
	ds_read_b128 v[198:201], v1 offset:1024
	ds_read_b128 v[202:205], v1 offset:2048
	ds_read_b128 v[206:209], v1 offset:3072
	s_add_u32 s10, s10, 0x40000
	s_addc_u32 s11, s11, 0
	s_mov_b32 m0, s13
	v_lshl_add_u64 v[6:7], s[10:11], 0, v[148:149]
	ds_read_b128 v[210:213], v173 offset:32768
	ds_read_b128 v[214:217], v173 offset:33792
	ds_read_b128 v[218:221], v173 offset:34816
	ds_read_b128 v[222:225], v173 offset:35840
	ds_read_b128 v[226:229], v173 offset:36864
	ds_read_b128 v[230:233], v173 offset:37888
	ds_read_b128 v[234:237], v173 offset:38912
	ds_read_b128 v[238:241], v173 offset:39936
	global_load_lds_dwordx4 v[6:7], off
	v_lshl_add_u64 v[6:7], s[10:11], 0, v[152:153]
	s_mov_b32 m0, s33
	s_nop 0
	global_load_lds_dwordx4 v[6:7], off
	s_waitcnt vmcnt(8)
	s_waitcnt lgkmcnt(0)
	s_barrier
	s_setprio 1
	s_waitcnt lgkmcnt(0)
	v_mfma_f32_16x16x32_bf16 v[144:147], v[120:123], v[210:213], v[144:147]
	v_mfma_f32_16x16x32_bf16 v[140:143], v[180:183], v[210:213], v[140:143]
	v_mfma_f32_16x16x32_bf16 v[112:115], v[120:123], v[218:221], v[112:115]
	v_mfma_f32_16x16x32_bf16 v[108:111], v[180:183], v[218:221], v[108:111]
	v_mfma_f32_16x16x32_bf16 v[96:99], v[120:123], v[226:229], v[96:99]
	v_mfma_f32_16x16x32_bf16 v[92:95], v[180:183], v[226:229], v[92:95]
	v_mfma_f32_16x16x32_bf16 v[80:83], v[120:123], v[234:237], v[80:83]
	v_mfma_f32_16x16x32_bf16 v[76:79], v[180:183], v[234:237], v[76:79]
	v_mfma_f32_16x16x32_bf16 v[144:147], v[176:179], v[214:217], v[144:147]
	v_mfma_f32_16x16x32_bf16 v[140:143], v[190:193], v[214:217], v[140:143]
	v_mfma_f32_16x16x32_bf16 v[112:115], v[176:179], v[222:225], v[112:115]
	v_mfma_f32_16x16x32_bf16 v[108:111], v[190:193], v[222:225], v[108:111]
	v_mfma_f32_16x16x32_bf16 v[96:99], v[176:179], v[230:233], v[96:99]
	v_mfma_f32_16x16x32_bf16 v[92:95], v[190:193], v[230:233], v[92:95]
	v_mfma_f32_16x16x32_bf16 v[80:83], v[176:179], v[238:241], v[80:83]
	v_mfma_f32_16x16x32_bf16 v[76:79], v[190:193], v[238:241], v[76:79]
	s_setprio 0
	s_setprio 1
	v_mfma_f32_16x16x32_bf16 v[124:127], v[194:197], v[210:213], v[124:127]
	v_mfma_f32_16x16x32_bf16 v[116:119], v[202:205], v[210:213], v[116:119]
	v_mfma_f32_16x16x32_bf16 v[104:107], v[194:197], v[218:221], v[104:107]
	v_mfma_f32_16x16x32_bf16 v[100:103], v[202:205], v[218:221], v[100:103]
	v_mfma_f32_16x16x32_bf16 v[88:91], v[194:197], v[226:229], v[88:91]
	v_mfma_f32_16x16x32_bf16 v[84:87], v[202:205], v[226:229], v[84:87]
	v_mfma_f32_16x16x32_bf16 v[72:75], v[194:197], v[234:237], v[72:75]
	v_mfma_f32_16x16x32_bf16 v[68:71], v[202:205], v[234:237], v[68:71]
	v_mfma_f32_16x16x32_bf16 v[124:127], v[198:201], v[214:217], v[124:127]
	v_mfma_f32_16x16x32_bf16 v[116:119], v[206:209], v[214:217], v[116:119]
	v_mfma_f32_16x16x32_bf16 v[104:107], v[198:201], v[222:225], v[104:107]
	v_mfma_f32_16x16x32_bf16 v[100:103], v[206:209], v[222:225], v[100:103]
	v_mfma_f32_16x16x32_bf16 v[88:91], v[198:201], v[230:233], v[88:91]
	v_mfma_f32_16x16x32_bf16 v[84:87], v[206:209], v[230:233], v[84:87]
	v_mfma_f32_16x16x32_bf16 v[72:75], v[198:201], v[238:241], v[72:75]
	s_barrier
; #define PG8_STAGE(bufoff, gbase, voff) do { _Pragma("unroll") for (int _i = 0; _i < 2; ++_i) \
;         __builtin_amdgcn_global_load_lds((const unsigned*)((const char*)(gbase) + (voff)[_i]), (PG8_LAS unsigned*)(lds + (bufoff) + ldsw + _i * 8192), 16, 0, 0); } while (0)
; #define PG8_LDA(dst, b, h) do { _Pragma("unroll") for (int m = 0; m < 4; ++m) _Pragma("unroll") for (int k = 0; k < 2; ++k) dst[m][k] = *(const PG8_LAS bf16x8*)(lds + PG8_SA(b, h) + aoff + m * 2048 + k * 1024); } while (0)
; #define PG8_LDB(dst, b, h) do { _Pragma("unroll") for (int n = 0; n < 2; ++n) _Pragma("unroll") for (int k = 0; k < 2; ++k) dst[n][k] = *(const PG8_LAS bf16x8*)(lds + PG8_SB(b, h) + boff + n * 2048 + k * 1024); } while (0)
; #define PG8_MMA(ai, bj, At, Bt) do { __builtin_amdgcn_s_setprio(1); _Pragma("unroll") for (int m = 0; m < 4; ++m) _Pragma("unroll") for (int n = 0; n < 2; ++n) _Pragma("unroll") for (int k = 0; k < 2; ++k) \
;         acc[ai][bj][m][n] = __builtin_amdgcn_mfma_f32_16x16x32_bf16(Bt[n][k], At[m][k], acc[ai][bj][m][n], 0, 0, 0); __builtin_amdgcn_s_setprio(0); } while (0)
; #define PG8_WAIT_V(n) asm volatile("s_waitcnt vmcnt(" #n ")" ::: "memory")
; template <class Epi, class Sched, bool ALIGN_EPI = false, bool SP2 = false>
; __device__ __forceinline__ void gemm_phase(PG8_LAS unsigned char* lds, const Gemm g, const Sched S, const Epi E) {
;     ...
;             PG8_LDB(B0, 0, 0); PG8_LDB(B1, 0, 1); PG8_SCHED; PG8_LDA(At, 0, 0); PG8_STAGE(PG8_SA(1, 1), a1 + hstep, voffA);
;             PG8_WAIT_V(8); PG8_WAIT_L(0); PG8_BAR; PG8_MMA(0, 0, At, B0); PG8_MMA(0, 1, At, B1); PG8_BAR; PG8_SCHED;
;             PG8_LDA(At, 0, 1); PG8_STAGE(PG8_SB(0, 0), b2, voffB); PG8_STAGE(PG8_SB(0, 1), b2 + hstep, voffB); PG8_STAGE(PG8_SA(0, 0), a2, voffA);
;             PG8_WAIT_V(8); PG8_WAIT_L(0); PG8_BAR; PG8_MMA(1, 0, At, B0); PG8_MMA(1, 1, At, B1); PG8_BAR; PG8_SCHED;
;             PG8_LDB(B0, 1, 0); PG8_LDB(B1, 1, 1); PG8_SCHED; PG8_LDA(At, 1, 0); PG8_STAGE(PG8_SA(0, 1), a2 + hstep, voffA);
;             PG8_WAIT_V(8); PG8_WAIT_L(0); PG8_BAR; PG8_MMA(0, 0, At, B0); PG8_MMA(0, 1, At, B1); PG8_BAR; PG8_SCHED;
;             PG8_LDA(At, 1, 1); PG8_STAGE(PG8_SB(1, 0), b3, voffB); PG8_STAGE(PG8_SB(1, 1), b3 + hstep, voffB); PG8_STAGE(PG8_SA(1, 0), a3, voffA);
;             PG8_WAIT_V(8); PG8_WAIT_L(0); PG8_BAR; PG8_MMA(1, 0, At, B0); PG8_MMA(1, 1, At, B1); PG8_BAR; PG8_SCHED;
	v_mfma_f32_16x16x32_bf16 v[68:71], v[206:209], v[238:241], v[68:71]
	s_setprio 0
	s_add_i32 s10, s14, s8
	v_lshl_add_u64 v[6:7], v[166:167], 0, s[18:19]
	s_mov_b32 m0, s10
	ds_read_b128 v[210:213], v173 offset:49152
	ds_read_b128 v[214:217], v173 offset:50176
	ds_read_b128 v[218:221], v173 offset:51200
	ds_read_b128 v[222:225], v173 offset:52224
	ds_read_b128 v[226:229], v173 offset:53248
	ds_read_b128 v[230:233], v173 offset:54272
	ds_read_b128 v[234:237], v173 offset:55296
	ds_read_b128 v[238:241], v173 offset:56320
	global_load_lds_dwordx4 v[6:7], off
	s_add_i32 m0, s10, 0x2000
	s_add_u32 s6, s6, 0x40080
	v_lshl_add_u64 v[6:7], v[184:185], 0, s[18:19]
	s_addc_u32 s7, s7, 0
	s_add_i32 s10, s15, s8
	global_load_lds_dwordx4 v[6:7], off
	v_lshl_add_u64 v[6:7], s[6:7], 0, v[150:151]
	s_mov_b32 m0, s10
	s_nop 0
	global_load_lds_dwordx4 v[6:7], off
	v_lshl_add_u64 v[6:7], s[6:7], 0, v[154:155]
	s_add_i32 m0, s10, 0x2000
	s_nop 0
	global_load_lds_dwordx4 v[6:7], off
	v_lshl_add_u64 v[6:7], v[186:187], 0, s[18:19]
	s_mov_b32 m0, s55
	s_nop 0
	global_load_lds_dwordx4 v[6:7], off
	v_lshl_add_u64 v[6:7], v[242:243], 0, s[18:19]
	s_mov_b32 m0, s58
	s_nop 0
	global_load_lds_dwordx4 v[6:7], off
	s_waitcnt vmcnt(8)
	s_waitcnt lgkmcnt(0)
	s_barrier
	s_setprio 1
	s_waitcnt lgkmcnt(0)
	v_mfma_f32_16x16x32_bf16 v[64:67], v[120:123], v[210:213], v[64:67]
	v_mfma_f32_16x16x32_bf16 v[60:63], v[180:183], v[210:213], v[60:63]
	v_mfma_f32_16x16x32_bf16 v[48:51], v[120:123], v[218:221], v[48:51]
	v_mfma_f32_16x16x32_bf16 v[44:47], v[180:183], v[218:221], v[44:47]
	v_mfma_f32_16x16x32_bf16 v[32:35], v[120:123], v[226:229], v[32:35]
	v_mfma_f32_16x16x32_bf16 v[28:31], v[180:183], v[226:229], v[28:31]
	v_mfma_f32_16x16x32_bf16 v[16:19], v[120:123], v[234:237], v[16:19]
	v_mfma_f32_16x16x32_bf16 v[12:15], v[180:183], v[234:237], v[12:15]
	v_mfma_f32_16x16x32_bf16 v[64:67], v[176:179], v[214:217], v[64:67]
	v_mfma_f32_16x16x32_bf16 v[60:63], v[190:193], v[214:217], v[60:63]
	v_mfma_f32_16x16x32_bf16 v[48:51], v[176:179], v[222:225], v[48:51]
	v_mfma_f32_16x16x32_bf16 v[44:47], v[190:193], v[222:225], v[44:47]
	v_mfma_f32_16x16x32_bf16 v[32:35], v[176:179], v[230:233], v[32:35]
	v_mfma_f32_16x16x32_bf16 v[28:31], v[190:193], v[230:233], v[28:31]
	v_mfma_f32_16x16x32_bf16 v[16:19], v[176:179], v[238:241], v[16:19]
	v_mfma_f32_16x16x32_bf16 v[12:15], v[190:193], v[238:241], v[12:15]
	s_setprio 0
	s_setprio 1
	v_mfma_f32_16x16x32_bf16 v[56:59], v[194:197], v[210:213], v[56:59]
	v_mfma_f32_16x16x32_bf16 v[52:55], v[202:205], v[210:213], v[52:55]
	v_mfma_f32_16x16x32_bf16 v[40:43], v[194:197], v[218:221], v[40:43]
	v_mfma_f32_16x16x32_bf16 v[36:39], v[202:205], v[218:221], v[36:39]
	v_mfma_f32_16x16x32_bf16 v[24:27], v[194:197], v[226:229], v[24:27]
	v_mfma_f32_16x16x32_bf16 v[20:23], v[202:205], v[226:229], v[20:23]
	v_mfma_f32_16x16x32_bf16 v[6:9], v[194:197], v[234:237], v[8:11]
	v_mfma_f32_16x16x32_bf16 v[2:5], v[202:205], v[234:237], v[2:5]
	v_mfma_f32_16x16x32_bf16 v[56:59], v[198:201], v[214:217], v[56:59]
	v_mfma_f32_16x16x32_bf16 v[52:55], v[206:209], v[214:217], v[52:55]
	v_mfma_f32_16x16x32_bf16 v[40:43], v[198:201], v[222:225], v[40:43]
	v_mfma_f32_16x16x32_bf16 v[36:39], v[206:209], v[222:225], v[36:39]
	v_mfma_f32_16x16x32_bf16 v[24:27], v[198:201], v[230:233], v[24:27]
	v_mfma_f32_16x16x32_bf16 v[20:23], v[206:209], v[230:233], v[20:23]
	v_mfma_f32_16x16x32_bf16 v[8:11], v[198:201], v[238:241], v[6:9]
	s_barrier
	v_mfma_f32_16x16x32_bf16 v[4:7], v[206:209], v[238:241], v[2:5]
	s_setprio 0
	s_add_i32 s76, s76, 2
	s_add_u32 s70, s70, 0x100
	s_addc_u32 s71, s71, 0
	s_cmp_gt_u32 s76, 13
	s_cbranch_scc1 .LBB0_901

; #define PG8_STAGE(bufoff, gbase, voff) do { _Pragma("unroll") for (int _i = 0; _i < 2; ++_i) \
;         __builtin_amdgcn_global_load_lds((const unsigned*)((const char*)(gbase) + (voff)[_i]), (PG8_LAS unsigned*)(lds + (bufoff) + ldsw + _i * 8192), 16, 0, 0); } while (0)
; #define PG8_LDA(dst, b, h) do { _Pragma("unroll") for (int m = 0; m < 4; ++m) _Pragma("unroll") for (int k = 0; k < 2; ++k) dst[m][k] = *(const PG8_LAS bf16x8*)(lds + PG8_SA(b, h) + aoff + m * 2048 + k * 1024); } while (0)
; #define PG8_LDB(dst, b, h) do { _Pragma("unroll") for (int n = 0; n < 2; ++n) _Pragma("unroll") for (int k = 0; k < 2; ++k) dst[n][k] = *(const PG8_LAS bf16x8*)(lds + PG8_SB(b, h) + boff + n * 2048 + k * 1024); } while (0)
; #define PG8_MMA(ai, bj, At, Bt) do { __builtin_amdgcn_s_setprio(1); _Pragma("unroll") for (int m = 0; m < 4; ++m) _Pragma("unroll") for (int n = 0; n < 2; ++n) _Pragma("unroll") for (int k = 0; k < 2; ++k) \
;         acc[ai][bj][m][n] = __builtin_amdgcn_mfma_f32_16x16x32_bf16(Bt[n][k], At[m][k], acc[ai][bj][m][n], 0, 0, 0); __builtin_amdgcn_s_setprio(0); } while (0)
; #define PG8_WAIT_V(n) asm volatile("s_waitcnt vmcnt(" #n ")" ::: "memory")
; template <class Epi, class Sched, bool ALIGN_EPI = false, bool SP2 = false>
; __device__ __forceinline__ void gemm_phase(PG8_LAS unsigned char* lds, const Gemm g, const Sched S, const Epi E) {
;     ...
;             PG8_LDB(B0, 0, 0); PG8_LDB(B1, 0, 1); PG8_SCHED; PG8_LDA(At, 0, 0); PG8_STAGE(PG8_SA(1, 1), a1 + hstep, voffA);
;             PG8_WAIT_V(8); PG8_WAIT_L(0); PG8_BAR; PG8_MMA(0, 0, At, B0); PG8_MMA(0, 1, At, B1); PG8_BAR; PG8_SCHED;
;             PG8_LDA(At, 0, 1); PG8_STAGE(PG8_SB(0, 0), b2, voffB); PG8_STAGE(PG8_SB(0, 1), b2 + hstep, voffB); PG8_STAGE(PG8_SA(0, 0), a2, voffA);
;             PG8_WAIT_V(8); PG8_WAIT_L(0); PG8_BAR; PG8_MMA(1, 0, At, B0); PG8_MMA(1, 1, At, B1); PG8_BAR; PG8_SCHED;
;             PG8_LDB(B0, 1, 0); PG8_LDB(B1, 1, 1); PG8_SCHED; PG8_LDA(At, 1, 0); PG8_STAGE(PG8_SA(0, 1), a2 + hstep, voffA);
;             PG8_WAIT_V(8); PG8_WAIT_L(0); PG8_BAR; PG8_MMA(0, 0, At, B0); PG8_MMA(0, 1, At, B1); PG8_BAR; PG8_SCHED;
;             PG8_LDA(At, 1, 1); PG8_STAGE(PG8_SB(1, 0), b3, voffB); PG8_STAGE(PG8_SB(1, 1), b3 + hstep, voffB); PG8_STAGE(PG8_SA(1, 0), a3, voffA);
;             PG8_WAIT_V(8); PG8_WAIT_L(0); PG8_BAR; PG8_MMA(1, 0, At, B0); PG8_MMA(1, 1, At, B1); PG8_BAR; PG8_SCHED;
.LBB0_1025:
	ds_read_b128 v[152:155], v149
	ds_read_b128 v[156:159], v149 offset:1024
	ds_read_b128 v[160:163], v149 offset:2048
	ds_read_b128 v[164:167], v149 offset:3072
	ds_read_b128 v[168:171], v150
	ds_read_b128 v[172:175], v150 offset:1024
	ds_read_b128 v[176:179], v150 offset:2048
	ds_read_b128 v[180:183], v150 offset:3072
	s_add_u32 s42, s40, 0xfffc0080
	s_addc_u32 s43, s41, -1
	s_cmp_eq_u32 s63, 12
	s_cselect_b32 s45, s19, s43
	s_cselect_b32 s44, s59, s42
	s_cselect_b32 s43, s17, s62
	s_cselect_b32 s42, s60, s61
	v_lshl_add_u64 v[144:145], s[40:41], 0, v[136:137]
	s_add_i32 m0, s12, 0xc000
	ds_read_b128 v[190:193], v151
	ds_read_b128 v[194:197], v151 offset:1024
	ds_read_b128 v[198:201], v151 offset:2048
	ds_read_b128 v[202:205], v151 offset:3072
	ds_read_b128 v[206:209], v151 offset:4096
	ds_read_b128 v[210:213], v151 offset:5120
	ds_read_b128 v[214:217], v151 offset:6144
	ds_read_b128 v[218:221], v151 offset:7168
	global_load_lds_dwordx4 v[144:145], off
	v_lshl_add_u64 v[144:145], s[40:41], 0, v[138:139]
	s_add_i32 m0, s12, 0xe000
	s_nop 0
	global_load_lds_dwordx4 v[144:145], off
	s_waitcnt vmcnt(8)
	s_waitcnt lgkmcnt(0)
	s_barrier
	s_setprio 1
	s_waitcnt lgkmcnt(0)
	v_mfma_f32_16x16x32_bf16 v[124:127], v[152:155], v[190:193], v[124:127]
	v_mfma_f32_16x16x32_bf16 v[116:119], v[160:163], v[190:193], v[116:119]
	v_mfma_f32_16x16x32_bf16 v[108:111], v[152:155], v[198:201], v[108:111]
	v_mfma_f32_16x16x32_bf16 v[100:103], v[160:163], v[198:201], v[100:103]
	v_mfma_f32_16x16x32_bf16 v[92:95], v[152:155], v[206:209], v[92:95]
	v_mfma_f32_16x16x32_bf16 v[84:87], v[160:163], v[206:209], v[84:87]
	v_mfma_f32_16x16x32_bf16 v[76:79], v[152:155], v[214:217], v[76:79]
	v_mfma_f32_16x16x32_bf16 v[68:71], v[160:163], v[214:217], v[68:71]
	v_mfma_f32_16x16x32_bf16 v[124:127], v[156:159], v[194:197], v[124:127]
	v_mfma_f32_16x16x32_bf16 v[116:119], v[164:167], v[194:197], v[116:119]
	v_mfma_f32_16x16x32_bf16 v[108:111], v[156:159], v[202:205], v[108:111]
	v_mfma_f32_16x16x32_bf16 v[100:103], v[164:167], v[202:205], v[100:103]
	v_mfma_f32_16x16x32_bf16 v[92:95], v[156:159], v[210:213], v[92:95]
	v_mfma_f32_16x16x32_bf16 v[84:87], v[164:167], v[210:213], v[84:87]
	v_mfma_f32_16x16x32_bf16 v[76:79], v[156:159], v[218:221], v[76:79]
	v_mfma_f32_16x16x32_bf16 v[68:71], v[164:167], v[218:221], v[68:71]
	s_setprio 0
	s_setprio 1
	v_mfma_f32_16x16x32_bf16 v[120:123], v[168:171], v[190:193], v[120:123]
	v_mfma_f32_16x16x32_bf16 v[112:115], v[176:179], v[190:193], v[112:115]
	v_mfma_f32_16x16x32_bf16 v[104:107], v[168:171], v[198:201], v[104:107]
	v_mfma_f32_16x16x32_bf16 v[96:99], v[176:179], v[198:201], v[96:99]
	v_mfma_f32_16x16x32_bf16 v[88:91], v[168:171], v[206:209], v[88:91]
	v_mfma_f32_16x16x32_bf16 v[80:83], v[176:179], v[206:209], v[80:83]
	v_mfma_f32_16x16x32_bf16 v[72:75], v[168:171], v[214:217], v[72:75]
	v_mfma_f32_16x16x32_bf16 v[64:67], v[176:179], v[214:217], v[64:67]
	v_mfma_f32_16x16x32_bf16 v[120:123], v[172:175], v[194:197], v[120:123]
	v_mfma_f32_16x16x32_bf16 v[112:115], v[180:183], v[194:197], v[112:115]
	v_mfma_f32_16x16x32_bf16 v[104:107], v[172:175], v[202:205], v[104:107]
	v_mfma_f32_16x16x32_bf16 v[96:99], v[180:183], v[202:205], v[96:99]
	v_mfma_f32_16x16x32_bf16 v[88:91], v[172:175], v[210:213], v[88:91]
	v_mfma_f32_16x16x32_bf16 v[80:83], v[180:183], v[210:213], v[80:83]
	v_mfma_f32_16x16x32_bf16 v[72:75], v[172:175], v[218:221], v[72:75]
	s_barrier
	v_mfma_f32_16x16x32_bf16 v[64:67], v[180:183], v[218:221], v[64:67]
	s_setprio 0
	s_add_i32 s64, s53, s8
	v_lshl_add_u64 v[144:145], s[42:43], 0, v[132:133]
	s_mov_b32 m0, s64
	ds_read_b128 v[190:193], v151 offset:16384
	ds_read_b128 v[194:197], v151 offset:17408
	ds_read_b128 v[198:201], v151 offset:18432
	ds_read_b128 v[202:205], v151 offset:19456
	ds_read_b128 v[206:209], v151 offset:20480
	ds_read_b128 v[210:213], v151 offset:21504
	ds_read_b128 v[214:217], v151 offset:22528
	ds_read_b128 v[218:221], v151 offset:23552
	global_load_lds_dwordx4 v[144:145], off
	s_add_i32 m0, s64, 0x2000
	s_add_u32 s64, s42, 0x40000
	v_lshl_add_u64 v[184:185], s[42:43], 0, v[128:129]
	s_addc_u32 s65, s43, 0
	s_add_i32 s66, s54, s8
	global_load_lds_dwordx4 v[184:185], off
	v_lshl_add_u64 v[186:187], s[64:65], 0, v[132:133]
	s_mov_b32 m0, s66
	v_lshl_add_u64 v[222:223], s[44:45], 0, v[130:131]
	global_load_lds_dwordx4 v[186:187], off
	v_lshl_add_u64 v[186:187], s[64:65], 0, v[128:129]
	s_add_i32 m0, s66, 0x2000
	s_nop 0
	global_load_lds_dwordx4 v[186:187], off
	v_lshl_add_u64 v[186:187], s[44:45], 0, v[134:135]
	s_mov_b32 m0, s12
	s_nop 0
	global_load_lds_dwordx4 v[186:187], off
	s_mov_b32 m0, s13
	s_nop 0
	global_load_lds_dwordx4 v[222:223], off
	s_waitcnt vmcnt(8)
	s_waitcnt lgkmcnt(0)
	s_barrier
; #define PG8_STAGE(bufoff, gbase, voff) do { _Pragma("unroll") for (int _i = 0; _i < 2; ++_i) \
;         __builtin_amdgcn_global_load_lds((const unsigned*)((const char*)(gbase) + (voff)[_i]), (PG8_LAS unsigned*)(lds + (bufoff) + ldsw + _i * 8192), 16, 0, 0); } while (0)
; #define PG8_LDA(dst, b, h) do { _Pragma("unroll") for (int m = 0; m < 4; ++m) _Pragma("unroll") for (int k = 0; k < 2; ++k) dst[m][k] = *(const PG8_LAS bf16x8*)(lds + PG8_SA(b, h) + aoff + m * 2048 + k * 1024); } while (0)
; #define PG8_LDB(dst, b, h) do { _Pragma("unroll") for (int n = 0; n < 2; ++n) _Pragma("unroll") for (int k = 0; k < 2; ++k) dst[n][k] = *(const PG8_LAS bf16x8*)(lds + PG8_SB(b, h) + boff + n * 2048 + k * 1024); } while (0)
; #define PG8_MMA(ai, bj, At, Bt) do { __builtin_amdgcn_s_setprio(1); _Pragma("unroll") for (int m = 0; m < 4; ++m) _Pragma("unroll") for (int n = 0; n < 2; ++n) _Pragma("unroll") for (int k = 0; k < 2; ++k) \
;         acc[ai][bj][m][n] = __builtin_amdgcn_mfma_f32_16x16x32_bf16(Bt[n][k], At[m][k], acc[ai][bj][m][n], 0, 0, 0); __builtin_amdgcn_s_setprio(0); } while (0)
; #define PG8_WAIT_V(n) asm volatile("s_waitcnt vmcnt(" #n ")" ::: "memory")
; template <class Epi, class Sched, bool ALIGN_EPI = false, bool SP2 = false>
; __device__ __forceinline__ void gemm_phase(PG8_LAS unsigned char* lds, const Gemm g, const Sched S, const Epi E) {
;     ...
;             PG8_LDB(B0, 0, 0); PG8_LDB(B1, 0, 1); PG8_SCHED; PG8_LDA(At, 0, 0); PG8_STAGE(PG8_SA(1, 1), a1 + hstep, voffA);
;             PG8_WAIT_V(8); PG8_WAIT_L(0); PG8_BAR; PG8_MMA(0, 0, At, B0); PG8_MMA(0, 1, At, B1); PG8_BAR; PG8_SCHED;
;             PG8_LDA(At, 0, 1); PG8_STAGE(PG8_SB(0, 0), b2, voffB); PG8_STAGE(PG8_SB(0, 1), b2 + hstep, voffB); PG8_STAGE(PG8_SA(0, 0), a2, voffA);
;             PG8_WAIT_V(8); PG8_WAIT_L(0); PG8_BAR; PG8_MMA(1, 0, At, B0); PG8_MMA(1, 1, At, B1); PG8_BAR; PG8_SCHED;
;             PG8_LDB(B0, 1, 0); PG8_LDB(B1, 1, 1); PG8_SCHED; PG8_LDA(At, 1, 0); PG8_STAGE(PG8_SA(0, 1), a2 + hstep, voffA);
;             PG8_WAIT_V(8); PG8_WAIT_L(0); PG8_BAR; PG8_MMA(0, 0, At, B0); PG8_MMA(0, 1, At, B1); PG8_BAR; PG8_SCHED;
;             PG8_LDA(At, 1, 1); PG8_STAGE(PG8_SB(1, 0), b3, voffB); PG8_STAGE(PG8_SB(1, 1), b3 + hstep, voffB); PG8_STAGE(PG8_SA(1, 0), a3, voffA);
;             PG8_WAIT_V(8); PG8_WAIT_L(0); PG8_BAR; PG8_MMA(1, 0, At, B0); PG8_MMA(1, 1, At, B1); PG8_BAR; PG8_SCHED;
	s_setprio 1
	s_waitcnt lgkmcnt(0)
	v_mfma_f32_16x16x32_bf16 v[60:63], v[152:155], v[190:193], v[60:63]
	v_mfma_f32_16x16x32_bf16 v[52:55], v[160:163], v[190:193], v[52:55]
	v_mfma_f32_16x16x32_bf16 v[44:47], v[152:155], v[198:201], v[44:47]
	v_mfma_f32_16x16x32_bf16 v[36:39], v[160:163], v[198:201], v[36:39]
	v_mfma_f32_16x16x32_bf16 v[28:31], v[152:155], v[206:209], v[28:31]
	v_mfma_f32_16x16x32_bf16 v[20:23], v[160:163], v[206:209], v[20:23]
	v_mfma_f32_16x16x32_bf16 v[12:15], v[152:155], v[214:217], v[12:15]
	v_mfma_f32_16x16x32_bf16 v[4:7], v[160:163], v[214:217], v[4:7]
	v_mfma_f32_16x16x32_bf16 v[60:63], v[156:159], v[194:197], v[60:63]
	v_mfma_f32_16x16x32_bf16 v[52:55], v[164:167], v[194:197], v[52:55]
	v_mfma_f32_16x16x32_bf16 v[44:47], v[156:159], v[202:205], v[44:47]
	v_mfma_f32_16x16x32_bf16 v[36:39], v[164:167], v[202:205], v[36:39]
	v_mfma_f32_16x16x32_bf16 v[28:31], v[156:159], v[210:213], v[28:31]
	v_mfma_f32_16x16x32_bf16 v[20:23], v[164:167], v[210:213], v[20:23]
	v_mfma_f32_16x16x32_bf16 v[12:15], v[156:159], v[218:221], v[12:15]
	v_mfma_f32_16x16x32_bf16 v[4:7], v[164:167], v[218:221], v[4:7]
	s_setprio 0
	s_setprio 1
	v_mfma_f32_16x16x32_bf16 v[56:59], v[168:171], v[190:193], v[56:59]
	v_mfma_f32_16x16x32_bf16 v[48:51], v[176:179], v[190:193], v[48:51]
	v_mfma_f32_16x16x32_bf16 v[40:43], v[168:171], v[198:201], v[40:43]
	v_mfma_f32_16x16x32_bf16 v[32:35], v[176:179], v[198:201], v[32:35]
	v_mfma_f32_16x16x32_bf16 v[24:27], v[168:171], v[206:209], v[24:27]
	v_mfma_f32_16x16x32_bf16 v[16:19], v[176:179], v[206:209], v[16:19]
	v_mfma_f32_16x16x32_bf16 v[8:11], v[168:171], v[214:217], v[8:11]
	v_mfma_f32_16x16x32_bf16 v[0:3], v[176:179], v[214:217], v[0:3]
	v_mfma_f32_16x16x32_bf16 v[56:59], v[172:175], v[194:197], v[56:59]
	v_mfma_f32_16x16x32_bf16 v[48:51], v[180:183], v[194:197], v[48:51]
	v_mfma_f32_16x16x32_bf16 v[40:43], v[172:175], v[202:205], v[40:43]
	v_mfma_f32_16x16x32_bf16 v[32:35], v[180:183], v[202:205], v[32:35]
	v_mfma_f32_16x16x32_bf16 v[24:27], v[172:175], v[210:213], v[24:27]
	v_mfma_f32_16x16x32_bf16 v[16:19], v[180:183], v[210:213], v[16:19]
	v_mfma_f32_16x16x32_bf16 v[8:11], v[172:175], v[218:221], v[8:11]
	s_barrier
	v_mfma_f32_16x16x32_bf16 v[0:3], v[180:183], v[218:221], v[0:3]
	s_setprio 0
	s_add_i32 s64, 0, 0x18000
	s_add_i32 s65, 0, 0x1c000
	v_add_u32_e32 v164, s64, v148
	v_add_u32_e32 v180, s65, v148
	ds_read_b128 v[152:155], v164
	ds_read_b128 v[156:159], v164 offset:1024
	ds_read_b128 v[160:163], v164 offset:2048
	ds_read_b128 v[164:167], v164 offset:3072
	ds_read_b128 v[168:171], v180
	ds_read_b128 v[172:175], v180 offset:1024
	ds_read_b128 v[176:179], v180 offset:2048
	ds_read_b128 v[180:183], v180 offset:3072
	s_add_u32 s44, s44, 0x40000
	s_addc_u32 s45, s45, 0
	s_mov_b32 m0, s33
	v_lshl_add_u64 v[224:225], s[44:45], 0, v[134:135]
	ds_read_b128 v[190:193], v151 offset:32768
	ds_read_b128 v[194:197], v151 offset:33792
	ds_read_b128 v[198:201], v151 offset:34816
	ds_read_b128 v[202:205], v151 offset:35840
	ds_read_b128 v[206:209], v151 offset:36864
	ds_read_b128 v[210:213], v151 offset:37888
	ds_read_b128 v[214:217], v151 offset:38912
	ds_read_b128 v[218:221], v151 offset:39936
	global_load_lds_dwordx4 v[224:225], off
	v_lshl_add_u64 v[224:225], s[44:45], 0, v[130:131]
	s_mov_b32 m0, s39
	s_nop 0
	global_load_lds_dwordx4 v[224:225], off
	s_waitcnt vmcnt(8)
	s_waitcnt lgkmcnt(0)
	s_barrier
	s_setprio 1
	s_waitcnt lgkmcnt(0)
	v_mfma_f32_16x16x32_bf16 v[124:127], v[152:155], v[190:193], v[124:127]
	v_mfma_f32_16x16x32_bf16 v[116:119], v[160:163], v[190:193], v[116:119]
	v_mfma_f32_16x16x32_bf16 v[108:111], v[152:155], v[198:201], v[108:111]
	v_mfma_f32_16x16x32_bf16 v[100:103], v[160:163], v[198:201], v[100:103]
	v_mfma_f32_16x16x32_bf16 v[92:95], v[152:155], v[206:209], v[92:95]
	v_mfma_f32_16x16x32_bf16 v[84:87], v[160:163], v[206:209], v[84:87]
	v_mfma_f32_16x16x32_bf16 v[76:79], v[152:155], v[214:217], v[76:79]
	v_mfma_f32_16x16x32_bf16 v[68:71], v[160:163], v[214:217], v[68:71]
	v_mfma_f32_16x16x32_bf16 v[124:127], v[156:159], v[194:197], v[124:127]
	v_mfma_f32_16x16x32_bf16 v[116:119], v[164:167], v[194:197], v[116:119]
	v_mfma_f32_16x16x32_bf16 v[108:111], v[156:159], v[202:205], v[108:111]
	v_mfma_f32_16x16x32_bf16 v[100:103], v[164:167], v[202:205], v[100:103]
	v_mfma_f32_16x16x32_bf16 v[92:95], v[156:159], v[210:213], v[92:95]
	v_mfma_f32_16x16x32_bf16 v[84:87], v[164:167], v[210:213], v[84:87]
	v_mfma_f32_16x16x32_bf16 v[76:79], v[156:159], v[218:221], v[76:79]
	v_mfma_f32_16x16x32_bf16 v[68:71], v[164:167], v[218:221], v[68:71]
	s_setprio 0
	s_setprio 1
	v_mfma_f32_16x16x32_bf16 v[120:123], v[168:171], v[190:193], v[120:123]
	v_mfma_f32_16x16x32_bf16 v[112:115], v[176:179], v[190:193], v[112:115]
	v_mfma_f32_16x16x32_bf16 v[104:107], v[168:171], v[198:201], v[104:107]
	v_mfma_f32_16x16x32_bf16 v[96:99], v[176:179], v[198:201], v[96:99]
	v_mfma_f32_16x16x32_bf16 v[88:91], v[168:171], v[206:209], v[88:91]
	v_mfma_f32_16x16x32_bf16 v[80:83], v[176:179], v[206:209], v[80:83]
	v_mfma_f32_16x16x32_bf16 v[72:75], v[168:171], v[214:217], v[72:75]
	v_mfma_f32_16x16x32_bf16 v[64:67], v[176:179], v[214:217], v[64:67]
	v_mfma_f32_16x16x32_bf16 v[120:123], v[172:175], v[194:197], v[120:123]
	v_mfma_f32_16x16x32_bf16 v[112:115], v[180:183], v[194:197], v[112:115]
	v_mfma_f32_16x16x32_bf16 v[104:107], v[172:175], v[202:205], v[104:107]
	v_mfma_f32_16x16x32_bf16 v[96:99], v[180:183], v[202:205], v[96:99]
	v_mfma_f32_16x16x32_bf16 v[88:91], v[172:175], v[210:213], v[88:91]
	v_mfma_f32_16x16x32_bf16 v[80:83], v[180:183], v[210:213], v[80:83]
	v_mfma_f32_16x16x32_bf16 v[72:75], v[172:175], v[218:221], v[72:75]
	s_barrier
; #define PG8_STAGE(bufoff, gbase, voff) do { _Pragma("unroll") for (int _i = 0; _i < 2; ++_i) \
;         __builtin_amdgcn_global_load_lds((const unsigned*)((const char*)(gbase) + (voff)[_i]), (PG8_LAS unsigned*)(lds + (bufoff) + ldsw + _i * 8192), 16, 0, 0); } while (0)
; #define PG8_LDA(dst, b, h) do { _Pragma("unroll") for (int m = 0; m < 4; ++m) _Pragma("unroll") for (int k = 0; k < 2; ++k) dst[m][k] = *(const PG8_LAS bf16x8*)(lds + PG8_SA(b, h) + aoff + m * 2048 + k * 1024); } while (0)
; #define PG8_LDB(dst, b, h) do { _Pragma("unroll") for (int n = 0; n < 2; ++n) _Pragma("unroll") for (int k = 0; k < 2; ++k) dst[n][k] = *(const PG8_LAS bf16x8*)(lds + PG8_SB(b, h) + boff + n * 2048 + k * 1024); } while (0)
; #define PG8_MMA(ai, bj, At, Bt) do { __builtin_amdgcn_s_setprio(1); _Pragma("unroll") for (int m = 0; m < 4; ++m) _Pragma("unroll") for (int n = 0; n < 2; ++n) _Pragma("unroll") for (int k = 0; k < 2; ++k) \
;         acc[ai][bj][m][n] = __builtin_amdgcn_mfma_f32_16x16x32_bf16(Bt[n][k], At[m][k], acc[ai][bj][m][n], 0, 0, 0); __builtin_amdgcn_s_setprio(0); } while (0)
; #define PG8_WAIT_V(n) asm volatile("s_waitcnt vmcnt(" #n ")" ::: "memory")
; template <class Epi, class Sched, bool ALIGN_EPI = false, bool SP2 = false>
; __device__ __forceinline__ void gemm_phase(PG8_LAS unsigned char* lds, const Gemm g, const Sched S, const Epi E) {
;     ...
;             PG8_LDB(B0, 0, 0); PG8_LDB(B1, 0, 1); PG8_SCHED; PG8_LDA(At, 0, 0); PG8_STAGE(PG8_SA(1, 1), a1 + hstep, voffA);
;             PG8_WAIT_V(8); PG8_WAIT_L(0); PG8_BAR; PG8_MMA(0, 0, At, B0); PG8_MMA(0, 1, At, B1); PG8_BAR; PG8_SCHED;
;             PG8_LDA(At, 0, 1); PG8_STAGE(PG8_SB(0, 0), b2, voffB); PG8_STAGE(PG8_SB(0, 1), b2 + hstep, voffB); PG8_STAGE(PG8_SA(0, 0), a2, voffA);
;             PG8_WAIT_V(8); PG8_WAIT_L(0); PG8_BAR; PG8_MMA(1, 0, At, B0); PG8_MMA(1, 1, At, B1); PG8_BAR; PG8_SCHED;
;             PG8_LDB(B0, 1, 0); PG8_LDB(B1, 1, 1); PG8_SCHED; PG8_LDA(At, 1, 0); PG8_STAGE(PG8_SA(0, 1), a2 + hstep, voffA);
;             PG8_WAIT_V(8); PG8_WAIT_L(0); PG8_BAR; PG8_MMA(0, 0, At, B0); PG8_MMA(0, 1, At, B1); PG8_BAR; PG8_SCHED;
;             PG8_LDA(At, 1, 1); PG8_STAGE(PG8_SB(1, 0), b3, voffB); PG8_STAGE(PG8_SB(1, 1), b3 + hstep, voffB); PG8_STAGE(PG8_SA(1, 0), a3, voffA);
;             PG8_WAIT_V(8); PG8_WAIT_L(0); PG8_BAR; PG8_MMA(1, 0, At, B0); PG8_MMA(1, 1, At, B1); PG8_BAR; PG8_SCHED;
	v_mfma_f32_16x16x32_bf16 v[64:67], v[180:183], v[218:221], v[64:67]
	s_setprio 0
	s_add_i32 s44, s64, s8
	v_lshl_add_u64 v[144:145], v[144:145], 0, s[10:11]
	s_mov_b32 m0, s44
	ds_read_b128 v[190:193], v151 offset:49152
	ds_read_b128 v[194:197], v151 offset:50176
	ds_read_b128 v[198:201], v151 offset:51200
	ds_read_b128 v[202:205], v151 offset:52224
	ds_read_b128 v[206:209], v151 offset:53248
	ds_read_b128 v[210:213], v151 offset:54272
	ds_read_b128 v[214:217], v151 offset:55296
	ds_read_b128 v[218:221], v151 offset:56320
	global_load_lds_dwordx4 v[144:145], off
	s_add_i32 m0, s44, 0x2000
	s_add_u32 s42, s42, 0x40080
	v_lshl_add_u64 v[144:145], v[184:185], 0, s[10:11]
	s_addc_u32 s43, s43, 0
	s_add_i32 s44, s65, s8
	global_load_lds_dwordx4 v[144:145], off
	v_lshl_add_u64 v[144:145], s[42:43], 0, v[132:133]
	s_mov_b32 m0, s44
	s_nop 0
	global_load_lds_dwordx4 v[144:145], off
	v_lshl_add_u64 v[144:145], s[42:43], 0, v[128:129]
	s_add_i32 m0, s44, 0x2000
	s_nop 0
	global_load_lds_dwordx4 v[144:145], off
	v_lshl_add_u64 v[144:145], v[186:187], 0, s[10:11]
	s_mov_b32 m0, s49
	s_nop 0
	global_load_lds_dwordx4 v[144:145], off
	v_lshl_add_u64 v[144:145], v[222:223], 0, s[10:11]
	s_mov_b32 m0, s50
	s_nop 0
	global_load_lds_dwordx4 v[144:145], off
	s_waitcnt vmcnt(8)
	s_waitcnt lgkmcnt(0)
	s_barrier
	s_setprio 1
	s_waitcnt lgkmcnt(0)
	v_mfma_f32_16x16x32_bf16 v[60:63], v[152:155], v[190:193], v[60:63]
	v_mfma_f32_16x16x32_bf16 v[52:55], v[160:163], v[190:193], v[52:55]
	v_mfma_f32_16x16x32_bf16 v[44:47], v[152:155], v[198:201], v[44:47]
	v_mfma_f32_16x16x32_bf16 v[36:39], v[160:163], v[198:201], v[36:39]
	v_mfma_f32_16x16x32_bf16 v[28:31], v[152:155], v[206:209], v[28:31]
	v_mfma_f32_16x16x32_bf16 v[20:23], v[160:163], v[206:209], v[20:23]
	v_mfma_f32_16x16x32_bf16 v[12:15], v[152:155], v[214:217], v[12:15]
	v_mfma_f32_16x16x32_bf16 v[4:7], v[160:163], v[214:217], v[4:7]
	v_mfma_f32_16x16x32_bf16 v[60:63], v[156:159], v[194:197], v[60:63]
	v_mfma_f32_16x16x32_bf16 v[52:55], v[164:167], v[194:197], v[52:55]
	v_mfma_f32_16x16x32_bf16 v[44:47], v[156:159], v[202:205], v[44:47]
	v_mfma_f32_16x16x32_bf16 v[36:39], v[164:167], v[202:205], v[36:39]
	v_mfma_f32_16x16x32_bf16 v[28:31], v[156:159], v[210:213], v[28:31]
	v_mfma_f32_16x16x32_bf16 v[20:23], v[164:167], v[210:213], v[20:23]
	v_mfma_f32_16x16x32_bf16 v[12:15], v[156:159], v[218:221], v[12:15]
	v_mfma_f32_16x16x32_bf16 v[4:7], v[164:167], v[218:221], v[4:7]
	s_setprio 0
	s_setprio 1
	v_mfma_f32_16x16x32_bf16 v[56:59], v[168:171], v[190:193], v[56:59]
	v_mfma_f32_16x16x32_bf16 v[48:51], v[176:179], v[190:193], v[48:51]
	v_mfma_f32_16x16x32_bf16 v[40:43], v[168:171], v[198:201], v[40:43]
	v_mfma_f32_16x16x32_bf16 v[32:35], v[176:179], v[198:201], v[32:35]
	v_mfma_f32_16x16x32_bf16 v[24:27], v[168:171], v[206:209], v[24:27]
	v_mfma_f32_16x16x32_bf16 v[16:19], v[176:179], v[206:209], v[16:19]
	v_mfma_f32_16x16x32_bf16 v[8:11], v[168:171], v[214:217], v[8:11]
	v_mfma_f32_16x16x32_bf16 v[0:3], v[176:179], v[214:217], v[0:3]
	v_mfma_f32_16x16x32_bf16 v[56:59], v[172:175], v[194:197], v[56:59]
	v_mfma_f32_16x16x32_bf16 v[48:51], v[180:183], v[194:197], v[48:51]
	v_mfma_f32_16x16x32_bf16 v[40:43], v[172:175], v[202:205], v[40:43]
	v_mfma_f32_16x16x32_bf16 v[32:35], v[180:183], v[202:205], v[32:35]
	v_mfma_f32_16x16x32_bf16 v[24:27], v[172:175], v[210:213], v[24:27]
	v_mfma_f32_16x16x32_bf16 v[16:19], v[180:183], v[210:213], v[16:19]
	v_mfma_f32_16x16x32_bf16 v[8:11], v[172:175], v[218:221], v[8:11]
	s_barrier
	v_mfma_f32_16x16x32_bf16 v[0:3], v[180:183], v[218:221], v[0:3]
	s_setprio 0
	s_add_i32 s63, s63, 2
	s_add_u32 s40, s40, 0x100
	s_addc_u32 s41, s41, 0
	s_add_u32 s61, s61, 0x100
	s_addc_u32 s62, s62, 0
	s_cmp_gt_u32 s63, 13
	s_cbranch_scc0 .LBB0_1025
	s_and_b64 vcc, exec, s[14:15]
	s_cbranch_vccz .LBB0_1028
	s_barrier

; #define PG8_STAGE(bufoff, gbase, voff) do { _Pragma("unroll") for (int _i = 0; _i < 2; ++_i) \
;         __builtin_amdgcn_global_load_lds((const unsigned*)((const char*)(gbase) + (voff)[_i]), (PG8_LAS unsigned*)(lds + (bufoff) + ldsw + _i * 8192), 16, 0, 0); } while (0)
; #define PG8_LDA(dst, b, h) do { _Pragma("unroll") for (int m = 0; m < 4; ++m) _Pragma("unroll") for (int k = 0; k < 2; ++k) dst[m][k] = *(const PG8_LAS bf16x8*)(lds + PG8_SA(b, h) + aoff + m * 2048 + k * 1024); } while (0)
; #define PG8_LDB(dst, b, h) do { _Pragma("unroll") for (int n = 0; n < 2; ++n) _Pragma("unroll") for (int k = 0; k < 2; ++k) dst[n][k] = *(const PG8_LAS bf16x8*)(lds + PG8_SB(b, h) + boff + n * 2048 + k * 1024); } while (0)
; #define PG8_MMA(ai, bj, At, Bt) do { __builtin_amdgcn_s_setprio(1); _Pragma("unroll") for (int m = 0; m < 4; ++m) _Pragma("unroll") for (int n = 0; n < 2; ++n) _Pragma("unroll") for (int k = 0; k < 2; ++k) \
;         acc[ai][bj][m][n] = __builtin_amdgcn_mfma_f32_16x16x32_bf16(Bt[n][k], At[m][k], acc[ai][bj][m][n], 0, 0, 0); __builtin_amdgcn_s_setprio(0); } while (0)
; #define PG8_WAIT_V(n) asm volatile("s_waitcnt vmcnt(" #n ")" ::: "memory")
; template <class Epi, class Sched, bool ALIGN_EPI = false, bool SP2 = false>
; __device__ __forceinline__ void gemm_phase(PG8_LAS unsigned char* lds, const Gemm g, const Sched S, const Epi E) {
;     ...
;             PG8_LDB(B0, 0, 0); PG8_LDB(B1, 0, 1); PG8_SCHED; PG8_LDA(At, 0, 0); PG8_STAGE(PG8_SA(1, 1), a1 + hstep, voffA);
;             PG8_WAIT_V(8); PG8_WAIT_L(0); PG8_BAR; PG8_MMA(0, 0, At, B0); PG8_MMA(0, 1, At, B1); PG8_BAR; PG8_SCHED;
;             PG8_LDA(At, 0, 1); PG8_STAGE(PG8_SB(0, 0), b2, voffB); PG8_STAGE(PG8_SB(0, 1), b2 + hstep, voffB); PG8_STAGE(PG8_SA(0, 0), a2, voffA);
;             PG8_WAIT_V(8); PG8_WAIT_L(0); PG8_BAR; PG8_MMA(1, 0, At, B0); PG8_MMA(1, 1, At, B1); PG8_BAR; PG8_SCHED;
;             PG8_LDB(B0, 1, 0); PG8_LDB(B1, 1, 1); PG8_SCHED; PG8_LDA(At, 1, 0); PG8_STAGE(PG8_SA(0, 1), a2 + hstep, voffA);
;             PG8_WAIT_V(8); PG8_WAIT_L(0); PG8_BAR; PG8_MMA(0, 0, At, B0); PG8_MMA(0, 1, At, B1); PG8_BAR; PG8_SCHED;
;             PG8_LDA(At, 1, 1); PG8_STAGE(PG8_SB(1, 0), b3, voffB); PG8_STAGE(PG8_SB(1, 1), b3 + hstep, voffB); PG8_STAGE(PG8_SA(1, 0), a3, voffA);
;             PG8_WAIT_V(8); PG8_WAIT_L(0); PG8_BAR; PG8_MMA(1, 0, At, B0); PG8_MMA(1, 1, At, B1); PG8_BAR; PG8_SCHED;
.LBB0_1105:
	ds_read_b128 v[128:131], v241
	ds_read_b128 v[132:135], v241 offset:1024
	ds_read_b128 v[136:139], v241 offset:2048
	ds_read_b128 v[140:143], v241 offset:3072
	ds_read_b128 v[144:147], v242
	ds_read_b128 v[148:151], v242 offset:1024
	ds_read_b128 v[152:155], v242 offset:2048
	ds_read_b128 v[156:159], v242 offset:3072
	s_add_u32 s48, s46, 0x100
	s_addc_u32 s49, s47, 0
	s_cmp_eq_u32 s71, 40
	s_cselect_b32 s53, s5, s49
	s_cselect_b32 s52, s4, s48
	s_cselect_b32 s51, s45, s70
	s_cselect_b32 s50, s44, s69
	v_lshl_add_u64 v[210:211], s[46:47], 0, v[198:199]
	s_add_i32 m0, s9, 0xc000
	ds_read_b128 v[160:163], v243
	ds_read_b128 v[164:167], v243 offset:1024
	ds_read_b128 v[168:171], v243 offset:2048
	ds_read_b128 v[172:175], v243 offset:3072
	ds_read_b128 v[176:179], v243 offset:4096
	ds_read_b128 v[180:183], v243 offset:5120
	ds_read_b128 v[184:187], v243 offset:6144
	ds_read_b128 v[206:209], v243 offset:7168
	global_load_lds_dwordx4 v[210:211], off
	v_lshl_add_u64 v[210:211], s[46:47], 0, v[200:201]
	s_add_i32 m0, s9, 0xe000
	s_nop 0
	global_load_lds_dwordx4 v[210:211], off
	s_waitcnt vmcnt(8)
	s_waitcnt lgkmcnt(0)
	s_barrier
	s_setprio 1
	s_waitcnt lgkmcnt(0)
	v_mfma_f32_16x16x32_bf16 v[124:127], v[128:131], v[160:163], v[124:127]
	v_mfma_f32_16x16x32_bf16 v[120:123], v[136:139], v[160:163], v[120:123]
	v_mfma_f32_16x16x32_bf16 v[112:115], v[128:131], v[168:171], v[112:115]
	v_mfma_f32_16x16x32_bf16 v[104:107], v[136:139], v[168:171], v[104:107]
	v_mfma_f32_16x16x32_bf16 v[96:99], v[128:131], v[176:179], v[96:99]
	v_mfma_f32_16x16x32_bf16 v[88:91], v[136:139], v[176:179], v[88:91]
	v_mfma_f32_16x16x32_bf16 v[80:83], v[128:131], v[184:187], v[80:83]
	v_mfma_f32_16x16x32_bf16 v[72:75], v[136:139], v[184:187], v[72:75]
	v_mfma_f32_16x16x32_bf16 v[124:127], v[132:135], v[164:167], v[124:127]
	v_mfma_f32_16x16x32_bf16 v[120:123], v[140:143], v[164:167], v[120:123]
	v_mfma_f32_16x16x32_bf16 v[112:115], v[132:135], v[172:175], v[112:115]
	v_mfma_f32_16x16x32_bf16 v[104:107], v[140:143], v[172:175], v[104:107]
	v_mfma_f32_16x16x32_bf16 v[96:99], v[132:135], v[180:183], v[96:99]
	v_mfma_f32_16x16x32_bf16 v[88:91], v[140:143], v[180:183], v[88:91]
	v_mfma_f32_16x16x32_bf16 v[80:83], v[132:135], v[206:209], v[80:83]
	v_mfma_f32_16x16x32_bf16 v[72:75], v[140:143], v[206:209], v[72:75]
	s_setprio 0
	s_setprio 1
	v_mfma_f32_16x16x32_bf16 v[116:119], v[144:147], v[160:163], v[116:119]
	v_mfma_f32_16x16x32_bf16 v[108:111], v[152:155], v[160:163], v[108:111]
	v_mfma_f32_16x16x32_bf16 v[100:103], v[144:147], v[168:171], v[100:103]
	v_mfma_f32_16x16x32_bf16 v[92:95], v[152:155], v[168:171], v[92:95]
	v_mfma_f32_16x16x32_bf16 v[84:87], v[144:147], v[176:179], v[84:87]
	v_mfma_f32_16x16x32_bf16 v[76:79], v[152:155], v[176:179], v[76:79]
	v_mfma_f32_16x16x32_bf16 v[68:71], v[144:147], v[184:187], v[68:71]
	v_mfma_f32_16x16x32_bf16 v[64:67], v[152:155], v[184:187], v[64:67]
	v_mfma_f32_16x16x32_bf16 v[116:119], v[148:151], v[164:167], v[116:119]
	v_mfma_f32_16x16x32_bf16 v[108:111], v[156:159], v[164:167], v[108:111]
	v_mfma_f32_16x16x32_bf16 v[100:103], v[148:151], v[172:175], v[100:103]
	v_mfma_f32_16x16x32_bf16 v[92:95], v[156:159], v[172:175], v[92:95]
	v_mfma_f32_16x16x32_bf16 v[84:87], v[148:151], v[180:183], v[84:87]
	v_mfma_f32_16x16x32_bf16 v[76:79], v[156:159], v[180:183], v[76:79]
	v_mfma_f32_16x16x32_bf16 v[68:71], v[148:151], v[206:209], v[68:71]
	s_barrier
	v_mfma_f32_16x16x32_bf16 v[64:67], v[156:159], v[206:209], v[64:67]
	s_setprio 0
	s_add_i32 s46, s63, s8
	v_lshl_add_u64 v[210:211], s[50:51], 0, v[192:193]
	s_mov_b32 m0, s46
	ds_read_b128 v[160:163], v243 offset:16384
	ds_read_b128 v[164:167], v243 offset:17408
	ds_read_b128 v[168:171], v243 offset:18432
	ds_read_b128 v[172:175], v243 offset:19456
	ds_read_b128 v[176:179], v243 offset:20480
	ds_read_b128 v[180:183], v243 offset:21504
	ds_read_b128 v[184:187], v243 offset:22528
	ds_read_b128 v[206:209], v243 offset:23552
	global_load_lds_dwordx4 v[210:211], off
	s_add_i32 m0, s46, 0x2000
	s_add_u32 s46, s50, 0xb0000
	v_lshl_add_u64 v[212:213], s[50:51], 0, v[196:197]
	s_addc_u32 s47, s51, 0
	s_add_i32 s72, s64, s8
	global_load_lds_dwordx4 v[212:213], off
	v_lshl_add_u64 v[214:215], s[46:47], 0, v[192:193]
	s_mov_b32 m0, s72
	v_lshl_add_u64 v[216:217], s[52:53], 0, v[194:195]
	global_load_lds_dwordx4 v[214:215], off
	v_lshl_add_u64 v[214:215], s[46:47], 0, v[196:197]
	s_add_i32 m0, s72, 0x2000
	s_nop 0
	global_load_lds_dwordx4 v[214:215], off
	v_lshl_add_u64 v[214:215], s[52:53], 0, v[190:191]
	s_mov_b32 m0, s9
	s_nop 0
	global_load_lds_dwordx4 v[214:215], off
	s_mov_b32 m0, s12
	s_nop 0
	global_load_lds_dwordx4 v[216:217], off
	s_waitcnt vmcnt(8)
	s_waitcnt lgkmcnt(0)
	s_barrier
; #define PG8_STAGE(bufoff, gbase, voff) do { _Pragma("unroll") for (int _i = 0; _i < 2; ++_i) \
;         __builtin_amdgcn_global_load_lds((const unsigned*)((const char*)(gbase) + (voff)[_i]), (PG8_LAS unsigned*)(lds + (bufoff) + ldsw + _i * 8192), 16, 0, 0); } while (0)
; #define PG8_LDA(dst, b, h) do { _Pragma("unroll") for (int m = 0; m < 4; ++m) _Pragma("unroll") for (int k = 0; k < 2; ++k) dst[m][k] = *(const PG8_LAS bf16x8*)(lds + PG8_SA(b, h) + aoff + m * 2048 + k * 1024); } while (0)
; #define PG8_LDB(dst, b, h) do { _Pragma("unroll") for (int n = 0; n < 2; ++n) _Pragma("unroll") for (int k = 0; k < 2; ++k) dst[n][k] = *(const PG8_LAS bf16x8*)(lds + PG8_SB(b, h) + boff + n * 2048 + k * 1024); } while (0)
; #define PG8_MMA(ai, bj, At, Bt) do { __builtin_amdgcn_s_setprio(1); _Pragma("unroll") for (int m = 0; m < 4; ++m) _Pragma("unroll") for (int n = 0; n < 2; ++n) _Pragma("unroll") for (int k = 0; k < 2; ++k) \
;         acc[ai][bj][m][n] = __builtin_amdgcn_mfma_f32_16x16x32_bf16(Bt[n][k], At[m][k], acc[ai][bj][m][n], 0, 0, 0); __builtin_amdgcn_s_setprio(0); } while (0)
; #define PG8_WAIT_V(n) asm volatile("s_waitcnt vmcnt(" #n ")" ::: "memory")
; template <class Epi, class Sched, bool ALIGN_EPI = false, bool SP2 = false>
; __device__ __forceinline__ void gemm_phase(PG8_LAS unsigned char* lds, const Gemm g, const Sched S, const Epi E) {
;     ...
;             PG8_LDB(B0, 0, 0); PG8_LDB(B1, 0, 1); PG8_SCHED; PG8_LDA(At, 0, 0); PG8_STAGE(PG8_SA(1, 1), a1 + hstep, voffA);
;             PG8_WAIT_V(8); PG8_WAIT_L(0); PG8_BAR; PG8_MMA(0, 0, At, B0); PG8_MMA(0, 1, At, B1); PG8_BAR; PG8_SCHED;
;             PG8_LDA(At, 0, 1); PG8_STAGE(PG8_SB(0, 0), b2, voffB); PG8_STAGE(PG8_SB(0, 1), b2 + hstep, voffB); PG8_STAGE(PG8_SA(0, 0), a2, voffA);
;             PG8_WAIT_V(8); PG8_WAIT_L(0); PG8_BAR; PG8_MMA(1, 0, At, B0); PG8_MMA(1, 1, At, B1); PG8_BAR; PG8_SCHED;
;             PG8_LDB(B0, 1, 0); PG8_LDB(B1, 1, 1); PG8_SCHED; PG8_LDA(At, 1, 0); PG8_STAGE(PG8_SA(0, 1), a2 + hstep, voffA);
;             PG8_WAIT_V(8); PG8_WAIT_L(0); PG8_BAR; PG8_MMA(0, 0, At, B0); PG8_MMA(0, 1, At, B1); PG8_BAR; PG8_SCHED;
;             PG8_LDA(At, 1, 1); PG8_STAGE(PG8_SB(1, 0), b3, voffB); PG8_STAGE(PG8_SB(1, 1), b3 + hstep, voffB); PG8_STAGE(PG8_SA(1, 0), a3, voffA);
;             PG8_WAIT_V(8); PG8_WAIT_L(0); PG8_BAR; PG8_MMA(1, 0, At, B0); PG8_MMA(1, 1, At, B1); PG8_BAR; PG8_SCHED;
	s_setprio 1
	s_waitcnt lgkmcnt(0)
	v_mfma_f32_16x16x32_bf16 v[60:63], v[128:131], v[160:163], v[60:63]
	v_mfma_f32_16x16x32_bf16 v[56:59], v[136:139], v[160:163], v[56:59]
	v_mfma_f32_16x16x32_bf16 v[48:51], v[128:131], v[168:171], v[48:51]
	v_mfma_f32_16x16x32_bf16 v[40:43], v[136:139], v[168:171], v[40:43]
	v_mfma_f32_16x16x32_bf16 v[32:35], v[128:131], v[176:179], v[32:35]
	v_mfma_f32_16x16x32_bf16 v[24:27], v[136:139], v[176:179], v[24:27]
	v_mfma_f32_16x16x32_bf16 v[16:19], v[128:131], v[184:187], v[16:19]
	v_mfma_f32_16x16x32_bf16 v[8:11], v[136:139], v[184:187], v[8:11]
	v_mfma_f32_16x16x32_bf16 v[60:63], v[132:135], v[164:167], v[60:63]
	v_mfma_f32_16x16x32_bf16 v[56:59], v[140:143], v[164:167], v[56:59]
	v_mfma_f32_16x16x32_bf16 v[48:51], v[132:135], v[172:175], v[48:51]
	v_mfma_f32_16x16x32_bf16 v[40:43], v[140:143], v[172:175], v[40:43]
	v_mfma_f32_16x16x32_bf16 v[32:35], v[132:135], v[180:183], v[32:35]
	v_mfma_f32_16x16x32_bf16 v[24:27], v[140:143], v[180:183], v[24:27]
	v_mfma_f32_16x16x32_bf16 v[16:19], v[132:135], v[206:209], v[16:19]
	v_mfma_f32_16x16x32_bf16 v[8:11], v[140:143], v[206:209], v[8:11]
	s_setprio 0
	s_setprio 1
	v_mfma_f32_16x16x32_bf16 v[52:55], v[144:147], v[160:163], v[52:55]
	v_mfma_f32_16x16x32_bf16 v[44:47], v[152:155], v[160:163], v[44:47]
	v_mfma_f32_16x16x32_bf16 v[36:39], v[144:147], v[168:171], v[36:39]
	v_mfma_f32_16x16x32_bf16 v[28:31], v[152:155], v[168:171], v[28:31]
	v_mfma_f32_16x16x32_bf16 v[20:23], v[144:147], v[176:179], v[20:23]
	v_mfma_f32_16x16x32_bf16 v[12:15], v[152:155], v[176:179], v[12:15]
	v_mfma_f32_16x16x32_bf16 v[4:7], v[144:147], v[184:187], v[4:7]
	v_mfma_f32_16x16x32_bf16 v[0:3], v[152:155], v[184:187], v[0:3]
	v_mfma_f32_16x16x32_bf16 v[52:55], v[148:151], v[164:167], v[52:55]
	v_mfma_f32_16x16x32_bf16 v[44:47], v[156:159], v[164:167], v[44:47]
	v_mfma_f32_16x16x32_bf16 v[36:39], v[148:151], v[172:175], v[36:39]
	v_mfma_f32_16x16x32_bf16 v[28:31], v[156:159], v[172:175], v[28:31]
	v_mfma_f32_16x16x32_bf16 v[20:23], v[148:151], v[180:183], v[20:23]
	v_mfma_f32_16x16x32_bf16 v[12:15], v[156:159], v[180:183], v[12:15]
	v_mfma_f32_16x16x32_bf16 v[4:7], v[148:151], v[206:209], v[4:7]
	s_barrier
	v_mfma_f32_16x16x32_bf16 v[0:3], v[156:159], v[206:209], v[0:3]
	s_setprio 0
	s_add_i32 s72, 0, 0x18000
	s_add_i32 s73, 0, 0x1c000
	v_add_u32_e32 v140, s72, v240
	v_add_u32_e32 v156, s73, v240
	ds_read_b128 v[128:131], v140
	ds_read_b128 v[132:135], v140 offset:1024
	ds_read_b128 v[136:139], v140 offset:2048
	ds_read_b128 v[140:143], v140 offset:3072
	ds_read_b128 v[144:147], v156
	ds_read_b128 v[148:151], v156 offset:1024
	ds_read_b128 v[152:155], v156 offset:2048
	ds_read_b128 v[156:159], v156 offset:3072
	s_add_u32 s46, s52, 0xb0000
	s_addc_u32 s47, s53, 0
	s_mov_b32 m0, s13
	v_lshl_add_u64 v[218:219], s[46:47], 0, v[190:191]
	ds_read_b128 v[160:163], v243 offset:32768
	ds_read_b128 v[164:167], v243 offset:33792
	ds_read_b128 v[168:171], v243 offset:34816
	ds_read_b128 v[172:175], v243 offset:35840
	ds_read_b128 v[176:179], v243 offset:36864
	ds_read_b128 v[180:183], v243 offset:37888
	ds_read_b128 v[184:187], v243 offset:38912
	ds_read_b128 v[206:209], v243 offset:39936
	global_load_lds_dwordx4 v[218:219], off
	v_lshl_add_u64 v[218:219], s[46:47], 0, v[194:195]
	s_mov_b32 m0, s33
	s_nop 0
	global_load_lds_dwordx4 v[218:219], off
	s_waitcnt vmcnt(8)
	s_waitcnt lgkmcnt(0)
	s_barrier
	s_setprio 1
	s_waitcnt lgkmcnt(0)
	v_mfma_f32_16x16x32_bf16 v[124:127], v[128:131], v[160:163], v[124:127]
	v_mfma_f32_16x16x32_bf16 v[120:123], v[136:139], v[160:163], v[120:123]
	v_mfma_f32_16x16x32_bf16 v[112:115], v[128:131], v[168:171], v[112:115]
	v_mfma_f32_16x16x32_bf16 v[104:107], v[136:139], v[168:171], v[104:107]
	v_mfma_f32_16x16x32_bf16 v[96:99], v[128:131], v[176:179], v[96:99]
	v_mfma_f32_16x16x32_bf16 v[88:91], v[136:139], v[176:179], v[88:91]
	v_mfma_f32_16x16x32_bf16 v[80:83], v[128:131], v[184:187], v[80:83]
	v_mfma_f32_16x16x32_bf16 v[72:75], v[136:139], v[184:187], v[72:75]
	v_mfma_f32_16x16x32_bf16 v[124:127], v[132:135], v[164:167], v[124:127]
	v_mfma_f32_16x16x32_bf16 v[120:123], v[140:143], v[164:167], v[120:123]
	v_mfma_f32_16x16x32_bf16 v[112:115], v[132:135], v[172:175], v[112:115]
	v_mfma_f32_16x16x32_bf16 v[104:107], v[140:143], v[172:175], v[104:107]
	v_mfma_f32_16x16x32_bf16 v[96:99], v[132:135], v[180:183], v[96:99]
	v_mfma_f32_16x16x32_bf16 v[88:91], v[140:143], v[180:183], v[88:91]
	v_mfma_f32_16x16x32_bf16 v[80:83], v[132:135], v[206:209], v[80:83]
	v_mfma_f32_16x16x32_bf16 v[72:75], v[140:143], v[206:209], v[72:75]
	s_setprio 0
	s_setprio 1
	v_mfma_f32_16x16x32_bf16 v[116:119], v[144:147], v[160:163], v[116:119]
	v_mfma_f32_16x16x32_bf16 v[108:111], v[152:155], v[160:163], v[108:111]
	v_mfma_f32_16x16x32_bf16 v[100:103], v[144:147], v[168:171], v[100:103]
	v_mfma_f32_16x16x32_bf16 v[92:95], v[152:155], v[168:171], v[92:95]
	v_mfma_f32_16x16x32_bf16 v[84:87], v[144:147], v[176:179], v[84:87]
	v_mfma_f32_16x16x32_bf16 v[76:79], v[152:155], v[176:179], v[76:79]
	v_mfma_f32_16x16x32_bf16 v[68:71], v[144:147], v[184:187], v[68:71]
	v_mfma_f32_16x16x32_bf16 v[64:67], v[152:155], v[184:187], v[64:67]
	v_mfma_f32_16x16x32_bf16 v[116:119], v[148:151], v[164:167], v[116:119]
	v_mfma_f32_16x16x32_bf16 v[108:111], v[156:159], v[164:167], v[108:111]
	v_mfma_f32_16x16x32_bf16 v[100:103], v[148:151], v[172:175], v[100:103]
	v_mfma_f32_16x16x32_bf16 v[92:95], v[156:159], v[172:175], v[92:95]
	v_mfma_f32_16x16x32_bf16 v[84:87], v[148:151], v[180:183], v[84:87]
	v_mfma_f32_16x16x32_bf16 v[76:79], v[156:159], v[180:183], v[76:79]
	v_mfma_f32_16x16x32_bf16 v[68:71], v[148:151], v[206:209], v[68:71]
	s_barrier
; #define PG8_STAGE(bufoff, gbase, voff) do { _Pragma("unroll") for (int _i = 0; _i < 2; ++_i) \
;         __builtin_amdgcn_global_load_lds((const unsigned*)((const char*)(gbase) + (voff)[_i]), (PG8_LAS unsigned*)(lds + (bufoff) + ldsw + _i * 8192), 16, 0, 0); } while (0)
; #define PG8_LDA(dst, b, h) do { _Pragma("unroll") for (int m = 0; m < 4; ++m) _Pragma("unroll") for (int k = 0; k < 2; ++k) dst[m][k] = *(const PG8_LAS bf16x8*)(lds + PG8_SA(b, h) + aoff + m * 2048 + k * 1024); } while (0)
; #define PG8_LDB(dst, b, h) do { _Pragma("unroll") for (int n = 0; n < 2; ++n) _Pragma("unroll") for (int k = 0; k < 2; ++k) dst[n][k] = *(const PG8_LAS bf16x8*)(lds + PG8_SB(b, h) + boff + n * 2048 + k * 1024); } while (0)
; #define PG8_MMA(ai, bj, At, Bt) do { __builtin_amdgcn_s_setprio(1); _Pragma("unroll") for (int m = 0; m < 4; ++m) _Pragma("unroll") for (int n = 0; n < 2; ++n) _Pragma("unroll") for (int k = 0; k < 2; ++k) \
;         acc[ai][bj][m][n] = __builtin_amdgcn_mfma_f32_16x16x32_bf16(Bt[n][k], At[m][k], acc[ai][bj][m][n], 0, 0, 0); __builtin_amdgcn_s_setprio(0); } while (0)
; #define PG8_WAIT_V(n) asm volatile("s_waitcnt vmcnt(" #n ")" ::: "memory")
; template <class Epi, class Sched, bool ALIGN_EPI = false, bool SP2 = false>
; __device__ __forceinline__ void gemm_phase(PG8_LAS unsigned char* lds, const Gemm g, const Sched S, const Epi E) {
;     ...
;             PG8_LDB(B0, 0, 0); PG8_LDB(B1, 0, 1); PG8_SCHED; PG8_LDA(At, 0, 0); PG8_STAGE(PG8_SA(1, 1), a1 + hstep, voffA);
;             PG8_WAIT_V(8); PG8_WAIT_L(0); PG8_BAR; PG8_MMA(0, 0, At, B0); PG8_MMA(0, 1, At, B1); PG8_BAR; PG8_SCHED;
;             PG8_LDA(At, 0, 1); PG8_STAGE(PG8_SB(0, 0), b2, voffB); PG8_STAGE(PG8_SB(0, 1), b2 + hstep, voffB); PG8_STAGE(PG8_SA(0, 0), a2, voffA);
;             PG8_WAIT_V(8); PG8_WAIT_L(0); PG8_BAR; PG8_MMA(1, 0, At, B0); PG8_MMA(1, 1, At, B1); PG8_BAR; PG8_SCHED;
;             PG8_LDB(B0, 1, 0); PG8_LDB(B1, 1, 1); PG8_SCHED; PG8_LDA(At, 1, 0); PG8_STAGE(PG8_SA(0, 1), a2 + hstep, voffA);
;             PG8_WAIT_V(8); PG8_WAIT_L(0); PG8_BAR; PG8_MMA(0, 0, At, B0); PG8_MMA(0, 1, At, B1); PG8_BAR; PG8_SCHED;
;             PG8_LDA(At, 1, 1); PG8_STAGE(PG8_SB(1, 0), b3, voffB); PG8_STAGE(PG8_SB(1, 1), b3 + hstep, voffB); PG8_STAGE(PG8_SA(1, 0), a3, voffA);
;             PG8_WAIT_V(8); PG8_WAIT_L(0); PG8_BAR; PG8_MMA(1, 0, At, B0); PG8_MMA(1, 1, At, B1); PG8_BAR; PG8_SCHED;
	v_mfma_f32_16x16x32_bf16 v[64:67], v[156:159], v[206:209], v[64:67]
	s_setprio 0
	s_add_i32 s46, s72, s8
	v_lshl_add_u64 v[210:211], v[210:211], 0, s[10:11]
	s_mov_b32 m0, s46
	ds_read_b128 v[160:163], v243 offset:49152
	ds_read_b128 v[164:167], v243 offset:50176
	ds_read_b128 v[168:171], v243 offset:51200
	ds_read_b128 v[172:175], v243 offset:52224
	ds_read_b128 v[176:179], v243 offset:53248
	ds_read_b128 v[180:183], v243 offset:54272
	ds_read_b128 v[184:187], v243 offset:55296
	ds_read_b128 v[206:209], v243 offset:56320
	global_load_lds_dwordx4 v[210:211], off
	s_add_i32 m0, s46, 0x2000
	s_add_u32 s46, s50, 0xb0080
	v_lshl_add_u64 v[210:211], v[212:213], 0, s[10:11]
	s_addc_u32 s47, s51, 0
	s_add_i32 s50, s73, s8
	global_load_lds_dwordx4 v[210:211], off
	v_lshl_add_u64 v[210:211], s[46:47], 0, v[192:193]
	s_mov_b32 m0, s50
	s_nop 0
	global_load_lds_dwordx4 v[210:211], off
	v_lshl_add_u64 v[210:211], s[46:47], 0, v[196:197]
	s_add_i32 m0, s50, 0x2000
	s_nop 0
	global_load_lds_dwordx4 v[210:211], off
	v_lshl_add_u64 v[210:211], v[214:215], 0, s[10:11]
	s_mov_b32 m0, s59
	s_nop 0
	global_load_lds_dwordx4 v[210:211], off
	v_lshl_add_u64 v[210:211], v[216:217], 0, s[10:11]
	s_mov_b32 m0, s60
	s_nop 0
	global_load_lds_dwordx4 v[210:211], off
	s_waitcnt vmcnt(8)
	s_waitcnt lgkmcnt(0)
	s_barrier
	s_setprio 1
	s_waitcnt lgkmcnt(0)
	v_mfma_f32_16x16x32_bf16 v[60:63], v[128:131], v[160:163], v[60:63]
	v_mfma_f32_16x16x32_bf16 v[56:59], v[136:139], v[160:163], v[56:59]
	v_mfma_f32_16x16x32_bf16 v[48:51], v[128:131], v[168:171], v[48:51]
	v_mfma_f32_16x16x32_bf16 v[40:43], v[136:139], v[168:171], v[40:43]
	v_mfma_f32_16x16x32_bf16 v[32:35], v[128:131], v[176:179], v[32:35]
	v_mfma_f32_16x16x32_bf16 v[24:27], v[136:139], v[176:179], v[24:27]
	v_mfma_f32_16x16x32_bf16 v[16:19], v[128:131], v[184:187], v[16:19]
	v_mfma_f32_16x16x32_bf16 v[8:11], v[136:139], v[184:187], v[8:11]
	v_mfma_f32_16x16x32_bf16 v[60:63], v[132:135], v[164:167], v[60:63]
	v_mfma_f32_16x16x32_bf16 v[56:59], v[140:143], v[164:167], v[56:59]
	v_mfma_f32_16x16x32_bf16 v[48:51], v[132:135], v[172:175], v[48:51]
	v_mfma_f32_16x16x32_bf16 v[40:43], v[140:143], v[172:175], v[40:43]
	v_mfma_f32_16x16x32_bf16 v[32:35], v[132:135], v[180:183], v[32:35]
	v_mfma_f32_16x16x32_bf16 v[24:27], v[140:143], v[180:183], v[24:27]
	v_mfma_f32_16x16x32_bf16 v[16:19], v[132:135], v[206:209], v[16:19]
	v_mfma_f32_16x16x32_bf16 v[8:11], v[140:143], v[206:209], v[8:11]
	s_setprio 0
	s_setprio 1
	v_mfma_f32_16x16x32_bf16 v[52:55], v[144:147], v[160:163], v[52:55]
	v_mfma_f32_16x16x32_bf16 v[44:47], v[152:155], v[160:163], v[44:47]
	v_mfma_f32_16x16x32_bf16 v[36:39], v[144:147], v[168:171], v[36:39]
	v_mfma_f32_16x16x32_bf16 v[28:31], v[152:155], v[168:171], v[28:31]
	v_mfma_f32_16x16x32_bf16 v[20:23], v[144:147], v[176:179], v[20:23]
	v_mfma_f32_16x16x32_bf16 v[12:15], v[152:155], v[176:179], v[12:15]
	v_mfma_f32_16x16x32_bf16 v[4:7], v[144:147], v[184:187], v[4:7]
	v_mfma_f32_16x16x32_bf16 v[0:3], v[152:155], v[184:187], v[0:3]
	v_mfma_f32_16x16x32_bf16 v[52:55], v[148:151], v[164:167], v[52:55]
	v_mfma_f32_16x16x32_bf16 v[44:47], v[156:159], v[164:167], v[44:47]
	v_mfma_f32_16x16x32_bf16 v[36:39], v[148:151], v[172:175], v[36:39]
	v_mfma_f32_16x16x32_bf16 v[28:31], v[156:159], v[172:175], v[28:31]
	v_mfma_f32_16x16x32_bf16 v[20:23], v[148:151], v[180:183], v[20:23]
	v_mfma_f32_16x16x32_bf16 v[12:15], v[156:159], v[180:183], v[12:15]
	v_mfma_f32_16x16x32_bf16 v[4:7], v[148:151], v[206:209], v[4:7]
	s_barrier
	v_mfma_f32_16x16x32_bf16 v[0:3], v[156:159], v[206:209], v[0:3]
	s_setprio 0
	s_add_i32 s71, s71, 2
	s_add_u32 s69, s69, 0x100
	s_addc_u32 s70, s70, 0
	s_cmp_gt_u32 s71, 41
	s_mov_b64 s[46:47], s[48:49]
	s_cbranch_scc0 .LBB0_1105
	s_and_b64 vcc, exec, s[16:17]
	s_cbranch_vccz .LBB0_1108
	s_barrier
